# stack9 + gMLP LayerNorm 8-lane sums with DPP (quad_perm, row_half_mirror) instead of 48 serialized ds_bpermute round trips
# baseline (speedup 1.0000x reference)
; #define LAS __attribute__((address_space(3)))
; #define GAS __attribute__((address_space(1)))
; __device__ __forceinline__ void gmlp_unit(unsigned char* ws, h16* Y, const h16* Ws16  , const float* bs  , size_t r0, LAS unsigned char* lds, int tid) {
;     const int lane = tid & 63, wid = __builtin_amdgcn_readfirstlane(tid >> 6), r32 = lane & 31, hi = lane >> 5;
;     const h16* VN = (const h16*)(ws + WS_VN); const h16* GU = (const h16*)(ws + WS_GU); const h16* SZ = (const h16*)(ws + WS_SZ);
;     const int g = wid >> 1, ph = wid & 1; const h16* Wg = Ws16 + (size_t)g * 128 * 128;
;     u32x4 stg[8];
; #pragma unroll
;     for (int j = 0; j < 8; ++j) { const int i = tid + 512 * j, row = i >> 5, c8 = i & 31; stg[j] = *(const GAS u32x4*)(VN + (r0 + row) * 256 + c8 * 8); }
;     s16x8 af[2][8];
; #pragma unroll
;     for (int q = 0; q < 2; ++q)
; #pragma unroll
;         for (int ks = 0; ks < 8; ++ks) af[q][ks] = *(const GAS s16x8*)(Wg + (size_t)(32 * (2 * ph + q) + r32) * 128 + 16 * ks + 8 * hi);
;     const int erow = lane >> 3, ech = lane & 7;
;     h16x8 gu[2][4], sz[2][4]; float bias[2][4];
; #pragma unroll
;     for (int q = 0; q < 2; ++q)
; #pragma unroll
;         for (int ps = 0; ps < 4; ++ps) { bias[q][ps] = *(const GAS float*)(bs + g * 128 + 32 * (2 * ph + q) + 8 * ps + erow);
;             const size_t go = (r0 + 32 * (2 * ph + q) + 8 * ps + erow) * 256 + g * 64 + 8 * ech;
;             gu[q][ps] = *(const GAS h16x8*)(GU + go); sz[q][ps] = *(const GAS h16x8*)(SZ + go); }
.LBB0_47:
	s_or_b64 exec, exec, s[0:1]
	v_mov_b32_e32 v247, v212
	s_mov_b32 s50, s40
	s_xor_b64 s[0:1], s[2:3], -1
	s_add_i32 s41, s74, s50
	v_readlane_b32 s22, v253, 0
	v_mov_b32_e32 v211, 0x2880000
	v_readlane_b32 s23, v253, 1
	s_cmpk_gt_i32 s84, 0x7f
	s_mov_b64 s[6:7], -1
	s_cbranch_scc0 .LBB0_228
	s_mov_b64 s[2:3], -1
	s_cmp_ge_i32 s84, s78
	v_lshlrev_b32_e32 v131, 3, v247
	v_bfe_u32 v248, v247, 5, 1
	s_cbranch_scc0 .LBB0_50
	v_readlane_b32 s2, v253, 14
	v_readlane_b32 s3, v253, 15
	s_add_u32 s13, s22, s2
	s_addc_u32 s14, s23, s3
	s_sub_i32 s2, s84, s78
	s_mov_b32 s3, s40
	v_lshlrev_b32_e32 v171, 4, v247
	v_ashrrev_i32_e32 v4, 5, v247
	s_lshl_b64 s[2:3], s[2:3], 7
	v_and_b32_e32 v0, 0x1f0, v171
	v_ashrrev_i32_e32 v5, 31, v4
	v_lshl_add_u64 v[2:3], s[22:23], 0, v[0:1]
	s_mov_b64 s[10:11], 0x9780000
	v_lshl_add_u64 v[4:5], s[2:3], 0, v[4:5]
	v_lshl_add_u64 v[2:3], v[2:3], 0, s[10:11]
	v_lshlrev_b64 v[4:5], 9, v[4:5]
	v_lshl_add_u64 v[4:5], v[2:3], 0, v[4:5]
	global_load_dwordx4 v[160:163], v[4:5], off
	v_add_u32_e32 v0, 0x200, v247
	v_ashrrev_i32_e32 v4, 5, v0
	v_ashrrev_i32_e32 v5, 31, v4
	v_lshl_add_u64 v[4:5], s[2:3], 0, v[4:5]
	v_lshlrev_b64 v[4:5], 9, v[4:5]
	v_lshl_add_u64 v[4:5], v[2:3], 0, v[4:5]
	v_add_u32_e32 v0, 0x400, v247
	global_load_dwordx4 v[156:159], v[4:5], off
	v_ashrrev_i32_e32 v4, 5, v0
	v_ashrrev_i32_e32 v5, 31, v4
	v_lshl_add_u64 v[4:5], s[2:3], 0, v[4:5]
	v_lshlrev_b64 v[4:5], 9, v[4:5]
	v_lshl_add_u64 v[4:5], v[2:3], 0, v[4:5]
	v_add_u32_e32 v0, 0x600, v247
	global_load_dwordx4 v[152:155], v[4:5], off
	v_ashrrev_i32_e32 v4, 5, v0
	v_ashrrev_i32_e32 v5, 31, v4
	v_lshl_add_u64 v[4:5], s[2:3], 0, v[4:5]
	v_lshlrev_b64 v[4:5], 9, v[4:5]
	v_lshl_add_u64 v[4:5], v[2:3], 0, v[4:5]
	v_add_u32_e32 v0, 0x800, v247
	global_load_dwordx4 v[148:151], v[4:5], off
	v_ashrrev_i32_e32 v4, 5, v0
	v_ashrrev_i32_e32 v5, 31, v4
	v_lshl_add_u64 v[4:5], s[2:3], 0, v[4:5]
	v_lshlrev_b64 v[4:5], 9, v[4:5]
	v_lshl_add_u64 v[4:5], v[2:3], 0, v[4:5]
	v_add_u32_e32 v0, 0xa00, v247
	global_load_dwordx4 v[14:17], v[4:5], off
	v_ashrrev_i32_e32 v4, 5, v0
	v_ashrrev_i32_e32 v5, 31, v4
	v_lshl_add_u64 v[4:5], s[2:3], 0, v[4:5]
	v_lshlrev_b64 v[4:5], 9, v[4:5]
	v_lshl_add_u64 v[4:5], v[2:3], 0, v[4:5]
	v_add_u32_e32 v0, 0xc00, v247
	v_readfirstlane_b32 s15, v247
	s_add_u32 s8, s22, 0x8580000
	global_load_dwordx4 v[10:13], v[4:5], off
	v_ashrrev_i32_e32 v4, 5, v0
	s_addc_u32 s9, s23, 0
	s_ashr_i32 s4, s15, 7
	v_ashrrev_i32_e32 v5, 31, v4
	s_ashr_i32 s5, s4, 31
	v_lshl_add_u64 v[4:5], s[2:3], 0, v[4:5]
	s_ashr_i32 s12, s15, 6
	s_lshl_b64 s[6:7], s[4:5], 15
	v_lshlrev_b64 v[4:5], 9, v[4:5]
	s_and_b32 s16, s12, 1
	v_lshl_add_u64 v[4:5], v[2:3], 0, v[4:5]
	v_add_u32_e32 v0, 0xe00, v247
	s_add_u32 s6, s13, s6
	v_and_b32_e32 v169, 31, v247
	global_load_dwordx4 v[6:9], v[4:5], off
	v_ashrrev_i32_e32 v4, 5, v0
	s_addc_u32 s7, s14, s7
	v_lshlrev_b32_e32 v0, 4, v248
	v_lshl_add_u64 v[18:19], s[6:7], 0, v[0:1]
	v_lshlrev_b32_e32 v0, 8, v169
	v_lshl_or_b32 v0, s16, 14, v0
	v_lshl_add_u64 v[18:19], v[18:19], 0, v[0:1]
	s_mov_b64 s[6:7], 0x2500000
	s_mov_b32 s5, 0x2500000
	s_add_u32 s10, s22, 0xa980000
	v_lshl_add_u64 v[20:21], v[18:19], 0, s[6:7]
	s_waitcnt vmcnt(9)
	v_add_co_u32_e32 v22, vcc, s5, v18
	s_addc_u32 s11, s23, 0
	s_and_b32 s6, s15, 0xffffff80
	v_ashrrev_i32_e32 v5, 31, v4
	v_addc_co_u32_e32 v23, vcc, 0, v19, vcc
	s_mov_b32 s5, 0x2502000
	s_ashr_i32 s7, s6, 31
	v_lshl_add_u64 v[4:5], s[2:3], 0, v[4:5]
	v_add_co_u32_e32 v18, vcc, s5, v18
	s_lshl_b64 s[6:7], s[6:7], 2
	v_readlane_b32 s5, v253, 18
	v_lshlrev_b64 v[4:5], 9, v[4:5]
	v_bfe_u32 v167, v247, 3, 3
	s_add_u32 s6, s5, s6
	v_readlane_b32 s5, v253, 20
	v_lshl_add_u64 v[2:3], v[2:3], 0, v[4:5]
	v_addc_co_u32_e32 v19, vcc, 0, v19, vcc
	s_addc_u32 s7, s5, s7
	v_lshlrev_b32_e32 v0, 2, v167
	global_load_dwordx4 v[2:5], v[2:3], off
	s_nop 0
	global_load_dwordx4 v[140:143], v[22:23], off
	global_load_dwordx4 v[144:147], v[20:21], off offset:32
	global_load_dwordx4 v[136:139], v[20:21], off offset:64
	global_load_dwordx4 v[132:135], v[20:21], off offset:96
	global_load_dwordx4 v[126:129], v[20:21], off offset:128
	global_load_dwordx4 v[122:125], v[20:21], off offset:160
	global_load_dwordx4 v[118:121], v[20:21], off offset:192
	global_load_dwordx4 v[114:117], v[20:21], off offset:224
	global_load_dwordx4 v[78:81], v[18:19], off
	global_load_dwordx4 v[74:77], v[18:19], off offset:32
	global_load_dwordx4 v[70:73], v[18:19], off offset:64
	global_load_dwordx4 v[66:69], v[18:19], off offset:96
	global_load_dwordx4 v[62:65], v[18:19], off offset:128
	global_load_dwordx4 v[58:61], v[18:19], off offset:160
	global_load_dwordx4 v[54:57], v[18:19], off offset:192
	global_load_dwordx4 v[50:53], v[18:19], off offset:224
	s_lshl_b32 s5, s16, 6
	v_lshl_add_u64 v[18:19], s[6:7], 0, v[0:1]
	v_or_b32_e32 v28, s2, v167
	s_lshl_b32 s6, s4, 6
	s_ashr_i32 s7, s6, 31
	v_and_b32_e32 v0, 56, v131
	v_or_b32_e32 v164, s5, v28
	v_mov_b32_e32 v165, s3
	v_or_b32_e32 v20, s6, v0
	v_mov_b32_e32 v21, s7
	v_lshlrev_b64 v[22:23], 8, v[164:165]
	v_lshl_add_u64 v[22:23], v[22:23], 0, v[20:21]
	v_lshlrev_b64 v[22:23], 1, v[22:23]
	s_lshl_b32 s14, s16, 8
	s_mov_b32 s15, s40
	v_lshl_add_u64 v[24:25], s[8:9], 0, v[22:23]
	v_lshl_add_u64 v[18:19], v[18:19], 0, s[14:15]
	global_load_dwordx4 v[106:109], v[24:25], off
	v_lshl_add_u64 v[24:25], s[10:11], 0, v[22:23]
	s_mov_b64 s[14:15], 0x1000
	global_load_dword v180, v[18:19], off
	global_load_dwordx4 v[110:113], v[24:25], off
	global_load_dword v178, v[18:19], off offset:32
	v_lshl_add_u64 v[24:25], v[22:23], 0, s[14:15]
	v_lshl_add_u64 v[26:27], s[8:9], 0, v[24:25]
	v_lshl_add_u64 v[24:25], s[10:11], 0, v[24:25]
	s_mov_b64 s[16:17], 0x2000
	global_load_dwordx4 v[98:101], v[26:27], off
	global_load_dwordx4 v[102:105], v[24:25], off
	global_load_dword v176, v[18:19], off offset:64
	v_lshl_add_u64 v[24:25], v[22:23], 0, s[16:17]
	s_mov_b64 s[18:19], 0x3000
	v_lshl_add_u64 v[26:27], s[8:9], 0, v[24:25]
	v_lshl_add_u64 v[24:25], s[10:11], 0, v[24:25]
	v_lshl_add_u64 v[22:23], v[22:23], 0, s[18:19]
	s_or_b32 s3, s5, 32
	global_load_dwordx4 v[90:93], v[26:27], off
	global_load_dwordx4 v[94:97], v[24:25], off
	global_load_dword v174, v[18:19], off offset:96
	v_lshl_add_u64 v[24:25], s[8:9], 0, v[22:23]
	v_lshl_add_u64 v[22:23], s[10:11], 0, v[22:23]
	v_or_b32_e32 v164, s3, v28
	global_load_dwordx4 v[82:85], v[24:25], off
	global_load_dwordx4 v[86:89], v[22:23], off
	v_lshlrev_b64 v[22:23], 8, v[164:165]
	v_lshl_add_u64 v[20:21], v[22:23], 0, v[20:21]
	v_lshlrev_b64 v[20:21], 1, v[20:21]
	v_lshl_add_u64 v[22:23], s[8:9], 0, v[20:21]
	global_load_dwordx4 v[42:45], v[22:23], off
	v_lshl_add_u64 v[22:23], s[10:11], 0, v[20:21]
	global_load_dword v172, v[18:19], off offset:128
	global_load_dwordx4 v[46:49], v[22:23], off
	global_load_dword v170, v[18:19], off offset:160
	v_lshl_add_u64 v[22:23], v[20:21], 0, s[14:15]
	v_lshl_add_u64 v[24:25], s[8:9], 0, v[22:23]
	v_lshl_add_u64 v[22:23], s[10:11], 0, v[22:23]
	s_waitcnt vmcnt(39)
; #define LAS __attribute__((address_space(3)))
; __device__ __forceinline__ float geluf(float x) { return x * __builtin_amdgcn_rcpf(1.f + __builtin_amdgcn_exp2f(x * (-0.10294324f * x * x - 2.3022082f))); }
; __device__ __forceinline__ float lx_xor(float v, int m, int lane) { return __int_as_float(__builtin_amdgcn_ds_bpermute((lane ^ m) << 2, __float_as_int(v))); }
; __device__ __forceinline__ unsigned cvtpk_h(float lo, float hi) { f32x2 v = {lo, hi}; h16x2 b = __builtin_convertvector(v, h16x2); return __builtin_bit_cast(unsigned, b); }
; __device__ __forceinline__ void gmlp_unit(unsigned char* ws, h16* Y, const h16* Ws16  , const float* bs  , size_t r0, LAS unsigned char* lds, int tid) {
;     ...
;     for (int j = 0; j < 8; ++j) { const int i = tid + 512 * j, row = i >> 5, c8 = i & 31, gg = c8 >> 3, cg = (c8 & 7) * 8;
;         const h16x8 hv = __builtin_bit_cast(h16x8, stg[j]); float x[8]; float sm = 0.f;
; #pragma unroll
;         for (int k = 0; k < 8; ++k) { x[k] = geluf((float)hv[k]); sm += x[k]; }
;         sm += lx_xor(sm, 1, lane); sm += lx_xor(sm, 2, lane); sm += lx_xor(sm, 4, lane);
;         const float mu = sm * (1.f / 64.f); float q = 0.f;
; #pragma unroll
;         for (int k = 0; k < 8; ++k) { x[k] -= mu; q += x[k] * x[k]; }
;         q += lx_xor(q, 1, lane); q += lx_xor(q, 2, lane); q += lx_xor(q, 4, lane);
;         const float rd = __builtin_amdgcn_rsqf(q * (1.f / 64.f) + EPS);
;         u32x4 o; o.x = cvtpk_h(x[0] * rd, x[1] * rd); o.y = cvtpk_h(x[2] * rd, x[3] * rd); o.z = cvtpk_h(x[4] * rd, x[5] * rd); o.w = cvtpk_h(x[6] * rd, x[7] * rd);
;         *(LAS u32x4*)(lds + gg * 16384 + (cg >> 5) * 8192 + row * 64 + (cg & 31) * 2) = o; }
	v_cvt_f32_f16_e32 v192, v161
	v_cvt_f32_f16_sdwa v193, v161 dst_sel:DWORD dst_unused:UNUSED_PAD src0_sel:WORD_1
	global_load_dwordx4 v[34:37], v[24:25], off
	global_load_dwordx4 v[38:41], v[22:23], off
	global_load_dword v168, v[18:19], off offset:192
	v_lshl_add_u64 v[22:23], v[20:21], 0, s[16:17]
	v_lshl_add_u64 v[24:25], s[8:9], 0, v[22:23]
	v_lshl_add_u64 v[22:23], s[10:11], 0, v[22:23]
	global_load_dwordx4 v[26:29], v[24:25], off
	global_load_dwordx4 v[30:33], v[22:23], off
	global_load_dword v166, v[18:19], off offset:224
	v_lshl_add_u64 v[22:23], v[20:21], 0, s[18:19]
	v_lshl_add_u64 v[18:19], s[8:9], 0, v[22:23]
	v_cvt_f32_f16_e32 v182, v163
	v_cvt_f32_f16_sdwa v183, v163 dst_sel:DWORD dst_unused:UNUSED_PAD src0_sel:WORD_1
	s_mov_b32 s9, 0xc0135761
	v_mul_f32_e32 v194, 0x3dd2d3e8, v192
	v_mul_f32_e32 v195, 0x3dd2d3e8, v193
	v_fma_mix_f32 v194, -v194, v161, s9 op_sel_hi:[0,1,0]
	v_fma_mix_f32 v161, -v195, v161, s9 op_sel:[0,1,0] op_sel_hi:[0,1,0]
	v_mul_f32_e32 v161, v161, v193
	v_exp_f32_e32 v161, v161
	v_mul_f32_e32 v184, 0x3dd2d3e8, v182
	v_mul_f32_e32 v185, 0x3dd2d3e8, v183
	v_cvt_f32_f16_e32 v198, v160
	v_fma_mix_f32 v184, -v184, v163, s9 op_sel_hi:[0,1,0]
	v_fma_mix_f32 v163, -v185, v163, s9 op_sel:[0,1,0] op_sel_hi:[0,1,0]
	v_mul_f32_e32 v163, v163, v183
	v_exp_f32_e32 v163, v163
	v_add_f32_e32 v161, 1.0, v161
	v_cvt_f32_f16_e32 v186, v162
	v_rcp_f32_e32 v195, v161
	v_mul_f32_e32 v161, 0x3dd2d3e8, v198
	v_fma_mix_f32 v161, -v161, v160, s9 op_sel_hi:[0,1,0]
	v_mul_f32_e32 v161, v161, v198
	v_add_f32_e32 v163, 1.0, v163
	v_exp_f32_e32 v161, v161
	v_rcp_f32_e32 v185, v163
	v_mul_f32_e32 v163, 0x3dd2d3e8, v186
	v_cvt_f32_f16_sdwa v199, v160 dst_sel:DWORD dst_unused:UNUSED_PAD src0_sel:WORD_1
	v_fma_mix_f32 v163, -v163, v162, s9 op_sel_hi:[0,1,0]
	v_mul_f32_e32 v163, v163, v186
	v_exp_f32_e32 v163, v163
	v_add_f32_e32 v161, 1.0, v161
	v_cvt_f32_f16_sdwa v187, v162 dst_sel:DWORD dst_unused:UNUSED_PAD src0_sel:WORD_1
	v_rcp_f32_e32 v200, v161
	v_mul_f32_e32 v161, 0x3dd2d3e8, v199
	v_fma_mix_f32 v160, -v161, v160, s9 op_sel:[0,1,0] op_sel_hi:[0,1,0]
	v_mul_f32_e32 v160, v160, v199
	v_add_f32_e32 v163, 1.0, v163
	v_exp_f32_e32 v160, v160
	v_rcp_f32_e32 v190, v163
	v_mul_f32_e32 v163, 0x3dd2d3e8, v187
	v_mul_f32_e32 v194, v194, v192
	v_fma_mix_f32 v162, -v163, v162, s9 op_sel:[0,1,0] op_sel_hi:[0,1,0]
	v_exp_f32_e32 v194, v194
	v_mul_f32_e32 v162, v162, v187
	v_exp_f32_e32 v162, v162
	v_add_f32_e32 v160, 1.0, v160
	v_mul_f32_e32 v184, v184, v182
	v_rcp_f32_e32 v201, v160
	v_exp_f32_e32 v184, v184
	v_add_f32_e32 v194, 1.0, v194
	v_rcp_f32_e32 v194, v194
	v_add_f32_e32 v162, 1.0, v162
	v_rcp_f32_e32 v191, v162
	v_pk_mul_f32 v[160:161], v[200:201], v[198:199]
	v_add_f32_e32 v184, 1.0, v184
	v_add_f32_e32 v160, 0, v160
	v_rcp_f32_e32 v184, v184
	v_pk_mul_f32 v[196:197], v[194:195], v[192:193]
	v_add_f32_e32 v160, v161, v160
	v_add_f32_e32 v160, v196, v160
	v_pk_mul_f32 v[162:163], v[190:191], v[186:187]
	v_add_f32_e32 v160, v197, v160
	v_add_f32_e32 v160, v162, v160
	v_and_b32_e32 v173, 63, v247
	v_pk_mul_f32 v[188:189], v[184:185], v[182:183]
	v_add_f32_e32 v160, v163, v160
	v_lshlrev_b32_e32 v164, 2, v173
	v_add_f32_e32 v160, v188, v160
	v_xor_b32_e32 v177, 4, v164
	v_add_f32_e32 v160, v189, v160
	s_nop 0
	v_xor_b32_e32 v175, 8, v164
	v_xor_b32_e32 v173, 16, v164
	v_lshlrev_b32_e32 v179, 11, v247
	v_and_b32_e32 v181, 0xc000, v179
	s_nop 1
	v_add_f32_dpp v160, v160, v160 quad_perm:[1,0,3,2] row_mask:0xf bank_mask:0xf
	s_nop 0
	v_and_b32_e32 v179, 0x2000, v179
	v_add3_u32 v179, s41, v181, v179
	v_lshlrev_b32_e32 v181, 1, v247
	v_and_b32_e32 v202, 48, v171
	s_nop 1
	v_add_f32_dpp v160, v160, v160 quad_perm:[2,3,0,1] row_mask:0xf bank_mask:0xf
	s_nop 0
	v_and_b32_e32 v181, 0xffffffc0, v181
	v_add3_u32 v179, v179, v202, v181
	s_lshl_b32 s4, s4, 14
	v_lshl_add_u64 v[22:23], s[10:11], 0, v[22:23]
	s_nop 1
	v_add_f32_dpp v160, v160, v160 row_half_mirror row_mask:0xf bank_mask:0xf
	v_mul_f32_e32 v160, 0x3c800000, v160
	v_pk_fma_f32 v[162:163], v[200:201], v[198:199], v[160:161] op_sel_hi:[1,1,0] neg_lo:[0,0,1] neg_hi:[0,0,1]
	v_pk_fma_f32 v[192:193], v[194:195], v[192:193], v[160:161] op_sel_hi:[1,1,0] neg_lo:[0,0,1] neg_hi:[0,0,1]
	v_pk_mul_f32 v[188:189], v[162:163], v[162:163]
	v_pk_mul_f32 v[194:195], v[192:193], v[192:193]
	v_pk_fma_f32 v[182:183], v[184:185], v[182:183], v[160:161] op_sel_hi:[1,1,0] neg_lo:[0,0,1] neg_hi:[0,0,1]
	v_add_f32_e32 v184, v188, v189
	v_pk_fma_f32 v[186:187], v[190:191], v[186:187], v[160:161] op_sel_hi:[1,1,0] neg_lo:[0,0,1] neg_hi:[0,0,1]
	v_add_f32_e32 v184, v194, v184
	v_pk_mul_f32 v[190:191], v[186:187], v[186:187]
	v_add_f32_e32 v184, v195, v184
	v_add_f32_e32 v184, v190, v184
	v_pk_mul_f32 v[160:161], v[182:183], v[182:183]
	v_add_f32_e32 v184, v191, v184
	v_add_f32_e32 v160, v160, v184
	v_add_f32_e32 v160, v161, v160
	s_nop 0
	s_waitcnt vmcnt(44)
; #define LAS __attribute__((address_space(3)))
; __device__ __forceinline__ float geluf(float x) { return x * __builtin_amdgcn_rcpf(1.f + __builtin_amdgcn_exp2f(x * (-0.10294324f * x * x - 2.3022082f))); }
; __device__ __forceinline__ float lx_xor(float v, int m, int lane) { return __int_as_float(__builtin_amdgcn_ds_bpermute((lane ^ m) << 2, __float_as_int(v))); }
; __device__ __forceinline__ unsigned cvtpk_h(float lo, float hi) { f32x2 v = {lo, hi}; h16x2 b = __builtin_convertvector(v, h16x2); return __builtin_bit_cast(unsigned, b); }
; __device__ __forceinline__ void gmlp_unit(unsigned char* ws, h16* Y, const h16* Ws16  , const float* bs  , size_t r0, LAS unsigned char* lds, int tid) {
;     ...
;     for (int j = 0; j < 8; ++j) { const int i = tid + 512 * j, row = i >> 5, c8 = i & 31, gg = c8 >> 3, cg = (c8 & 7) * 8;
;         const h16x8 hv = __builtin_bit_cast(h16x8, stg[j]); float x[8]; float sm = 0.f;
; #pragma unroll
;         for (int k = 0; k < 8; ++k) { x[k] = geluf((float)hv[k]); sm += x[k]; }
;         sm += lx_xor(sm, 1, lane); sm += lx_xor(sm, 2, lane); sm += lx_xor(sm, 4, lane);
;         const float mu = sm * (1.f / 64.f); float q = 0.f;
; #pragma unroll
;         for (int k = 0; k < 8; ++k) { x[k] -= mu; q += x[k] * x[k]; }
;         q += lx_xor(q, 1, lane); q += lx_xor(q, 2, lane); q += lx_xor(q, 4, lane);
;         const float rd = __builtin_amdgcn_rsqf(q * (1.f / 64.f) + EPS);
;         u32x4 o; o.x = cvtpk_h(x[0] * rd, x[1] * rd); o.y = cvtpk_h(x[2] * rd, x[3] * rd); o.z = cvtpk_h(x[4] * rd, x[5] * rd); o.w = cvtpk_h(x[6] * rd, x[7] * rd);
;         *(LAS u32x4*)(lds + gg * 16384 + (cg >> 5) * 8192 + row * 64 + (cg & 31) * 2) = o; }
	v_cvt_f32_f16_e32 v188, v157
	v_cvt_f32_f16_sdwa v189, v157 dst_sel:DWORD dst_unused:UNUSED_PAD src0_sel:WORD_1
	v_cvt_f32_f16_e32 v194, v156
	v_cvt_f32_f16_sdwa v195, v156 dst_sel:DWORD dst_unused:UNUSED_PAD src0_sel:WORD_1
	s_nop 1
	v_add_f32_dpp v160, v160, v160 quad_perm:[1,0,3,2] row_mask:0xf bank_mask:0xf
	s_nop 0
	v_mul_f32_e32 v181, 0x3dd2d3e8, v188
	v_fma_mix_f32 v181, -v181, v157, s9 op_sel_hi:[0,1,0]
	v_mul_f32_e32 v181, v181, v188
	v_exp_f32_e32 v181, v181
	s_nop 1
	v_add_f32_dpp v160, v160, v160 quad_perm:[2,3,0,1] row_mask:0xf bank_mask:0xf
	s_nop 0
	s_add_i32 s4, s41, s4
	v_add_f32_e32 v181, 1.0, v181
	v_rcp_f32_e32 v190, v181
	v_mul_f32_e32 v181, 0x3dd2d3e8, v189
	s_nop 1
	v_add_f32_dpp v160, v160, v160 row_half_mirror row_mask:0xf bank_mask:0xf
	v_fmamk_f32 v160, v160, 0x3c800000, v229
	v_rsq_f32_e32 v184, v160
	v_fma_mix_f32 v157, -v181, v157, s9 op_sel:[0,1,0] op_sel_hi:[0,1,0]
	v_mul_f32_e32 v157, v157, v189
	v_exp_f32_e32 v157, v157
	v_pk_mul_f32 v[160:161], v[162:163], v[184:185] op_sel_hi:[1,0]
	v_pk_mul_f32 v[162:163], v[192:193], v[184:185] op_sel_hi:[1,0]
	v_cvt_pk_f16_f32 v160, v160, v161
	v_cvt_pk_f16_f32 v161, v162, v163
	v_pk_mul_f32 v[162:163], v[186:187], v[184:185] op_sel_hi:[1,0]
	v_pk_mul_f32 v[182:183], v[182:183], v[184:185] op_sel_hi:[1,0]
	v_cvt_pk_f16_f32 v162, v162, v163
	v_cvt_pk_f16_f32 v163, v182, v183
	ds_write_b128 v179, v[160:163]
	v_cvt_f32_f16_e32 v160, v159
	v_cvt_f32_f16_sdwa v161, v159 dst_sel:DWORD dst_unused:UNUSED_PAD src0_sel:WORD_1
	v_add_f32_e32 v157, 1.0, v157
	v_cvt_f32_f16_e32 v184, v158
	v_mul_f32_e32 v162, 0x3dd2d3e8, v160
	v_mul_f32_e32 v163, 0x3dd2d3e8, v161
	v_fma_mix_f32 v162, -v162, v159, s9 op_sel_hi:[0,1,0]
	v_fma_mix_f32 v159, -v163, v159, s9 op_sel:[0,1,0] op_sel_hi:[0,1,0]
	v_mul_f32_e32 v159, v159, v161
	v_exp_f32_e32 v159, v159
	v_rcp_f32_e32 v191, v157
	v_mul_f32_e32 v157, 0x3dd2d3e8, v194
	v_fma_mix_f32 v157, -v157, v156, s9 op_sel_hi:[0,1,0]
	v_mul_f32_e32 v157, v157, v194
	v_add_f32_e32 v159, 1.0, v159
	v_exp_f32_e32 v157, v157
	v_rcp_f32_e32 v163, v159
	v_mul_f32_e32 v159, 0x3dd2d3e8, v184
	v_fma_mix_f32 v159, -v159, v158, s9 op_sel_hi:[0,1,0]
	v_mul_f32_e32 v159, v159, v184
	v_exp_f32_e32 v159, v159
	v_add_f32_e32 v157, 1.0, v157
	v_cvt_f32_f16_sdwa v185, v158 dst_sel:DWORD dst_unused:UNUSED_PAD src0_sel:WORD_1
	v_rcp_f32_e32 v196, v157
	v_mul_f32_e32 v157, 0x3dd2d3e8, v195
	v_fma_mix_f32 v156, -v157, v156, s9 op_sel:[0,1,0] op_sel_hi:[0,1,0]
	v_mul_f32_e32 v156, v156, v195
	v_add_f32_e32 v159, 1.0, v159
	v_exp_f32_e32 v156, v156
	v_rcp_f32_e32 v186, v159
	v_mul_f32_e32 v159, 0x3dd2d3e8, v185
	v_fma_mix_f32 v158, -v159, v158, s9 op_sel:[0,1,0] op_sel_hi:[0,1,0]
	v_mul_f32_e32 v158, v158, v185
	v_exp_f32_e32 v158, v158
	v_add_f32_e32 v156, 1.0, v156
	v_mul_f32_e32 v162, v162, v160
	v_rcp_f32_e32 v197, v156
	v_exp_f32_e32 v162, v162
	v_add_f32_e32 v158, 1.0, v158
	v_rcp_f32_e32 v187, v158
	v_pk_mul_f32 v[156:157], v[196:197], v[194:195]
	v_add_f32_e32 v162, 1.0, v162
	v_add_f32_e32 v156, 0, v156
	v_rcp_f32_e32 v162, v162
	v_pk_mul_f32 v[192:193], v[190:191], v[188:189]
	v_add_f32_e32 v156, v157, v156
	v_add_f32_e32 v156, v192, v156
	v_pk_mul_f32 v[158:159], v[186:187], v[184:185]
	v_add_f32_e32 v156, v193, v156
	v_add_f32_e32 v156, v158, v156
	v_pk_mul_f32 v[182:183], v[162:163], v[160:161]
	v_add_f32_e32 v156, v159, v156
	v_add_f32_e32 v156, v182, v156
	v_add_f32_e32 v156, v183, v156
	s_nop 0
	global_load_dwordx4 v[18:21], v[18:19], off
	s_mulk_i32 s12, 0x1200
	global_load_dwordx4 v[22:25], v[22:23], off
	s_add_i32 s8, s41, s12
	s_nop 1
	v_add_f32_dpp v156, v156, v156 quad_perm:[1,0,3,2] row_mask:0xf bank_mask:0xf
	s_nop 0
	s_add_i32 s8, s8, 0x10000
	s_lshl_b64 s[6:7], s[6:7], 1
	v_readlane_b32 s12, v251, 0
	v_readlane_b32 s13, v251, 1
	s_nop 1
	v_add_f32_dpp v156, v156, v156 quad_perm:[2,3,0,1] row_mask:0xf bank_mask:0xf
	s_nop 0
	s_add_u32 s6, s12, s6
	v_lshlrev_b32_e32 v0, 1, v0
	s_addc_u32 s7, s13, s7
	v_readlane_b32 s14, v251, 2
	s_nop 1
	v_add_f32_dpp v156, v156, v156 row_half_mirror row_mask:0xf bank_mask:0xf
	v_mul_f32_e32 v156, 0x3c800000, v156
	v_pk_fma_f32 v[158:159], v[196:197], v[194:195], v[156:157] op_sel_hi:[1,1,0] neg_lo:[0,0,1] neg_hi:[0,0,1]
	v_pk_fma_f32 v[188:189], v[190:191], v[188:189], v[156:157] op_sel_hi:[1,1,0] neg_lo:[0,0,1] neg_hi:[0,0,1]
	v_pk_mul_f32 v[182:183], v[158:159], v[158:159]
	v_pk_mul_f32 v[190:191], v[188:189], v[188:189]
	v_pk_fma_f32 v[160:161], v[162:163], v[160:161], v[156:157] op_sel_hi:[1,1,0] neg_lo:[0,0,1] neg_hi:[0,0,1]
	v_add_f32_e32 v162, v182, v183
	v_pk_fma_f32 v[184:185], v[186:187], v[184:185], v[156:157] op_sel_hi:[1,1,0] neg_lo:[0,0,1] neg_hi:[0,0,1]
	v_add_f32_e32 v162, v190, v162
	v_pk_mul_f32 v[186:187], v[184:185], v[184:185]
	v_add_f32_e32 v162, v191, v162
	v_add_f32_e32 v162, v186, v162
	v_pk_mul_f32 v[156:157], v[160:161], v[160:161]
	v_add_f32_e32 v162, v187, v162
	v_add_f32_e32 v156, v156, v162
	v_add_f32_e32 v156, v157, v156
	s_nop 0
	s_waitcnt vmcnt(45)
; #define LAS __attribute__((address_space(3)))
; __device__ __forceinline__ float geluf(float x) { return x * __builtin_amdgcn_rcpf(1.f + __builtin_amdgcn_exp2f(x * (-0.10294324f * x * x - 2.3022082f))); }
; __device__ __forceinline__ float lx_xor(float v, int m, int lane) { return __int_as_float(__builtin_amdgcn_ds_bpermute((lane ^ m) << 2, __float_as_int(v))); }
; __device__ __forceinline__ unsigned cvtpk_h(float lo, float hi) { f32x2 v = {lo, hi}; h16x2 b = __builtin_convertvector(v, h16x2); return __builtin_bit_cast(unsigned, b); }
; __device__ __forceinline__ void gmlp_unit(unsigned char* ws, h16* Y, const h16* Ws16  , const float* bs  , size_t r0, LAS unsigned char* lds, int tid) {
;     ...
;     for (int j = 0; j < 8; ++j) { const int i = tid + 512 * j, row = i >> 5, c8 = i & 31, gg = c8 >> 3, cg = (c8 & 7) * 8;
;         const h16x8 hv = __builtin_bit_cast(h16x8, stg[j]); float x[8]; float sm = 0.f;
; #pragma unroll
;         for (int k = 0; k < 8; ++k) { x[k] = geluf((float)hv[k]); sm += x[k]; }
;         sm += lx_xor(sm, 1, lane); sm += lx_xor(sm, 2, lane); sm += lx_xor(sm, 4, lane);
;         const float mu = sm * (1.f / 64.f); float q = 0.f;
; #pragma unroll
;         for (int k = 0; k < 8; ++k) { x[k] -= mu; q += x[k] * x[k]; }
;         q += lx_xor(q, 1, lane); q += lx_xor(q, 2, lane); q += lx_xor(q, 4, lane);
;         const float rd = __builtin_amdgcn_rsqf(q * (1.f / 64.f) + EPS);
;         u32x4 o; o.x = cvtpk_h(x[0] * rd, x[1] * rd); o.y = cvtpk_h(x[2] * rd, x[3] * rd); o.z = cvtpk_h(x[4] * rd, x[5] * rd); o.w = cvtpk_h(x[6] * rd, x[7] * rd);
;         *(LAS u32x4*)(lds + gg * 16384 + (cg >> 5) * 8192 + row * 64 + (cg & 31) * 2) = o; }
	v_cvt_f32_f16_e32 v190, v152
	v_cvt_f32_f16_sdwa v191, v152 dst_sel:DWORD dst_unused:UNUSED_PAD src0_sel:WORD_1
	v_readlane_b32 s15, v251, 3
	v_readlane_b32 s16, v251, 4
	s_nop 1
	v_add_f32_dpp v156, v156, v156 quad_perm:[1,0,3,2] row_mask:0xf bank_mask:0xf
	s_nop 0
	v_readlane_b32 s17, v251, 5
	v_readlane_b32 s18, v251, 6
	v_readlane_b32 s19, v251, 7
	s_nop 1
	v_add_f32_dpp v156, v156, v156 quad_perm:[2,3,0,1] row_mask:0xf bank_mask:0xf
	s_nop 0
	s_nop 1
	v_add_f32_dpp v156, v156, v156 row_half_mirror row_mask:0xf bank_mask:0xf
	v_fmamk_f32 v156, v156, 0x3c800000, v229
	v_rsq_f32_e32 v162, v156
	s_nop 0
	v_pk_mul_f32 v[156:157], v[158:159], v[162:163] op_sel_hi:[1,0]
	v_pk_mul_f32 v[158:159], v[188:189], v[162:163] op_sel_hi:[1,0]
	v_cvt_pk_f16_f32 v156, v156, v157
	v_cvt_pk_f16_f32 v157, v158, v159
	v_pk_mul_f32 v[158:159], v[184:185], v[162:163] op_sel_hi:[1,0]
	v_cvt_f32_f16_e32 v184, v153
	v_cvt_f32_f16_sdwa v185, v153 dst_sel:DWORD dst_unused:UNUSED_PAD src0_sel:WORD_1
	v_pk_mul_f32 v[160:161], v[160:161], v[162:163] op_sel_hi:[1,0]
	v_cvt_pk_f16_f32 v158, v158, v159
	v_mul_f32_e32 v181, 0x3dd2d3e8, v184
	v_fma_mix_f32 v181, -v181, v153, s9 op_sel_hi:[0,1,0]
	v_mul_f32_e32 v181, v181, v184
	v_exp_f32_e32 v181, v181
	v_cvt_pk_f16_f32 v159, v160, v161
	ds_write_b128 v179, v[156:159] offset:1024
	v_cvt_f32_f16_e32 v156, v155
	v_add_f32_e32 v181, 1.0, v181
	v_cvt_f32_f16_sdwa v157, v155 dst_sel:DWORD dst_unused:UNUSED_PAD src0_sel:WORD_1
	v_rcp_f32_e32 v186, v181
	v_mul_f32_e32 v181, 0x3dd2d3e8, v185
	v_fma_mix_f32 v153, -v181, v153, s9 op_sel:[0,1,0] op_sel_hi:[0,1,0]
	v_mul_f32_e32 v153, v153, v185
	v_exp_f32_e32 v153, v153
	v_mul_f32_e32 v158, 0x3dd2d3e8, v156
	v_mul_f32_e32 v159, 0x3dd2d3e8, v157
	v_fma_mix_f32 v158, -v158, v155, s9 op_sel_hi:[0,1,0]
	v_fma_mix_f32 v155, -v159, v155, s9 op_sel:[0,1,0] op_sel_hi:[0,1,0]
	v_mul_f32_e32 v155, v155, v157
	v_exp_f32_e32 v155, v155
	v_add_f32_e32 v153, 1.0, v153
	v_cvt_f32_f16_e32 v162, v154
	v_rcp_f32_e32 v187, v153
	v_mul_f32_e32 v153, 0x3dd2d3e8, v190
	v_fma_mix_f32 v153, -v153, v152, s9 op_sel_hi:[0,1,0]
	v_mul_f32_e32 v153, v153, v190
	v_add_f32_e32 v155, 1.0, v155
	v_exp_f32_e32 v153, v153
	v_rcp_f32_e32 v159, v155
	v_mul_f32_e32 v155, 0x3dd2d3e8, v162
	v_fma_mix_f32 v155, -v155, v154, s9 op_sel_hi:[0,1,0]
	v_mul_f32_e32 v155, v155, v162
	v_exp_f32_e32 v155, v155
	v_add_f32_e32 v153, 1.0, v153
	v_cvt_f32_f16_sdwa v163, v154 dst_sel:DWORD dst_unused:UNUSED_PAD src0_sel:WORD_1
	v_rcp_f32_e32 v192, v153
	v_mul_f32_e32 v153, 0x3dd2d3e8, v191
	v_fma_mix_f32 v152, -v153, v152, s9 op_sel:[0,1,0] op_sel_hi:[0,1,0]
	v_mul_f32_e32 v152, v152, v191
	v_add_f32_e32 v155, 1.0, v155
	v_exp_f32_e32 v152, v152
	v_rcp_f32_e32 v182, v155
	v_mul_f32_e32 v155, 0x3dd2d3e8, v163
	v_fma_mix_f32 v154, -v155, v154, s9 op_sel:[0,1,0] op_sel_hi:[0,1,0]
	v_mul_f32_e32 v154, v154, v163
	v_exp_f32_e32 v154, v154
	v_add_f32_e32 v152, 1.0, v152
	v_mul_f32_e32 v158, v158, v156
	v_rcp_f32_e32 v193, v152
	v_exp_f32_e32 v158, v158
	v_add_f32_e32 v154, 1.0, v154
	v_rcp_f32_e32 v183, v154
	v_pk_mul_f32 v[152:153], v[192:193], v[190:191]
	v_add_f32_e32 v158, 1.0, v158
	v_add_f32_e32 v152, 0, v152
	v_rcp_f32_e32 v158, v158
	v_pk_mul_f32 v[188:189], v[186:187], v[184:185]
	v_add_f32_e32 v152, v153, v152
	v_add_f32_e32 v152, v188, v152
	v_pk_mul_f32 v[154:155], v[182:183], v[162:163]
	v_add_f32_e32 v152, v189, v152
	v_add_f32_e32 v152, v154, v152
	v_pk_mul_f32 v[160:161], v[158:159], v[156:157]
	v_add_f32_e32 v152, v155, v152
	v_add_f32_e32 v152, v160, v152
	v_add_f32_e32 v152, v161, v152
	s_nop 0
	s_nop 1
	v_add_f32_dpp v152, v152, v152 quad_perm:[1,0,3,2] row_mask:0xf bank_mask:0xf
	s_nop 0
	s_nop 1
	v_add_f32_dpp v152, v152, v152 quad_perm:[2,3,0,1] row_mask:0xf bank_mask:0xf
	s_nop 0
	s_nop 1
	v_add_f32_dpp v152, v152, v152 row_half_mirror row_mask:0xf bank_mask:0xf
	v_mul_f32_e32 v152, 0x3c800000, v152
	v_pk_fma_f32 v[154:155], v[192:193], v[190:191], v[152:153] op_sel_hi:[1,1,0] neg_lo:[0,0,1] neg_hi:[0,0,1]
	v_pk_fma_f32 v[184:185], v[186:187], v[184:185], v[152:153] op_sel_hi:[1,1,0] neg_lo:[0,0,1] neg_hi:[0,0,1]
	v_pk_mul_f32 v[160:161], v[154:155], v[154:155]
	v_pk_mul_f32 v[186:187], v[184:185], v[184:185]
	v_pk_fma_f32 v[156:157], v[158:159], v[156:157], v[152:153] op_sel_hi:[1,1,0] neg_lo:[0,0,1] neg_hi:[0,0,1]
	v_add_f32_e32 v158, v160, v161
	v_pk_fma_f32 v[162:163], v[182:183], v[162:163], v[152:153] op_sel_hi:[1,1,0] neg_lo:[0,0,1] neg_hi:[0,0,1]
	v_add_f32_e32 v158, v186, v158
	v_pk_mul_f32 v[182:183], v[162:163], v[162:163]
	v_add_f32_e32 v158, v187, v158
	v_add_f32_e32 v158, v182, v158
	v_pk_mul_f32 v[152:153], v[156:157], v[156:157]
	v_add_f32_e32 v158, v183, v158
	v_add_f32_e32 v152, v152, v158
	v_add_f32_e32 v152, v153, v152
	s_nop 0
	s_waitcnt vmcnt(44)
; #define LAS __attribute__((address_space(3)))
; __device__ __forceinline__ float geluf(float x) { return x * __builtin_amdgcn_rcpf(1.f + __builtin_amdgcn_exp2f(x * (-0.10294324f * x * x - 2.3022082f))); }
; __device__ __forceinline__ float lx_xor(float v, int m, int lane) { return __int_as_float(__builtin_amdgcn_ds_bpermute((lane ^ m) << 2, __float_as_int(v))); }
; __device__ __forceinline__ unsigned cvtpk_h(float lo, float hi) { f32x2 v = {lo, hi}; h16x2 b = __builtin_convertvector(v, h16x2); return __builtin_bit_cast(unsigned, b); }
; __device__ __forceinline__ void gmlp_unit(unsigned char* ws, h16* Y, const h16* Ws16  , const float* bs  , size_t r0, LAS unsigned char* lds, int tid) {
;     ...
;     for (int j = 0; j < 8; ++j) { const int i = tid + 512 * j, row = i >> 5, c8 = i & 31, gg = c8 >> 3, cg = (c8 & 7) * 8;
;         const h16x8 hv = __builtin_bit_cast(h16x8, stg[j]); float x[8]; float sm = 0.f;
; #pragma unroll
;         for (int k = 0; k < 8; ++k) { x[k] = geluf((float)hv[k]); sm += x[k]; }
;         sm += lx_xor(sm, 1, lane); sm += lx_xor(sm, 2, lane); sm += lx_xor(sm, 4, lane);
;         const float mu = sm * (1.f / 64.f); float q = 0.f;
; #pragma unroll
;         for (int k = 0; k < 8; ++k) { x[k] -= mu; q += x[k] * x[k]; }
;         q += lx_xor(q, 1, lane); q += lx_xor(q, 2, lane); q += lx_xor(q, 4, lane);
;         const float rd = __builtin_amdgcn_rsqf(q * (1.f / 64.f) + EPS);
;         u32x4 o; o.x = cvtpk_h(x[0] * rd, x[1] * rd); o.y = cvtpk_h(x[2] * rd, x[3] * rd); o.z = cvtpk_h(x[4] * rd, x[5] * rd); o.w = cvtpk_h(x[6] * rd, x[7] * rd);
;         *(LAS u32x4*)(lds + gg * 16384 + (cg >> 5) * 8192 + row * 64 + (cg & 31) * 2) = o; }
	v_cvt_f32_f16_e32 v186, v148
	v_cvt_f32_f16_sdwa v187, v148 dst_sel:DWORD dst_unused:UNUSED_PAD src0_sel:WORD_1
	s_nop 1
	v_add_f32_dpp v152, v152, v152 quad_perm:[1,0,3,2] row_mask:0xf bank_mask:0xf
	s_nop 0
	s_nop 1
	v_add_f32_dpp v152, v152, v152 quad_perm:[2,3,0,1] row_mask:0xf bank_mask:0xf
	s_nop 0
	s_nop 1
	v_add_f32_dpp v152, v152, v152 row_half_mirror row_mask:0xf bank_mask:0xf
	v_fmamk_f32 v152, v152, 0x3c800000, v229
	v_rsq_f32_e32 v158, v152
	s_nop 0
	v_pk_mul_f32 v[152:153], v[154:155], v[158:159] op_sel_hi:[1,0]
	v_pk_mul_f32 v[154:155], v[184:185], v[158:159] op_sel_hi:[1,0]
	v_cvt_pk_f16_f32 v152, v152, v153
	v_cvt_pk_f16_f32 v153, v154, v155
	v_pk_mul_f32 v[154:155], v[162:163], v[158:159] op_sel_hi:[1,0]
	v_cvt_f32_f16_e32 v162, v149
	v_cvt_f32_f16_sdwa v163, v149 dst_sel:DWORD dst_unused:UNUSED_PAD src0_sel:WORD_1
	v_pk_mul_f32 v[156:157], v[156:157], v[158:159] op_sel_hi:[1,0]
	v_cvt_pk_f16_f32 v154, v154, v155
	v_mul_f32_e32 v181, 0x3dd2d3e8, v162
	v_fma_mix_f32 v181, -v181, v149, s9 op_sel_hi:[0,1,0]
	v_mul_f32_e32 v181, v181, v162
	v_exp_f32_e32 v181, v181
	v_cvt_pk_f16_f32 v155, v156, v157
	ds_write_b128 v179, v[152:155] offset:2048
	v_cvt_f32_f16_e32 v152, v151
	v_add_f32_e32 v181, 1.0, v181
	v_cvt_f32_f16_sdwa v153, v151 dst_sel:DWORD dst_unused:UNUSED_PAD src0_sel:WORD_1
	v_rcp_f32_e32 v182, v181
	v_mul_f32_e32 v181, 0x3dd2d3e8, v163
	v_fma_mix_f32 v149, -v181, v149, s9 op_sel:[0,1,0] op_sel_hi:[0,1,0]
	v_mul_f32_e32 v149, v149, v163
	v_exp_f32_e32 v149, v149
	v_mul_f32_e32 v154, 0x3dd2d3e8, v152
	v_mul_f32_e32 v155, 0x3dd2d3e8, v153
	v_fma_mix_f32 v154, -v154, v151, s9 op_sel_hi:[0,1,0]
	v_fma_mix_f32 v151, -v155, v151, s9 op_sel:[0,1,0] op_sel_hi:[0,1,0]
	v_mul_f32_e32 v151, v151, v153
	v_exp_f32_e32 v151, v151
	v_add_f32_e32 v149, 1.0, v149
	v_cvt_f32_f16_e32 v158, v150
	v_rcp_f32_e32 v183, v149
	v_mul_f32_e32 v149, 0x3dd2d3e8, v186
	v_fma_mix_f32 v149, -v149, v148, s9 op_sel_hi:[0,1,0]
	v_mul_f32_e32 v149, v149, v186
	v_add_f32_e32 v151, 1.0, v151
	v_exp_f32_e32 v149, v149
	v_rcp_f32_e32 v155, v151
	v_mul_f32_e32 v151, 0x3dd2d3e8, v158
	v_fma_mix_f32 v151, -v151, v150, s9 op_sel_hi:[0,1,0]
	v_mul_f32_e32 v151, v151, v158
	v_exp_f32_e32 v151, v151
	v_add_f32_e32 v149, 1.0, v149
	v_cvt_f32_f16_sdwa v159, v150 dst_sel:DWORD dst_unused:UNUSED_PAD src0_sel:WORD_1
	v_rcp_f32_e32 v188, v149
	v_mul_f32_e32 v149, 0x3dd2d3e8, v187
	v_fma_mix_f32 v148, -v149, v148, s9 op_sel:[0,1,0] op_sel_hi:[0,1,0]
	v_mul_f32_e32 v148, v148, v187
	v_add_f32_e32 v151, 1.0, v151
	v_exp_f32_e32 v148, v148
	v_rcp_f32_e32 v160, v151
	v_mul_f32_e32 v151, 0x3dd2d3e8, v159
	v_fma_mix_f32 v150, -v151, v150, s9 op_sel:[0,1,0] op_sel_hi:[0,1,0]
	v_mul_f32_e32 v150, v150, v159
	v_exp_f32_e32 v150, v150
	v_add_f32_e32 v148, 1.0, v148
	v_mul_f32_e32 v154, v154, v152
	v_rcp_f32_e32 v189, v148
	v_exp_f32_e32 v154, v154
	v_add_f32_e32 v150, 1.0, v150
	v_rcp_f32_e32 v161, v150
	v_pk_mul_f32 v[148:149], v[188:189], v[186:187]
	v_add_f32_e32 v154, 1.0, v154
	v_add_f32_e32 v148, 0, v148
	v_rcp_f32_e32 v154, v154
	v_pk_mul_f32 v[184:185], v[182:183], v[162:163]
	v_add_f32_e32 v148, v149, v148
	v_add_f32_e32 v148, v184, v148
	v_pk_mul_f32 v[150:151], v[160:161], v[158:159]
	v_add_f32_e32 v148, v185, v148
	v_add_f32_e32 v148, v150, v148
	v_pk_mul_f32 v[156:157], v[154:155], v[152:153]
	v_add_f32_e32 v148, v151, v148
	v_add_f32_e32 v148, v156, v148
	v_add_f32_e32 v148, v157, v148
	s_nop 0
	s_nop 1
	v_add_f32_dpp v148, v148, v148 quad_perm:[1,0,3,2] row_mask:0xf bank_mask:0xf
	s_nop 0
	s_nop 1
	v_add_f32_dpp v148, v148, v148 quad_perm:[2,3,0,1] row_mask:0xf bank_mask:0xf
	s_nop 0
	s_nop 1
	v_add_f32_dpp v148, v148, v148 row_half_mirror row_mask:0xf bank_mask:0xf
	v_mul_f32_e32 v148, 0x3c800000, v148
	v_pk_fma_f32 v[150:151], v[188:189], v[186:187], v[148:149] op_sel_hi:[1,1,0] neg_lo:[0,0,1] neg_hi:[0,0,1]
	v_pk_fma_f32 v[162:163], v[182:183], v[162:163], v[148:149] op_sel_hi:[1,1,0] neg_lo:[0,0,1] neg_hi:[0,0,1]
	v_pk_mul_f32 v[156:157], v[150:151], v[150:151]
	v_pk_mul_f32 v[182:183], v[162:163], v[162:163]
	v_pk_fma_f32 v[152:153], v[154:155], v[152:153], v[148:149] op_sel_hi:[1,1,0] neg_lo:[0,0,1] neg_hi:[0,0,1]
	v_add_f32_e32 v154, v156, v157
	v_pk_fma_f32 v[158:159], v[160:161], v[158:159], v[148:149] op_sel_hi:[1,1,0] neg_lo:[0,0,1] neg_hi:[0,0,1]
	v_add_f32_e32 v154, v182, v154
	v_pk_mul_f32 v[160:161], v[158:159], v[158:159]
	v_add_f32_e32 v154, v183, v154
	v_add_f32_e32 v154, v160, v154
	v_pk_mul_f32 v[148:149], v[152:153], v[152:153]
	v_add_f32_e32 v154, v161, v154
	v_add_f32_e32 v148, v148, v154
	v_add_f32_e32 v148, v149, v148
	s_nop 0
	s_waitcnt vmcnt(43)
; #define LAS __attribute__((address_space(3)))
; __device__ __forceinline__ float geluf(float x) { return x * __builtin_amdgcn_rcpf(1.f + __builtin_amdgcn_exp2f(x * (-0.10294324f * x * x - 2.3022082f))); }
; __device__ __forceinline__ float lx_xor(float v, int m, int lane) { return __int_as_float(__builtin_amdgcn_ds_bpermute((lane ^ m) << 2, __float_as_int(v))); }
; __device__ __forceinline__ unsigned cvtpk_h(float lo, float hi) { f32x2 v = {lo, hi}; h16x2 b = __builtin_convertvector(v, h16x2); return __builtin_bit_cast(unsigned, b); }
; __device__ __forceinline__ void gmlp_unit(unsigned char* ws, h16* Y, const h16* Ws16  , const float* bs  , size_t r0, LAS unsigned char* lds, int tid) {
;     ...
;     for (int j = 0; j < 8; ++j) { const int i = tid + 512 * j, row = i >> 5, c8 = i & 31, gg = c8 >> 3, cg = (c8 & 7) * 8;
;         const h16x8 hv = __builtin_bit_cast(h16x8, stg[j]); float x[8]; float sm = 0.f;
; #pragma unroll
;         for (int k = 0; k < 8; ++k) { x[k] = geluf((float)hv[k]); sm += x[k]; }
;         sm += lx_xor(sm, 1, lane); sm += lx_xor(sm, 2, lane); sm += lx_xor(sm, 4, lane);
;         const float mu = sm * (1.f / 64.f); float q = 0.f;
; #pragma unroll
;         for (int k = 0; k < 8; ++k) { x[k] -= mu; q += x[k] * x[k]; }
;         q += lx_xor(q, 1, lane); q += lx_xor(q, 2, lane); q += lx_xor(q, 4, lane);
;         const float rd = __builtin_amdgcn_rsqf(q * (1.f / 64.f) + EPS);
;         u32x4 o; o.x = cvtpk_h(x[0] * rd, x[1] * rd); o.y = cvtpk_h(x[2] * rd, x[3] * rd); o.z = cvtpk_h(x[4] * rd, x[5] * rd); o.w = cvtpk_h(x[6] * rd, x[7] * rd);
;         *(LAS u32x4*)(lds + gg * 16384 + (cg >> 5) * 8192 + row * 64 + (cg & 31) * 2) = o; }
	v_cvt_f32_f16_e32 v182, v14
	v_cvt_f32_f16_sdwa v183, v14 dst_sel:DWORD dst_unused:UNUSED_PAD src0_sel:WORD_1
	s_nop 1
	v_add_f32_dpp v148, v148, v148 quad_perm:[1,0,3,2] row_mask:0xf bank_mask:0xf
	s_nop 0
	s_nop 1
	v_add_f32_dpp v148, v148, v148 quad_perm:[2,3,0,1] row_mask:0xf bank_mask:0xf
	s_nop 0
	s_nop 1
	v_add_f32_dpp v148, v148, v148 row_half_mirror row_mask:0xf bank_mask:0xf
	v_fmamk_f32 v148, v148, 0x3c800000, v229
	v_rsq_f32_e32 v154, v148
	s_nop 0
	v_pk_mul_f32 v[148:149], v[150:151], v[154:155] op_sel_hi:[1,0]
	v_pk_mul_f32 v[150:151], v[162:163], v[154:155] op_sel_hi:[1,0]
	v_cvt_pk_f16_f32 v148, v148, v149
	v_cvt_pk_f16_f32 v149, v150, v151
	v_pk_mul_f32 v[150:151], v[158:159], v[154:155] op_sel_hi:[1,0]
	v_cvt_f32_f16_e32 v158, v15
	v_cvt_f32_f16_sdwa v159, v15 dst_sel:DWORD dst_unused:UNUSED_PAD src0_sel:WORD_1
	v_pk_mul_f32 v[152:153], v[152:153], v[154:155] op_sel_hi:[1,0]
	v_cvt_pk_f16_f32 v150, v150, v151
	v_cvt_pk_f16_f32 v151, v152, v153
	ds_write_b128 v179, v[148:151] offset:3072
	v_cvt_f32_f16_e32 v148, v17
	v_cvt_f32_f16_sdwa v149, v17 dst_sel:DWORD dst_unused:UNUSED_PAD src0_sel:WORD_1
	v_mul_f32_e32 v160, 0x3dd2d3e8, v158
	v_mul_f32_e32 v161, 0x3dd2d3e8, v159
	v_fma_mix_f32 v160, -v160, v15, s9 op_sel_hi:[0,1,0]
	v_fma_mix_f32 v15, -v161, v15, s9 op_sel:[0,1,0] op_sel_hi:[0,1,0]
	v_mul_f32_e32 v15, v15, v159
	v_exp_f32_e32 v15, v15
	v_mul_f32_e32 v150, 0x3dd2d3e8, v148
	v_mul_f32_e32 v151, 0x3dd2d3e8, v149
	v_fma_mix_f32 v150, -v150, v17, s9 op_sel_hi:[0,1,0]
	v_fma_mix_f32 v17, -v151, v17, s9 op_sel:[0,1,0] op_sel_hi:[0,1,0]
	v_mul_f32_e32 v17, v17, v149
	v_exp_f32_e32 v17, v17
	v_add_f32_e32 v15, 1.0, v15
	v_cvt_f32_f16_e32 v154, v16
	v_rcp_f32_e32 v161, v15
	v_mul_f32_e32 v15, 0x3dd2d3e8, v182
	v_fma_mix_f32 v15, -v15, v14, s9 op_sel_hi:[0,1,0]
	v_mul_f32_e32 v15, v15, v182
	v_add_f32_e32 v17, 1.0, v17
	v_exp_f32_e32 v15, v15
	v_rcp_f32_e32 v151, v17
	v_mul_f32_e32 v17, 0x3dd2d3e8, v154
	v_fma_mix_f32 v17, -v17, v16, s9 op_sel_hi:[0,1,0]
	v_mul_f32_e32 v17, v17, v154
	v_exp_f32_e32 v17, v17
	v_add_f32_e32 v15, 1.0, v15
	v_cvt_f32_f16_sdwa v155, v16 dst_sel:DWORD dst_unused:UNUSED_PAD src0_sel:WORD_1
	v_rcp_f32_e32 v184, v15
	v_mul_f32_e32 v15, 0x3dd2d3e8, v183
	v_fma_mix_f32 v14, -v15, v14, s9 op_sel:[0,1,0] op_sel_hi:[0,1,0]
	v_mul_f32_e32 v14, v14, v183
	v_add_f32_e32 v17, 1.0, v17
	v_exp_f32_e32 v14, v14
	v_rcp_f32_e32 v156, v17
	v_mul_f32_e32 v17, 0x3dd2d3e8, v155
	v_mul_f32_e32 v160, v160, v158
	v_fma_mix_f32 v16, -v17, v16, s9 op_sel:[0,1,0] op_sel_hi:[0,1,0]
	v_exp_f32_e32 v160, v160
	v_mul_f32_e32 v16, v16, v155
	v_exp_f32_e32 v16, v16
	v_add_f32_e32 v14, 1.0, v14
	v_mul_f32_e32 v150, v150, v148
	v_rcp_f32_e32 v185, v14
	v_exp_f32_e32 v150, v150
	v_add_f32_e32 v160, 1.0, v160
	v_rcp_f32_e32 v160, v160
	v_add_f32_e32 v16, 1.0, v16
	v_rcp_f32_e32 v157, v16
	v_pk_mul_f32 v[14:15], v[184:185], v[182:183]
	v_add_f32_e32 v150, 1.0, v150
	v_add_f32_e32 v14, 0, v14
	v_rcp_f32_e32 v150, v150
	v_pk_mul_f32 v[162:163], v[160:161], v[158:159]
	v_add_f32_e32 v14, v15, v14
	v_add_f32_e32 v14, v162, v14
	v_pk_mul_f32 v[16:17], v[156:157], v[154:155]
	v_add_f32_e32 v14, v163, v14
	v_add_f32_e32 v14, v16, v14
	v_pk_mul_f32 v[152:153], v[150:151], v[148:149]
	v_add_f32_e32 v14, v17, v14
	v_add_f32_e32 v14, v152, v14
	v_add_f32_e32 v14, v153, v14
	s_nop 0
	s_nop 1
	v_add_f32_dpp v14, v14, v14 quad_perm:[1,0,3,2] row_mask:0xf bank_mask:0xf
	s_nop 0
	s_nop 1
	v_add_f32_dpp v14, v14, v14 quad_perm:[2,3,0,1] row_mask:0xf bank_mask:0xf
	s_nop 0
	s_nop 1
	v_add_f32_dpp v14, v14, v14 row_half_mirror row_mask:0xf bank_mask:0xf
	v_mul_f32_e32 v14, 0x3c800000, v14
	v_pk_fma_f32 v[16:17], v[184:185], v[182:183], v[14:15] op_sel_hi:[1,1,0] neg_lo:[0,0,1] neg_hi:[0,0,1]
	v_pk_fma_f32 v[158:159], v[160:161], v[158:159], v[14:15] op_sel_hi:[1,1,0] neg_lo:[0,0,1] neg_hi:[0,0,1]
	v_pk_mul_f32 v[152:153], v[16:17], v[16:17]
	v_pk_mul_f32 v[160:161], v[158:159], v[158:159]
	v_pk_fma_f32 v[148:149], v[150:151], v[148:149], v[14:15] op_sel_hi:[1,1,0] neg_lo:[0,0,1] neg_hi:[0,0,1]
	v_add_f32_e32 v150, v152, v153
	v_pk_fma_f32 v[154:155], v[156:157], v[154:155], v[14:15] op_sel_hi:[1,1,0] neg_lo:[0,0,1] neg_hi:[0,0,1]
	v_add_f32_e32 v150, v160, v150
	v_pk_mul_f32 v[156:157], v[154:155], v[154:155]
	v_add_f32_e32 v150, v161, v150
	v_add_f32_e32 v150, v156, v150
	v_pk_mul_f32 v[14:15], v[148:149], v[148:149]
	v_add_f32_e32 v150, v157, v150
	v_add_f32_e32 v14, v14, v150
	v_add_f32_e32 v14, v15, v14
	s_nop 0
	s_waitcnt vmcnt(42)
; #define LAS __attribute__((address_space(3)))
; __device__ __forceinline__ float geluf(float x) { return x * __builtin_amdgcn_rcpf(1.f + __builtin_amdgcn_exp2f(x * (-0.10294324f * x * x - 2.3022082f))); }
; __device__ __forceinline__ float lx_xor(float v, int m, int lane) { return __int_as_float(__builtin_amdgcn_ds_bpermute((lane ^ m) << 2, __float_as_int(v))); }
; __device__ __forceinline__ unsigned cvtpk_h(float lo, float hi) { f32x2 v = {lo, hi}; h16x2 b = __builtin_convertvector(v, h16x2); return __builtin_bit_cast(unsigned, b); }
; __device__ __forceinline__ void gmlp_unit(unsigned char* ws, h16* Y, const h16* Ws16  , const float* bs  , size_t r0, LAS unsigned char* lds, int tid) {
;     ...
;     for (int j = 0; j < 8; ++j) { const int i = tid + 512 * j, row = i >> 5, c8 = i & 31, gg = c8 >> 3, cg = (c8 & 7) * 8;
;         const h16x8 hv = __builtin_bit_cast(h16x8, stg[j]); float x[8]; float sm = 0.f;
; #pragma unroll
;         for (int k = 0; k < 8; ++k) { x[k] = geluf((float)hv[k]); sm += x[k]; }
;         sm += lx_xor(sm, 1, lane); sm += lx_xor(sm, 2, lane); sm += lx_xor(sm, 4, lane);
;         const float mu = sm * (1.f / 64.f); float q = 0.f;
; #pragma unroll
;         for (int k = 0; k < 8; ++k) { x[k] -= mu; q += x[k] * x[k]; }
;         q += lx_xor(q, 1, lane); q += lx_xor(q, 2, lane); q += lx_xor(q, 4, lane);
;         const float rd = __builtin_amdgcn_rsqf(q * (1.f / 64.f) + EPS);
;         u32x4 o; o.x = cvtpk_h(x[0] * rd, x[1] * rd); o.y = cvtpk_h(x[2] * rd, x[3] * rd); o.z = cvtpk_h(x[4] * rd, x[5] * rd); o.w = cvtpk_h(x[6] * rd, x[7] * rd);
;         *(LAS u32x4*)(lds + gg * 16384 + (cg >> 5) * 8192 + row * 64 + (cg & 31) * 2) = o; }
	v_cvt_f32_f16_e32 v160, v10
	v_cvt_f32_f16_sdwa v161, v10 dst_sel:DWORD dst_unused:UNUSED_PAD src0_sel:WORD_1
	s_nop 1
	v_add_f32_dpp v14, v14, v14 quad_perm:[1,0,3,2] row_mask:0xf bank_mask:0xf
	s_nop 0
	s_nop 1
	v_add_f32_dpp v14, v14, v14 quad_perm:[2,3,0,1] row_mask:0xf bank_mask:0xf
	s_nop 0
	s_nop 1
	v_add_f32_dpp v14, v14, v14 row_half_mirror row_mask:0xf bank_mask:0xf
	v_fmamk_f32 v14, v14, 0x3c800000, v229
	v_rsq_f32_e32 v150, v14
	s_nop 0
	v_pk_mul_f32 v[14:15], v[16:17], v[150:151] op_sel_hi:[1,0]
	v_pk_mul_f32 v[16:17], v[158:159], v[150:151] op_sel_hi:[1,0]
	v_cvt_pk_f16_f32 v14, v14, v15
	v_cvt_pk_f16_f32 v15, v16, v17
	v_pk_mul_f32 v[16:17], v[154:155], v[150:151] op_sel_hi:[1,0]
	v_cvt_f32_f16_e32 v154, v11
	v_cvt_f32_f16_sdwa v155, v11 dst_sel:DWORD dst_unused:UNUSED_PAD src0_sel:WORD_1
	v_pk_mul_f32 v[148:149], v[148:149], v[150:151] op_sel_hi:[1,0]
	v_cvt_pk_f16_f32 v16, v16, v17
	v_cvt_pk_f16_f32 v17, v148, v149
	ds_write_b128 v179, v[14:17] offset:4096
	v_cvt_f32_f16_e32 v14, v13
	v_cvt_f32_f16_sdwa v15, v13 dst_sel:DWORD dst_unused:UNUSED_PAD src0_sel:WORD_1
	v_mul_f32_e32 v156, 0x3dd2d3e8, v154
	v_mul_f32_e32 v157, 0x3dd2d3e8, v155
	v_fma_mix_f32 v156, -v156, v11, s9 op_sel_hi:[0,1,0]
	v_fma_mix_f32 v11, -v157, v11, s9 op_sel:[0,1,0] op_sel_hi:[0,1,0]
	v_mul_f32_e32 v11, v11, v155
	v_exp_f32_e32 v11, v11
	v_mul_f32_e32 v16, 0x3dd2d3e8, v14
	v_mul_f32_e32 v17, 0x3dd2d3e8, v15
	v_fma_mix_f32 v16, -v16, v13, s9 op_sel_hi:[0,1,0]
	v_fma_mix_f32 v13, -v17, v13, s9 op_sel:[0,1,0] op_sel_hi:[0,1,0]
	v_mul_f32_e32 v13, v13, v15
	v_exp_f32_e32 v13, v13
	v_add_f32_e32 v11, 1.0, v11
	v_cvt_f32_f16_e32 v150, v12
	v_rcp_f32_e32 v157, v11
	v_mul_f32_e32 v11, 0x3dd2d3e8, v160
	v_fma_mix_f32 v11, -v11, v10, s9 op_sel_hi:[0,1,0]
	v_mul_f32_e32 v11, v11, v160
	v_add_f32_e32 v13, 1.0, v13
	v_exp_f32_e32 v11, v11
	v_rcp_f32_e32 v17, v13
	v_mul_f32_e32 v13, 0x3dd2d3e8, v150
	v_fma_mix_f32 v13, -v13, v12, s9 op_sel_hi:[0,1,0]
	v_mul_f32_e32 v13, v13, v150
	v_exp_f32_e32 v13, v13
	v_add_f32_e32 v11, 1.0, v11
	v_cvt_f32_f16_sdwa v151, v12 dst_sel:DWORD dst_unused:UNUSED_PAD src0_sel:WORD_1
	v_rcp_f32_e32 v162, v11
	v_mul_f32_e32 v11, 0x3dd2d3e8, v161
	v_fma_mix_f32 v10, -v11, v10, s9 op_sel:[0,1,0] op_sel_hi:[0,1,0]
	v_mul_f32_e32 v10, v10, v161
	v_add_f32_e32 v13, 1.0, v13
	v_exp_f32_e32 v10, v10
	v_rcp_f32_e32 v152, v13
	v_mul_f32_e32 v13, 0x3dd2d3e8, v151
	v_mul_f32_e32 v156, v156, v154
	v_fma_mix_f32 v12, -v13, v12, s9 op_sel:[0,1,0] op_sel_hi:[0,1,0]
	v_exp_f32_e32 v156, v156
	v_mul_f32_e32 v12, v12, v151
	v_exp_f32_e32 v12, v12
	v_add_f32_e32 v10, 1.0, v10
	v_mul_f32_e32 v16, v16, v14
	v_rcp_f32_e32 v163, v10
	v_exp_f32_e32 v16, v16
	v_add_f32_e32 v156, 1.0, v156
	v_rcp_f32_e32 v156, v156
	v_add_f32_e32 v12, 1.0, v12
	v_rcp_f32_e32 v153, v12
	v_pk_mul_f32 v[10:11], v[162:163], v[160:161]
	v_add_f32_e32 v16, 1.0, v16
	v_add_f32_e32 v10, 0, v10
	v_rcp_f32_e32 v16, v16
	v_pk_mul_f32 v[158:159], v[156:157], v[154:155]
	v_add_f32_e32 v10, v11, v10
	v_add_f32_e32 v10, v158, v10
	v_pk_mul_f32 v[12:13], v[152:153], v[150:151]
	v_add_f32_e32 v10, v159, v10
	v_add_f32_e32 v10, v12, v10
	v_pk_mul_f32 v[148:149], v[16:17], v[14:15]
	v_add_f32_e32 v10, v13, v10
	v_add_f32_e32 v10, v148, v10
	v_add_f32_e32 v10, v149, v10
	s_nop 0
	s_nop 1
	v_add_f32_dpp v10, v10, v10 quad_perm:[1,0,3,2] row_mask:0xf bank_mask:0xf
	s_nop 0
	s_nop 1
	v_add_f32_dpp v10, v10, v10 quad_perm:[2,3,0,1] row_mask:0xf bank_mask:0xf
	s_nop 0
	s_nop 1
	v_add_f32_dpp v10, v10, v10 row_half_mirror row_mask:0xf bank_mask:0xf
	v_mul_f32_e32 v10, 0x3c800000, v10
	v_pk_fma_f32 v[12:13], v[162:163], v[160:161], v[10:11] op_sel_hi:[1,1,0] neg_lo:[0,0,1] neg_hi:[0,0,1]
	v_pk_fma_f32 v[154:155], v[156:157], v[154:155], v[10:11] op_sel_hi:[1,1,0] neg_lo:[0,0,1] neg_hi:[0,0,1]
	v_pk_mul_f32 v[148:149], v[12:13], v[12:13]
	v_pk_mul_f32 v[156:157], v[154:155], v[154:155]
	v_pk_fma_f32 v[14:15], v[16:17], v[14:15], v[10:11] op_sel_hi:[1,1,0] neg_lo:[0,0,1] neg_hi:[0,0,1]
	v_add_f32_e32 v16, v148, v149
	v_pk_fma_f32 v[150:151], v[152:153], v[150:151], v[10:11] op_sel_hi:[1,1,0] neg_lo:[0,0,1] neg_hi:[0,0,1]
	v_add_f32_e32 v16, v156, v16
	v_pk_mul_f32 v[152:153], v[150:151], v[150:151]
	v_add_f32_e32 v16, v157, v16
	v_add_f32_e32 v16, v152, v16
	v_pk_mul_f32 v[10:11], v[14:15], v[14:15]
	v_add_f32_e32 v16, v153, v16
	v_add_f32_e32 v10, v10, v16
	v_add_f32_e32 v10, v11, v10
	s_nop 0
	s_waitcnt vmcnt(41)
; #define LAS __attribute__((address_space(3)))
; __device__ __forceinline__ float geluf(float x) { return x * __builtin_amdgcn_rcpf(1.f + __builtin_amdgcn_exp2f(x * (-0.10294324f * x * x - 2.3022082f))); }
; __device__ __forceinline__ float lx_xor(float v, int m, int lane) { return __int_as_float(__builtin_amdgcn_ds_bpermute((lane ^ m) << 2, __float_as_int(v))); }
; __device__ __forceinline__ unsigned cvtpk_h(float lo, float hi) { f32x2 v = {lo, hi}; h16x2 b = __builtin_convertvector(v, h16x2); return __builtin_bit_cast(unsigned, b); }
; __device__ __forceinline__ void gmlp_unit(unsigned char* ws, h16* Y, const h16* Ws16  , const float* bs  , size_t r0, LAS unsigned char* lds, int tid) {
;     ...
;     for (int j = 0; j < 8; ++j) { const int i = tid + 512 * j, row = i >> 5, c8 = i & 31, gg = c8 >> 3, cg = (c8 & 7) * 8;
;         const h16x8 hv = __builtin_bit_cast(h16x8, stg[j]); float x[8]; float sm = 0.f;
; #pragma unroll
;         for (int k = 0; k < 8; ++k) { x[k] = geluf((float)hv[k]); sm += x[k]; }
;         sm += lx_xor(sm, 1, lane); sm += lx_xor(sm, 2, lane); sm += lx_xor(sm, 4, lane);
;         const float mu = sm * (1.f / 64.f); float q = 0.f;
; #pragma unroll
;         for (int k = 0; k < 8; ++k) { x[k] -= mu; q += x[k] * x[k]; }
;         q += lx_xor(q, 1, lane); q += lx_xor(q, 2, lane); q += lx_xor(q, 4, lane);
;         const float rd = __builtin_amdgcn_rsqf(q * (1.f / 64.f) + EPS);
;         u32x4 o; o.x = cvtpk_h(x[0] * rd, x[1] * rd); o.y = cvtpk_h(x[2] * rd, x[3] * rd); o.z = cvtpk_h(x[4] * rd, x[5] * rd); o.w = cvtpk_h(x[6] * rd, x[7] * rd);
;         *(LAS u32x4*)(lds + gg * 16384 + (cg >> 5) * 8192 + row * 64 + (cg & 31) * 2) = o; }
	v_cvt_f32_f16_e32 v156, v6
	v_cvt_f32_f16_sdwa v157, v6 dst_sel:DWORD dst_unused:UNUSED_PAD src0_sel:WORD_1
	s_nop 1
	v_add_f32_dpp v10, v10, v10 quad_perm:[1,0,3,2] row_mask:0xf bank_mask:0xf
	s_nop 0
	s_nop 1
	v_add_f32_dpp v10, v10, v10 quad_perm:[2,3,0,1] row_mask:0xf bank_mask:0xf
	s_nop 0
	s_nop 1
	v_add_f32_dpp v10, v10, v10 row_half_mirror row_mask:0xf bank_mask:0xf
	v_fmamk_f32 v10, v10, 0x3c800000, v229
	v_rsq_f32_e32 v16, v10
	s_nop 0
	v_pk_mul_f32 v[10:11], v[12:13], v[16:17] op_sel_hi:[1,0]
	v_pk_mul_f32 v[12:13], v[154:155], v[16:17] op_sel_hi:[1,0]
	v_cvt_pk_f16_f32 v10, v10, v11
	v_cvt_pk_f16_f32 v11, v12, v13
	v_pk_mul_f32 v[12:13], v[150:151], v[16:17] op_sel_hi:[1,0]
	v_cvt_f32_f16_e32 v150, v7
	v_cvt_f32_f16_sdwa v151, v7 dst_sel:DWORD dst_unused:UNUSED_PAD src0_sel:WORD_1
	v_pk_mul_f32 v[14:15], v[14:15], v[16:17] op_sel_hi:[1,0]
	v_cvt_pk_f16_f32 v12, v12, v13
	v_cvt_pk_f16_f32 v13, v14, v15
	ds_write_b128 v179, v[10:13] offset:5120
	v_cvt_f32_f16_e32 v10, v9
	v_cvt_f32_f16_sdwa v11, v9 dst_sel:DWORD dst_unused:UNUSED_PAD src0_sel:WORD_1
	v_mul_f32_e32 v152, 0x3dd2d3e8, v150
	v_mul_f32_e32 v153, 0x3dd2d3e8, v151
	v_fma_mix_f32 v152, -v152, v7, s9 op_sel_hi:[0,1,0]
	v_fma_mix_f32 v7, -v153, v7, s9 op_sel:[0,1,0] op_sel_hi:[0,1,0]
	v_mul_f32_e32 v7, v7, v151
	v_exp_f32_e32 v7, v7
	v_mul_f32_e32 v12, 0x3dd2d3e8, v10
	v_mul_f32_e32 v13, 0x3dd2d3e8, v11
	v_fma_mix_f32 v12, -v12, v9, s9 op_sel_hi:[0,1,0]
	v_fma_mix_f32 v9, -v13, v9, s9 op_sel:[0,1,0] op_sel_hi:[0,1,0]
	v_mul_f32_e32 v9, v9, v11
	v_exp_f32_e32 v9, v9
	v_add_f32_e32 v7, 1.0, v7
	v_cvt_f32_f16_e32 v16, v8
	v_rcp_f32_e32 v153, v7
	v_mul_f32_e32 v7, 0x3dd2d3e8, v156
	v_fma_mix_f32 v7, -v7, v6, s9 op_sel_hi:[0,1,0]
	v_mul_f32_e32 v7, v7, v156
	v_add_f32_e32 v9, 1.0, v9
	v_exp_f32_e32 v7, v7
	v_rcp_f32_e32 v13, v9
	v_mul_f32_e32 v9, 0x3dd2d3e8, v16
	v_fma_mix_f32 v9, -v9, v8, s9 op_sel_hi:[0,1,0]
	v_mul_f32_e32 v9, v9, v16
	v_exp_f32_e32 v9, v9
	v_add_f32_e32 v7, 1.0, v7
	v_cvt_f32_f16_sdwa v17, v8 dst_sel:DWORD dst_unused:UNUSED_PAD src0_sel:WORD_1
	v_rcp_f32_e32 v158, v7
	v_mul_f32_e32 v7, 0x3dd2d3e8, v157
	v_fma_mix_f32 v6, -v7, v6, s9 op_sel:[0,1,0] op_sel_hi:[0,1,0]
	v_mul_f32_e32 v6, v6, v157
	v_add_f32_e32 v9, 1.0, v9
	v_exp_f32_e32 v6, v6
	v_rcp_f32_e32 v148, v9
	v_mul_f32_e32 v9, 0x3dd2d3e8, v17
	v_mul_f32_e32 v152, v152, v150
	v_fma_mix_f32 v8, -v9, v8, s9 op_sel:[0,1,0] op_sel_hi:[0,1,0]
	v_exp_f32_e32 v152, v152
	v_mul_f32_e32 v8, v8, v17
	v_exp_f32_e32 v8, v8
	v_add_f32_e32 v6, 1.0, v6
	v_mul_f32_e32 v12, v12, v10
	v_rcp_f32_e32 v159, v6
	v_exp_f32_e32 v12, v12
	v_add_f32_e32 v152, 1.0, v152
	v_rcp_f32_e32 v152, v152
	v_add_f32_e32 v8, 1.0, v8
	v_rcp_f32_e32 v149, v8
	v_pk_mul_f32 v[6:7], v[158:159], v[156:157]
	v_add_f32_e32 v12, 1.0, v12
	v_add_f32_e32 v6, 0, v6
	v_rcp_f32_e32 v12, v12
	v_pk_mul_f32 v[154:155], v[152:153], v[150:151]
	v_add_f32_e32 v6, v7, v6
	v_add_f32_e32 v6, v154, v6
	v_pk_mul_f32 v[8:9], v[148:149], v[16:17]
	v_add_f32_e32 v6, v155, v6
	v_add_f32_e32 v6, v8, v6
	v_pk_mul_f32 v[14:15], v[12:13], v[10:11]
	v_add_f32_e32 v6, v9, v6
	v_add_f32_e32 v6, v14, v6
	v_add_f32_e32 v6, v15, v6
	s_nop 0
	s_nop 1
	v_add_f32_dpp v6, v6, v6 quad_perm:[1,0,3,2] row_mask:0xf bank_mask:0xf
	s_nop 0
	s_nop 1
	v_add_f32_dpp v6, v6, v6 quad_perm:[2,3,0,1] row_mask:0xf bank_mask:0xf
	s_nop 0
	s_nop 1
	v_add_f32_dpp v6, v6, v6 row_half_mirror row_mask:0xf bank_mask:0xf
	v_mul_f32_e32 v6, 0x3c800000, v6
	v_pk_fma_f32 v[8:9], v[158:159], v[156:157], v[6:7] op_sel_hi:[1,1,0] neg_lo:[0,0,1] neg_hi:[0,0,1]
	v_pk_fma_f32 v[150:151], v[152:153], v[150:151], v[6:7] op_sel_hi:[1,1,0] neg_lo:[0,0,1] neg_hi:[0,0,1]
	v_pk_mul_f32 v[14:15], v[8:9], v[8:9]
	v_pk_mul_f32 v[152:153], v[150:151], v[150:151]
	v_pk_fma_f32 v[10:11], v[12:13], v[10:11], v[6:7] op_sel_hi:[1,1,0] neg_lo:[0,0,1] neg_hi:[0,0,1]
	v_add_f32_e32 v12, v14, v15
	v_pk_fma_f32 v[16:17], v[148:149], v[16:17], v[6:7] op_sel_hi:[1,1,0] neg_lo:[0,0,1] neg_hi:[0,0,1]
	v_add_f32_e32 v12, v152, v12
	v_pk_mul_f32 v[148:149], v[16:17], v[16:17]
	v_add_f32_e32 v12, v153, v12
	v_add_f32_e32 v12, v148, v12
	v_pk_mul_f32 v[6:7], v[10:11], v[10:11]
	v_add_f32_e32 v12, v149, v12
	v_add_f32_e32 v6, v6, v12
	v_add_f32_e32 v6, v7, v6
	s_nop 0
	s_waitcnt vmcnt(40)
; #define LAS __attribute__((address_space(3)))
; __device__ __forceinline__ float geluf(float x) { return x * __builtin_amdgcn_rcpf(1.f + __builtin_amdgcn_exp2f(x * (-0.10294324f * x * x - 2.3022082f))); }
; __device__ __forceinline__ float lx_xor(float v, int m, int lane) { return __int_as_float(__builtin_amdgcn_ds_bpermute((lane ^ m) << 2, __float_as_int(v))); }
; __device__ __forceinline__ unsigned cvtpk_h(float lo, float hi) { f32x2 v = {lo, hi}; h16x2 b = __builtin_convertvector(v, h16x2); return __builtin_bit_cast(unsigned, b); }
; #define BAR_LDS() asm volatile("s_waitcnt lgkmcnt(0)\n\ts_barrier" ::: "memory")
; __device__ __forceinline__ void gmlp_unit(unsigned char* ws, h16* Y, const h16* Ws16  , const float* bs  , size_t r0, LAS unsigned char* lds, int tid) {
;     ...
;     for (int j = 0; j < 8; ++j) { const int i = tid + 512 * j, row = i >> 5, c8 = i & 31, gg = c8 >> 3, cg = (c8 & 7) * 8;
;         const h16x8 hv = __builtin_bit_cast(h16x8, stg[j]); float x[8]; float sm = 0.f;
; #pragma unroll
;         for (int k = 0; k < 8; ++k) { x[k] = geluf((float)hv[k]); sm += x[k]; }
;         sm += lx_xor(sm, 1, lane); sm += lx_xor(sm, 2, lane); sm += lx_xor(sm, 4, lane);
;         const float mu = sm * (1.f / 64.f); float q = 0.f;
; #pragma unroll
;         for (int k = 0; k < 8; ++k) { x[k] -= mu; q += x[k] * x[k]; }
;         q += lx_xor(q, 1, lane); q += lx_xor(q, 2, lane); q += lx_xor(q, 4, lane);
;         const float rd = __builtin_amdgcn_rsqf(q * (1.f / 64.f) + EPS);
;         u32x4 o; o.x = cvtpk_h(x[0] * rd, x[1] * rd); o.y = cvtpk_h(x[2] * rd, x[3] * rd); o.z = cvtpk_h(x[4] * rd, x[5] * rd); o.w = cvtpk_h(x[6] * rd, x[7] * rd);
;         *(LAS u32x4*)(lds + gg * 16384 + (cg >> 5) * 8192 + row * 64 + (cg & 31) * 2) = o; }
;     BAR_LDS();
	v_cvt_f32_f16_e32 v152, v2
	v_cvt_f32_f16_sdwa v153, v2 dst_sel:DWORD dst_unused:UNUSED_PAD src0_sel:WORD_1
	s_nop 1
	v_add_f32_dpp v6, v6, v6 quad_perm:[1,0,3,2] row_mask:0xf bank_mask:0xf
	s_nop 0
	s_nop 1
	v_add_f32_dpp v6, v6, v6 quad_perm:[2,3,0,1] row_mask:0xf bank_mask:0xf
	s_nop 0
	s_nop 1
	v_add_f32_dpp v6, v6, v6 row_half_mirror row_mask:0xf bank_mask:0xf
	v_fmamk_f32 v6, v6, 0x3c800000, v229
	v_rsq_f32_e32 v12, v6
	s_nop 0
	v_pk_mul_f32 v[6:7], v[8:9], v[12:13] op_sel_hi:[1,0]
	v_pk_mul_f32 v[8:9], v[150:151], v[12:13] op_sel_hi:[1,0]
	v_cvt_pk_f16_f32 v6, v6, v7
	v_cvt_pk_f16_f32 v7, v8, v9
	v_pk_mul_f32 v[8:9], v[16:17], v[12:13] op_sel_hi:[1,0]
	v_cvt_f32_f16_e32 v16, v3
	v_cvt_f32_f16_sdwa v17, v3 dst_sel:DWORD dst_unused:UNUSED_PAD src0_sel:WORD_1
	v_pk_mul_f32 v[10:11], v[10:11], v[12:13] op_sel_hi:[1,0]
	v_cvt_pk_f16_f32 v8, v8, v9
	v_cvt_pk_f16_f32 v9, v10, v11
	ds_write_b128 v179, v[6:9] offset:6144
	v_cvt_f32_f16_e32 v6, v5
	v_cvt_f32_f16_sdwa v7, v5 dst_sel:DWORD dst_unused:UNUSED_PAD src0_sel:WORD_1
	v_mul_f32_e32 v148, 0x3dd2d3e8, v16
	v_mul_f32_e32 v149, 0x3dd2d3e8, v17
	v_fma_mix_f32 v148, -v148, v3, s9 op_sel_hi:[0,1,0]
	v_fma_mix_f32 v3, -v149, v3, s9 op_sel:[0,1,0] op_sel_hi:[0,1,0]
	v_mul_f32_e32 v3, v3, v17
	v_exp_f32_e32 v3, v3
	v_mul_f32_e32 v8, 0x3dd2d3e8, v6
	v_mul_f32_e32 v9, 0x3dd2d3e8, v7
	v_fma_mix_f32 v8, -v8, v5, s9 op_sel_hi:[0,1,0]
	v_fma_mix_f32 v5, -v9, v5, s9 op_sel:[0,1,0] op_sel_hi:[0,1,0]
	v_mul_f32_e32 v5, v5, v7
	v_exp_f32_e32 v5, v5
	v_add_f32_e32 v3, 1.0, v3
	v_cvt_f32_f16_e32 v12, v4
	v_rcp_f32_e32 v149, v3
	v_mul_f32_e32 v3, 0x3dd2d3e8, v152
	v_fma_mix_f32 v3, -v3, v2, s9 op_sel_hi:[0,1,0]
	v_mul_f32_e32 v3, v3, v152
	v_add_f32_e32 v5, 1.0, v5
	v_exp_f32_e32 v3, v3
	v_rcp_f32_e32 v9, v5
	v_mul_f32_e32 v5, 0x3dd2d3e8, v12
	v_fma_mix_f32 v5, -v5, v4, s9 op_sel_hi:[0,1,0]
	v_mul_f32_e32 v5, v5, v12
	v_exp_f32_e32 v5, v5
	v_add_f32_e32 v3, 1.0, v3
	v_cvt_f32_f16_sdwa v13, v4 dst_sel:DWORD dst_unused:UNUSED_PAD src0_sel:WORD_1
	v_rcp_f32_e32 v154, v3
	v_mul_f32_e32 v3, 0x3dd2d3e8, v153
	v_fma_mix_f32 v2, -v3, v2, s9 op_sel:[0,1,0] op_sel_hi:[0,1,0]
	v_mul_f32_e32 v2, v2, v153
	v_add_f32_e32 v5, 1.0, v5
	v_exp_f32_e32 v2, v2
	v_rcp_f32_e32 v14, v5
	v_mul_f32_e32 v5, 0x3dd2d3e8, v13
	v_mul_f32_e32 v148, v148, v16
	v_fma_mix_f32 v4, -v5, v4, s9 op_sel:[0,1,0] op_sel_hi:[0,1,0]
	v_exp_f32_e32 v148, v148
	v_mul_f32_e32 v4, v4, v13
	v_exp_f32_e32 v4, v4
	v_add_f32_e32 v2, 1.0, v2
	v_mul_f32_e32 v8, v8, v6
	v_rcp_f32_e32 v155, v2
	v_exp_f32_e32 v8, v8
	v_add_f32_e32 v148, 1.0, v148
	v_rcp_f32_e32 v148, v148
	v_add_f32_e32 v4, 1.0, v4
	v_rcp_f32_e32 v15, v4
	v_pk_mul_f32 v[2:3], v[154:155], v[152:153]
	v_add_f32_e32 v8, 1.0, v8
	v_add_f32_e32 v2, 0, v2
	v_rcp_f32_e32 v8, v8
	v_pk_mul_f32 v[150:151], v[148:149], v[16:17]
	v_add_f32_e32 v2, v3, v2
	v_add_f32_e32 v2, v150, v2
	v_pk_mul_f32 v[4:5], v[14:15], v[12:13]
	v_add_f32_e32 v2, v151, v2
	v_add_f32_e32 v2, v4, v2
	v_pk_mul_f32 v[10:11], v[8:9], v[6:7]
	v_add_f32_e32 v2, v5, v2
	v_add_f32_e32 v2, v10, v2
	v_add_f32_e32 v2, v11, v2
	s_nop 0
	v_lshlrev_b32_e32 v150, 1, v169
	s_nop 1
	v_add_f32_dpp v2, v2, v2 quad_perm:[1,0,3,2] row_mask:0xf bank_mask:0xf
	s_nop 0
	s_nop 1
	v_add_f32_dpp v2, v2, v2 quad_perm:[2,3,0,1] row_mask:0xf bank_mask:0xf
	s_nop 0
	s_nop 1
	v_add_f32_dpp v2, v2, v2 row_half_mirror row_mask:0xf bank_mask:0xf
	v_mul_f32_e32 v2, 0x3c800000, v2
	v_pk_fma_f32 v[4:5], v[154:155], v[152:153], v[2:3] op_sel_hi:[1,1,0] neg_lo:[0,0,1] neg_hi:[0,0,1]
	v_pk_fma_f32 v[16:17], v[148:149], v[16:17], v[2:3] op_sel_hi:[1,1,0] neg_lo:[0,0,1] neg_hi:[0,0,1]
	v_pk_mul_f32 v[10:11], v[4:5], v[4:5]
	v_pk_mul_f32 v[148:149], v[16:17], v[16:17]
	v_pk_fma_f32 v[6:7], v[8:9], v[6:7], v[2:3] op_sel_hi:[1,1,0] neg_lo:[0,0,1] neg_hi:[0,0,1]
	v_add_f32_e32 v8, v10, v11
	v_pk_fma_f32 v[12:13], v[14:15], v[12:13], v[2:3] op_sel_hi:[1,1,0] neg_lo:[0,0,1] neg_hi:[0,0,1]
	v_add_f32_e32 v8, v148, v8
	v_pk_mul_f32 v[14:15], v[12:13], v[12:13]
	v_add_f32_e32 v8, v149, v8
	v_add_f32_e32 v8, v14, v8
	v_pk_mul_f32 v[2:3], v[6:7], v[6:7]
	v_add_f32_e32 v8, v15, v8
	v_add_f32_e32 v2, v2, v8
	v_add_f32_e32 v2, v3, v2
	s_nop 0
	v_lshl_add_u64 v[148:149], s[6:7], 0, v[0:1]
	s_nop 1
	v_add_f32_dpp v2, v2, v2 quad_perm:[1,0,3,2] row_mask:0xf bank_mask:0xf
	s_nop 0
	s_nop 1
	v_add_f32_dpp v2, v2, v2 quad_perm:[2,3,0,1] row_mask:0xf bank_mask:0xf
	s_nop 0
	s_nop 1
	v_add_f32_dpp v2, v2, v2 row_half_mirror row_mask:0xf bank_mask:0xf
	v_fmamk_f32 v2, v2, 0x3c800000, v229
	v_rsq_f32_e32 v8, v2
	s_nop 0
	v_pk_mul_f32 v[2:3], v[4:5], v[8:9] op_sel_hi:[1,0]
	v_pk_mul_f32 v[4:5], v[16:17], v[8:9] op_sel_hi:[1,0]
	v_cvt_pk_f16_f32 v2, v2, v3
	v_cvt_pk_f16_f32 v3, v4, v5
	v_pk_mul_f32 v[4:5], v[12:13], v[8:9] op_sel_hi:[1,0]
	v_pk_mul_f32 v[6:7], v[6:7], v[8:9] op_sel_hi:[1,0]
	v_cvt_pk_f16_f32 v4, v4, v5
	v_cvt_pk_f16_f32 v5, v6, v7
	ds_write_b128 v179, v[2:5] offset:7168
	v_and_b32_e32 v3, 16, v247
	v_and_or_b32 v3, v164, 12, v3
	v_and_b32_e32 v2, 0x2c0, v171
	v_lshlrev_b32_e32 v3, 1, v3
	s_waitcnt lgkmcnt(0)
	s_barrier
; #define LAS __attribute__((address_space(3)))
; #define GAS __attribute__((address_space(1)))
; __device__ __forceinline__ float siluf(float x) { return x * __builtin_amdgcn_rcpf(1.f + __builtin_amdgcn_exp2f(-1.4426950408889634f * x)); }
; __device__ __forceinline__ float geluf(float x) { return x * __builtin_amdgcn_rcpf(1.f + __builtin_amdgcn_exp2f(x * (-0.10294324f * x * x - 2.3022082f))); }
; __device__ __forceinline__ unsigned cvtpk_h(float lo, float hi) { f32x2 v = {lo, hi}; h16x2 b = __builtin_convertvector(v, h16x2); return __builtin_bit_cast(unsigned, b); }
; #define LDS_WAIT() asm volatile("s_waitcnt lgkmcnt(0)" ::: "memory")
; __device__ __forceinline__ int crow(int r, int hi) { return (r & 3) + 8 * (r >> 2) + 4 * hi; }
; __device__ __forceinline__ void gmlp_unit(unsigned char* ws, h16* Y, const h16* Ws16  , const float* bs  , size_t r0, LAS unsigned char* lds, int tid) {
;     ...
;     LAS h16* scr = (LAS h16*)(lds + GM_SCR) + wid * (32 * 72);
; #pragma unroll
;     for (int q = 0; q < 2; ++q) {
; #pragma unroll
;         for (int db = 0; db < 2; ++db) {
;             s16x8 bf[8];
; #pragma unroll
;             for (int ks = 0; ks < 8; ++ks) bf[ks] = tr_frag((LAS const char*)lds + g * 16384, 8192, db, ks, lane);
;             f32x16 acc = f32x16{};
; #pragma unroll
;             for (int ks = 0; ks < 8; ++ks) acc = __builtin_amdgcn_mfma_f32_32x32x16_f16(H8(af[q][ks]), H8(bf[ks]), acc, 0, 0, 0);
; #pragma unroll
;             for (int r = 0; r < 16; ++r) scr[crow(r, hi) * 72 + 32 * db + r32] = (h16)acc[r];
;         }
;         LDS_WAIT();
; #pragma unroll
;         for (int ps = 0; ps < 4; ++ps) { const int row = 8 * ps + erow;
;             const h16x8 sv = *(const LAS h16x8*)(scr + row * 72 + 8 * ech);
;             float y[8];
; #pragma unroll
;             for (int k = 0; k < 8; ++k) y[k] = geluf((float)gu[q][ps][k]) * ((float)sv[k] + bias[q][ps]) * siluf((float)sz[q][ps][k]);
;             u32x4 w0; w0.x = cvtpk_h(y[0], y[1]); w0.y = cvtpk_h(y[2], y[3]); w0.z = cvtpk_h(y[4], y[5]); w0.w = cvtpk_h(y[6], y[7]);
;             *(GAS u32x4*)(Y + (r0 + 32 * (2 * ph + q) + row) * D + g * 64 + 8 * ech) = w0; }
	v_add3_u32 v151, s4, v2, v3
	ds_read_b64_tr_b16 v[2:3], v151
	ds_read_b64_tr_b16 v[4:5], v151 offset:256
	ds_read_b64_tr_b16 v[152:153], v151 offset:1024
	ds_read_b64_tr_b16 v[154:155], v151 offset:1280
	ds_read_b64_tr_b16 v[156:157], v151 offset:2048
	ds_read_b64_tr_b16 v[158:159], v151 offset:2304
	ds_read_b64_tr_b16 v[160:161], v151 offset:3072
	ds_read_b64_tr_b16 v[162:163], v151 offset:3328
	ds_read_b64_tr_b16 v[182:183], v151 offset:4096
	ds_read_b64_tr_b16 v[184:185], v151 offset:4352
	ds_read_b64_tr_b16 v[186:187], v151 offset:5120
	ds_read_b64_tr_b16 v[188:189], v151 offset:5376
	ds_read_b64_tr_b16 v[190:191], v151 offset:6144
	ds_read_b64_tr_b16 v[192:193], v151 offset:6400
	ds_read_b64_tr_b16 v[194:195], v151 offset:7168
	ds_read_b64_tr_b16 v[196:197], v151 offset:7424
	s_waitcnt vmcnt(39) lgkmcnt(14)
	v_mfma_f32_32x32x16_f16 v[2:17], v[140:143], v[2:5], 0
	s_or_b32 s4, s2, s5
	v_or_b32_e32 v164, s4, v167
	s_or_b32 s2, s2, s3
	s_waitcnt vmcnt(38) lgkmcnt(12)
	v_mfma_f32_32x32x16_f16 v[2:17], v[144:147], v[152:155], v[2:17]
	v_mul_u32_u24_e32 v152, 0x240, v248
	v_add3_u32 v150, s8, v150, v152
	s_waitcnt vmcnt(37) lgkmcnt(10)
	v_mfma_f32_32x32x16_f16 v[2:17], v[136:139], v[156:159], v[2:17]
	s_waitcnt vmcnt(36) lgkmcnt(8)
	v_mfma_f32_32x32x16_f16 v[2:17], v[132:135], v[160:163], v[2:17]
	s_waitcnt vmcnt(35) lgkmcnt(6)
	v_mfma_f32_32x32x16_f16 v[2:17], v[126:129], v[182:185], v[2:17]
	s_waitcnt vmcnt(34) lgkmcnt(4)
	v_mfma_f32_32x32x16_f16 v[2:17], v[122:125], v[186:189], v[2:17]
	s_waitcnt vmcnt(33) lgkmcnt(2)
	v_mfma_f32_32x32x16_f16 v[2:17], v[118:121], v[190:193], v[2:17]
	s_waitcnt vmcnt(32) lgkmcnt(0)
	v_mfma_f32_32x32x16_f16 v[2:17], v[114:117], v[194:197], v[2:17]
	s_nop 11
	v_cvt_f16_f32_e32 v2, v2
	ds_write_b16 v150, v2
	v_cvt_f16_f32_e32 v2, v3
	ds_write_b16 v150, v2 offset:144
	v_cvt_f16_f32_e32 v2, v4
	ds_write_b16 v150, v2 offset:288
	v_cvt_f16_f32_e32 v2, v5
	ds_write_b16 v150, v2 offset:432
	v_cvt_f16_f32_e32 v2, v6
	ds_write_b16 v150, v2 offset:1152
	v_cvt_f16_f32_e32 v2, v7
	ds_write_b16 v150, v2 offset:1296
	v_cvt_f16_f32_e32 v2, v8
	ds_write_b16 v150, v2 offset:1440
	v_cvt_f16_f32_e32 v2, v9
	ds_write_b16 v150, v2 offset:1584
	v_cvt_f16_f32_e32 v2, v10
	ds_write_b16 v150, v2 offset:2304
	v_cvt_f16_f32_e32 v2, v11
	ds_write_b16 v150, v2 offset:2448
	v_cvt_f16_f32_e32 v2, v12
	ds_write_b16 v150, v2 offset:2592
	v_cvt_f16_f32_e32 v2, v13
	ds_write_b16 v150, v2 offset:2736
	v_cvt_f16_f32_e32 v2, v14
	ds_write_b16 v150, v2 offset:3456
	v_cvt_f16_f32_e32 v2, v15
	ds_write_b16 v150, v2 offset:3600
	v_cvt_f16_f32_e32 v2, v16
	ds_write_b16 v150, v2 offset:3744
	v_cvt_f16_f32_e32 v2, v17
	ds_write_b16 v150, v2 offset:3888
	ds_read_b64_tr_b16 v[2:3], v151 offset:8192
	ds_read_b64_tr_b16 v[4:5], v151 offset:8448
	ds_read_b64_tr_b16 v[152:153], v151 offset:9216
	ds_read_b64_tr_b16 v[154:155], v151 offset:9472
	ds_read_b64_tr_b16 v[156:157], v151 offset:10240
	ds_read_b64_tr_b16 v[158:159], v151 offset:10496
	ds_read_b64_tr_b16 v[160:161], v151 offset:11264
	ds_read_b64_tr_b16 v[162:163], v151 offset:11520
	ds_read_b64_tr_b16 v[182:183], v151 offset:12288
	ds_read_b64_tr_b16 v[184:185], v151 offset:12544
	ds_read_b64_tr_b16 v[186:187], v151 offset:13312
	ds_read_b64_tr_b16 v[188:189], v151 offset:13568
	ds_read_b64_tr_b16 v[190:191], v151 offset:14336
	ds_read_b64_tr_b16 v[192:193], v151 offset:14592
	ds_read_b64_tr_b16 v[194:195], v151 offset:15360
	ds_read_b64_tr_b16 v[196:197], v151 offset:15616
	s_waitcnt lgkmcnt(14)
	v_mfma_f32_32x32x16_f16 v[2:17], v[140:143], v[2:5], 0
	s_waitcnt lgkmcnt(12)
	v_mfma_f32_32x32x16_f16 v[2:17], v[144:147], v[152:155], v[2:17]
	s_waitcnt lgkmcnt(10)
	v_mfma_f32_32x32x16_f16 v[2:17], v[136:139], v[156:159], v[2:17]
	s_waitcnt lgkmcnt(8)
	v_mfma_f32_32x32x16_f16 v[2:17], v[132:135], v[160:163], v[2:17]
	s_waitcnt lgkmcnt(6)
	v_mfma_f32_32x32x16_f16 v[2:17], v[126:129], v[182:185], v[2:17]
	s_waitcnt lgkmcnt(4)
	v_mfma_f32_32x32x16_f16 v[2:17], v[122:125], v[186:189], v[2:17]
	s_waitcnt lgkmcnt(2)
	v_mfma_f32_32x32x16_f16 v[2:17], v[118:121], v[190:193], v[2:17]
	s_waitcnt lgkmcnt(0)
	v_mfma_f32_32x32x16_f16 v[2:17], v[114:117], v[194:197], v[2:17]
	s_nop 11
	v_cvt_f16_f32_e32 v2, v2
	ds_write_b16 v150, v2 offset:64
	v_cvt_f16_f32_e32 v2, v3
	ds_write_b16 v150, v2 offset:208
	v_cvt_f16_f32_e32 v2, v4
	ds_write_b16 v150, v2 offset:352
	v_cvt_f16_f32_e32 v2, v5
	ds_write_b16 v150, v2 offset:496
	v_cvt_f16_f32_e32 v2, v6
	s_waitcnt vmcnt(23)
	v_cvt_f32_f16_e32 v6, v106
	ds_write_b16 v150, v2 offset:1216
	v_cvt_f16_f32_e32 v2, v7
	v_cvt_f32_f16_sdwa v7, v106 dst_sel:DWORD dst_unused:UNUSED_PAD src0_sel:WORD_1
	ds_write_b16 v150, v2 offset:1360
	v_cvt_f16_f32_e32 v2, v8
	v_mul_f32_e32 v8, 0x3dd2d3e8, v6
	v_fma_mix_f32 v8, -v8, v106, s9 op_sel_hi:[0,1,0]
	v_mul_f32_e32 v8, v8, v6
	ds_write_b16 v150, v2 offset:1504
	v_cvt_f16_f32_e32 v2, v9
	v_exp_f32_e32 v8, v8
	ds_write_b16 v150, v2 offset:1648
	v_cvt_f16_f32_e32 v2, v10
	s_waitcnt vmcnt(21)
	v_cvt_f32_f16_e32 v10, v110
	v_add_f32_e32 v8, 1.0, v8
	v_rcp_f32_e32 v8, v8
	ds_write_b16 v150, v2 offset:2368
	v_cvt_f16_f32_e32 v2, v11
	v_mul_f32_e32 v9, 0xbfb8aa3b, v10
	v_exp_f32_e32 v9, v9
	v_cvt_f32_f16_sdwa v11, v110 dst_sel:DWORD dst_unused:UNUSED_PAD src0_sel:WORD_1
	ds_write_b16 v150, v2 offset:2512
	v_cvt_f16_f32_e32 v2, v12
	v_add_f32_e32 v9, 1.0, v9
	v_rcp_f32_e32 v12, v9
	v_mul_f32_e32 v9, 0x3dd2d3e8, v7
	ds_write_b16 v150, v2 offset:2656
	v_cvt_f16_f32_e32 v2, v13
	v_fma_mix_f32 v9, -v9, v106, s9 op_sel:[0,1,0] op_sel_hi:[0,1,0]
	v_mul_f32_e32 v9, v9, v7
	v_exp_f32_e32 v9, v9
	ds_write_b16 v150, v2 offset:2800
	v_cvt_f16_f32_e32 v2, v14
	v_or_b32_e32 v106, 8, v167
	v_add_f32_e32 v9, 1.0, v9
	v_rcp_f32_e32 v9, v9
	ds_write_b16 v150, v2 offset:3520
	v_cvt_f16_f32_e32 v2, v15
	v_pk_mul_f32 v[6:7], v[8:9], v[6:7]
	ds_write_b16 v150, v2 offset:3664
	v_cvt_f16_f32_e32 v2, v16
	ds_write_b16 v150, v2 offset:3808
	v_cvt_f16_f32_e32 v2, v17
	ds_write_b16 v150, v2 offset:3952
	v_mul_u32_u24_e32 v2, 0x90, v167
	s_waitcnt lgkmcnt(0)
; #define LAS __attribute__((address_space(3)))
; #define GAS __attribute__((address_space(1)))
; __device__ __forceinline__ float siluf(float x) { return x * __builtin_amdgcn_rcpf(1.f + __builtin_amdgcn_exp2f(-1.4426950408889634f * x)); }
; __device__ __forceinline__ float geluf(float x) { return x * __builtin_amdgcn_rcpf(1.f + __builtin_amdgcn_exp2f(x * (-0.10294324f * x * x - 2.3022082f))); }
; __device__ __forceinline__ unsigned cvtpk_h(float lo, float hi) { f32x2 v = {lo, hi}; h16x2 b = __builtin_convertvector(v, h16x2); return __builtin_bit_cast(unsigned, b); }
; __device__ __forceinline__ void gmlp_unit(unsigned char* ws, h16* Y, const h16* Ws16  , const float* bs  , size_t r0, LAS unsigned char* lds, int tid) {
;     ...
;         for (int ps = 0; ps < 4; ++ps) { const int row = 8 * ps + erow;
;             const h16x8 sv = *(const LAS h16x8*)(scr + row * 72 + 8 * ech);
;             float y[8];
; #pragma unroll
;             for (int k = 0; k < 8; ++k) y[k] = geluf((float)gu[q][ps][k]) * ((float)sv[k] + bias[q][ps]) * siluf((float)sz[q][ps][k]);
;             u32x4 w0; w0.x = cvtpk_h(y[0], y[1]); w0.y = cvtpk_h(y[2], y[3]); w0.z = cvtpk_h(y[4], y[5]); w0.w = cvtpk_h(y[6], y[7]);
;             *(GAS u32x4*)(Y + (r0 + 32 * (2 * ph + q) + row) * D + g * 64 + 8 * ech) = w0; }
	v_add3_u32 v0, s8, v0, v2
	ds_read_b128 v[2:5], v0
	s_waitcnt lgkmcnt(0)
	v_cvt_f32_f16_e32 v8, v2
	v_cvt_f32_f16_sdwa v9, v2 dst_sel:DWORD dst_unused:UNUSED_PAD src0_sel:WORD_1
	v_mul_f32_e32 v2, 0xbfb8aa3b, v11
	v_exp_f32_e32 v2, v2
	v_pk_add_f32 v[8:9], v[180:181], v[8:9] op_sel_hi:[0,1]
	v_pk_mul_f32 v[6:7], v[6:7], v[8:9]
	v_add_f32_e32 v2, 1.0, v2
	v_rcp_f32_e32 v13, v2
	s_nop 0
	v_pk_mul_f32 v[8:9], v[12:13], v[10:11]
	s_nop 0
	v_pk_mul_f32 v[6:7], v[8:9], v[6:7]
	v_cvt_f32_f16_e32 v8, v107
	v_cvt_f32_f16_sdwa v9, v107 dst_sel:DWORD dst_unused:UNUSED_PAD src0_sel:WORD_1
	v_cvt_f32_f16_e32 v12, v111
	v_cvt_f32_f16_sdwa v13, v111 dst_sel:DWORD dst_unused:UNUSED_PAD src0_sel:WORD_1
	v_mul_f32_e32 v2, 0x3dd2d3e8, v8
	v_mul_f32_e32 v11, 0x3dd2d3e8, v9
	v_fma_mix_f32 v2, -v2, v107, s9 op_sel_hi:[0,1,0]
	v_fma_mix_f32 v11, -v11, v107, s9 op_sel:[0,1,0] op_sel_hi:[0,1,0]
	v_mul_f32_e32 v2, v2, v8
	v_mul_f32_e32 v11, v11, v9
	v_exp_f32_e32 v2, v2
	v_exp_f32_e32 v11, v11
	v_add_f32_e32 v2, 1.0, v2
	v_add_f32_e32 v11, 1.0, v11
	v_rcp_f32_e32 v10, v2
	v_rcp_f32_e32 v11, v11
	v_mul_f32_e32 v2, 0xbfb8aa3b, v12
	v_exp_f32_e32 v2, v2
	v_pk_mul_f32 v[8:9], v[10:11], v[8:9]
	v_cvt_f32_f16_e32 v10, v3
	v_cvt_f32_f16_sdwa v11, v3 dst_sel:DWORD dst_unused:UNUSED_PAD src0_sel:WORD_1
	v_mul_f32_e32 v3, 0xbfb8aa3b, v13
	v_exp_f32_e32 v3, v3
	v_add_f32_e32 v2, 1.0, v2
	v_rcp_f32_e32 v2, v2
	v_pk_add_f32 v[10:11], v[180:181], v[10:11] op_sel_hi:[0,1]
	v_add_f32_e32 v3, 1.0, v3
	v_rcp_f32_e32 v3, v3
	v_pk_mul_f32 v[8:9], v[8:9], v[10:11]
	v_pk_mul_f32 v[2:3], v[2:3], v[12:13]
	v_cvt_f32_f16_e32 v12, v112
	v_pk_mul_f32 v[8:9], v[2:3], v[8:9]
	v_cvt_f32_f16_e32 v2, v108
	v_cvt_f32_f16_sdwa v3, v108 dst_sel:DWORD dst_unused:UNUSED_PAD src0_sel:WORD_1
	v_mul_f32_e32 v11, 0xbfb8aa3b, v12
	v_exp_f32_e32 v11, v11
	v_mul_f32_e32 v10, 0x3dd2d3e8, v2
	v_fma_mix_f32 v10, -v10, v108, s9 op_sel_hi:[0,1,0]
	v_mul_f32_e32 v10, v10, v2
	v_add_f32_e32 v11, 1.0, v11
	v_rcp_f32_e32 v14, v11
	v_mul_f32_e32 v11, 0x3dd2d3e8, v3
	v_fma_mix_f32 v11, -v11, v108, s9 op_sel:[0,1,0] op_sel_hi:[0,1,0]
	v_mul_f32_e32 v11, v11, v3
	v_exp_f32_e32 v10, v10
	v_exp_f32_e32 v11, v11
	v_cvt_f32_f16_sdwa v13, v112 dst_sel:DWORD dst_unused:UNUSED_PAD src0_sel:WORD_1
	v_add_f32_e32 v10, 1.0, v10
	v_add_f32_e32 v11, 1.0, v11
	v_rcp_f32_e32 v10, v10
	v_rcp_f32_e32 v11, v11
	s_nop 0
	v_pk_mul_f32 v[2:3], v[10:11], v[2:3]
	v_cvt_f32_f16_e32 v10, v4
	v_cvt_f32_f16_sdwa v11, v4 dst_sel:DWORD dst_unused:UNUSED_PAD src0_sel:WORD_1
	v_mul_f32_e32 v4, 0xbfb8aa3b, v13
	v_exp_f32_e32 v4, v4
	v_pk_add_f32 v[10:11], v[180:181], v[10:11] op_sel_hi:[0,1]
	v_pk_mul_f32 v[2:3], v[2:3], v[10:11]
	v_add_f32_e32 v4, 1.0, v4
	v_rcp_f32_e32 v15, v4
	s_nop 0
	v_pk_mul_f32 v[10:11], v[14:15], v[12:13]
	s_nop 0
	v_pk_mul_f32 v[10:11], v[10:11], v[2:3]
	v_cvt_f32_f16_e32 v2, v109
	v_cvt_f32_f16_sdwa v3, v109 dst_sel:DWORD dst_unused:UNUSED_PAD src0_sel:WORD_1
	v_cvt_f32_f16_e32 v14, v113
	v_cvt_f32_f16_sdwa v15, v113 dst_sel:DWORD dst_unused:UNUSED_PAD src0_sel:WORD_1
	v_mul_f32_e32 v4, 0x3dd2d3e8, v2
	v_mul_f32_e32 v13, 0x3dd2d3e8, v3
	v_fma_mix_f32 v4, -v4, v109, s9 op_sel_hi:[0,1,0]
	v_fma_mix_f32 v13, -v13, v109, s9 op_sel:[0,1,0] op_sel_hi:[0,1,0]
	v_mul_f32_e32 v4, v4, v2
	v_mul_f32_e32 v13, v13, v3
	v_exp_f32_e32 v4, v4
	v_exp_f32_e32 v13, v13
	v_add_f32_e32 v4, 1.0, v4
	v_add_f32_e32 v13, 1.0, v13
	v_rcp_f32_e32 v12, v4
	v_rcp_f32_e32 v13, v13
	v_mul_f32_e32 v4, 0xbfb8aa3b, v14
	v_exp_f32_e32 v4, v4
	v_pk_mul_f32 v[2:3], v[12:13], v[2:3]
	v_cvt_f32_f16_e32 v12, v5
	v_cvt_f32_f16_sdwa v13, v5 dst_sel:DWORD dst_unused:UNUSED_PAD src0_sel:WORD_1
	v_mul_f32_e32 v5, 0xbfb8aa3b, v15
	v_exp_f32_e32 v5, v5
	v_add_f32_e32 v4, 1.0, v4
	v_rcp_f32_e32 v4, v4
	v_pk_add_f32 v[12:13], v[180:181], v[12:13] op_sel_hi:[0,1]
	v_add_f32_e32 v5, 1.0, v5
	v_rcp_f32_e32 v5, v5
	v_pk_mul_f32 v[2:3], v[2:3], v[12:13]
	v_pk_mul_f32 v[4:5], v[4:5], v[14:15]
	s_nop 0
	v_pk_mul_f32 v[12:13], v[4:5], v[2:3]
	v_cvt_pk_f16_f32 v4, v10, v11
	s_waitcnt vmcnt(18)
	v_cvt_f32_f16_e32 v10, v102
	v_cvt_pk_f16_f32 v2, v6, v7
	v_cvt_pk_f16_f32 v3, v8, v9
	v_lshlrev_b64 v[6:7], 11, v[164:165]
	v_mul_f32_e32 v9, 0xbfb8aa3b, v10
	v_cvt_pk_f16_f32 v5, v12, v13
	v_lshl_add_u64 v[6:7], v[148:149], 0, v[6:7]
	v_exp_f32_e32 v9, v9
	global_store_dwordx4 v[6:7], v[2:5], off
	v_cvt_f32_f16_e32 v6, v98
	v_cvt_f32_f16_sdwa v7, v98 dst_sel:DWORD dst_unused:UNUSED_PAD src0_sel:WORD_1
	v_add_f32_e32 v9, 1.0, v9
	v_rcp_f32_e32 v12, v9
	v_mul_f32_e32 v8, 0x3dd2d3e8, v6
	v_mul_f32_e32 v9, 0x3dd2d3e8, v7
	v_fma_mix_f32 v8, -v8, v98, s9 op_sel_hi:[0,1,0]
	v_fma_mix_f32 v9, -v9, v98, s9 op_sel:[0,1,0] op_sel_hi:[0,1,0]
	v_mul_f32_e32 v8, v8, v6
	v_mul_f32_e32 v9, v9, v7
	v_exp_f32_e32 v8, v8
	v_exp_f32_e32 v9, v9
	ds_read_b128 v[2:5], v0 offset:1152
	v_cvt_f32_f16_sdwa v11, v102 dst_sel:DWORD dst_unused:UNUSED_PAD src0_sel:WORD_1
	v_add_f32_e32 v8, 1.0, v8
	v_add_f32_e32 v9, 1.0, v9
	v_rcp_f32_e32 v8, v8
	v_rcp_f32_e32 v9, v9
	v_or_b32_e32 v164, s4, v106
	v_or_b32_e32 v98, 16, v167
	v_pk_mul_f32 v[6:7], v[8:9], v[6:7]
	s_waitcnt lgkmcnt(0)
; #define LAS __attribute__((address_space(3)))
; #define GAS __attribute__((address_space(1)))
; __device__ __forceinline__ float siluf(float x) { return x * __builtin_amdgcn_rcpf(1.f + __builtin_amdgcn_exp2f(-1.4426950408889634f * x)); }
; __device__ __forceinline__ float geluf(float x) { return x * __builtin_amdgcn_rcpf(1.f + __builtin_amdgcn_exp2f(x * (-0.10294324f * x * x - 2.3022082f))); }
; __device__ __forceinline__ unsigned cvtpk_h(float lo, float hi) { f32x2 v = {lo, hi}; h16x2 b = __builtin_convertvector(v, h16x2); return __builtin_bit_cast(unsigned, b); }
; __device__ __forceinline__ void gmlp_unit(unsigned char* ws, h16* Y, const h16* Ws16  , const float* bs  , size_t r0, LAS unsigned char* lds, int tid) {
;     ...
;         for (int ps = 0; ps < 4; ++ps) { const int row = 8 * ps + erow;
;             const h16x8 sv = *(const LAS h16x8*)(scr + row * 72 + 8 * ech);
;             float y[8];
; #pragma unroll
;             for (int k = 0; k < 8; ++k) y[k] = geluf((float)gu[q][ps][k]) * ((float)sv[k] + bias[q][ps]) * siluf((float)sz[q][ps][k]);
;             u32x4 w0; w0.x = cvtpk_h(y[0], y[1]); w0.y = cvtpk_h(y[2], y[3]); w0.z = cvtpk_h(y[4], y[5]); w0.w = cvtpk_h(y[6], y[7]);
;             *(GAS u32x4*)(Y + (r0 + 32 * (2 * ph + q) + row) * D + g * 64 + 8 * ech) = w0; }
	v_cvt_f32_f16_e32 v8, v2
	v_cvt_f32_f16_sdwa v9, v2 dst_sel:DWORD dst_unused:UNUSED_PAD src0_sel:WORD_1
	v_mul_f32_e32 v2, 0xbfb8aa3b, v11
	v_exp_f32_e32 v2, v2
	v_pk_add_f32 v[8:9], v[178:179], v[8:9] op_sel_hi:[0,1]
	v_pk_mul_f32 v[6:7], v[6:7], v[8:9]
	v_add_f32_e32 v2, 1.0, v2
	v_rcp_f32_e32 v13, v2
	s_nop 0
	v_pk_mul_f32 v[8:9], v[12:13], v[10:11]
	s_nop 0
	v_pk_mul_f32 v[6:7], v[8:9], v[6:7]
	v_cvt_f32_f16_e32 v8, v99
	v_cvt_f32_f16_sdwa v9, v99 dst_sel:DWORD dst_unused:UNUSED_PAD src0_sel:WORD_1
	v_cvt_f32_f16_e32 v12, v103
	v_cvt_f32_f16_sdwa v13, v103 dst_sel:DWORD dst_unused:UNUSED_PAD src0_sel:WORD_1
	v_mul_f32_e32 v2, 0x3dd2d3e8, v8
	v_mul_f32_e32 v11, 0x3dd2d3e8, v9
	v_fma_mix_f32 v2, -v2, v99, s9 op_sel_hi:[0,1,0]
	v_fma_mix_f32 v11, -v11, v99, s9 op_sel:[0,1,0] op_sel_hi:[0,1,0]
	v_mul_f32_e32 v2, v2, v8
	v_mul_f32_e32 v11, v11, v9
	v_exp_f32_e32 v2, v2
	v_exp_f32_e32 v11, v11
	v_add_f32_e32 v2, 1.0, v2
	v_add_f32_e32 v11, 1.0, v11
	v_rcp_f32_e32 v10, v2
	v_rcp_f32_e32 v11, v11
	v_mul_f32_e32 v2, 0xbfb8aa3b, v12
	v_exp_f32_e32 v2, v2
	v_pk_mul_f32 v[8:9], v[10:11], v[8:9]
	v_cvt_f32_f16_e32 v10, v3
	v_cvt_f32_f16_sdwa v11, v3 dst_sel:DWORD dst_unused:UNUSED_PAD src0_sel:WORD_1
	v_mul_f32_e32 v3, 0xbfb8aa3b, v13
	v_exp_f32_e32 v3, v3
	v_add_f32_e32 v2, 1.0, v2
	v_rcp_f32_e32 v2, v2
	v_pk_add_f32 v[10:11], v[178:179], v[10:11] op_sel_hi:[0,1]
	v_add_f32_e32 v3, 1.0, v3
	v_rcp_f32_e32 v3, v3
	v_pk_mul_f32 v[8:9], v[8:9], v[10:11]
	v_pk_mul_f32 v[2:3], v[2:3], v[12:13]
	v_cvt_f32_f16_e32 v12, v104
	v_pk_mul_f32 v[2:3], v[2:3], v[8:9]
	v_cvt_f32_f16_e32 v8, v100
	v_cvt_f32_f16_sdwa v9, v100 dst_sel:DWORD dst_unused:UNUSED_PAD src0_sel:WORD_1
	v_mul_f32_e32 v11, 0xbfb8aa3b, v12
	v_exp_f32_e32 v11, v11
	v_mul_f32_e32 v10, 0x3dd2d3e8, v8
	v_fma_mix_f32 v10, -v10, v100, s9 op_sel_hi:[0,1,0]
	v_mul_f32_e32 v10, v10, v8
	v_add_f32_e32 v11, 1.0, v11
	v_rcp_f32_e32 v14, v11
	v_mul_f32_e32 v11, 0x3dd2d3e8, v9
	v_fma_mix_f32 v11, -v11, v100, s9 op_sel:[0,1,0] op_sel_hi:[0,1,0]
	v_mul_f32_e32 v11, v11, v9
	v_exp_f32_e32 v10, v10
	v_exp_f32_e32 v11, v11
	v_cvt_f32_f16_sdwa v13, v104 dst_sel:DWORD dst_unused:UNUSED_PAD src0_sel:WORD_1
	v_add_f32_e32 v10, 1.0, v10
	v_add_f32_e32 v11, 1.0, v11
	v_rcp_f32_e32 v10, v10
	v_rcp_f32_e32 v11, v11
	s_nop 0
	v_pk_mul_f32 v[8:9], v[10:11], v[8:9]
	v_cvt_f32_f16_e32 v10, v4
	v_cvt_f32_f16_sdwa v11, v4 dst_sel:DWORD dst_unused:UNUSED_PAD src0_sel:WORD_1
	v_mul_f32_e32 v4, 0xbfb8aa3b, v13
	v_exp_f32_e32 v4, v4
	v_pk_add_f32 v[10:11], v[178:179], v[10:11] op_sel_hi:[0,1]
	v_pk_mul_f32 v[8:9], v[8:9], v[10:11]
	v_add_f32_e32 v4, 1.0, v4
	v_rcp_f32_e32 v15, v4
	s_nop 0
	v_pk_mul_f32 v[10:11], v[14:15], v[12:13]
	s_nop 0
	v_pk_mul_f32 v[8:9], v[10:11], v[8:9]
	v_cvt_f32_f16_e32 v10, v101
	v_cvt_f32_f16_sdwa v11, v101 dst_sel:DWORD dst_unused:UNUSED_PAD src0_sel:WORD_1
	v_cvt_f32_f16_e32 v14, v105
	v_cvt_f32_f16_sdwa v15, v105 dst_sel:DWORD dst_unused:UNUSED_PAD src0_sel:WORD_1
	v_mul_f32_e32 v4, 0x3dd2d3e8, v10
	v_mul_f32_e32 v13, 0x3dd2d3e8, v11
	v_fma_mix_f32 v4, -v4, v101, s9 op_sel_hi:[0,1,0]
	v_fma_mix_f32 v13, -v13, v101, s9 op_sel:[0,1,0] op_sel_hi:[0,1,0]
	v_mul_f32_e32 v4, v4, v10
	v_mul_f32_e32 v13, v13, v11
	v_exp_f32_e32 v4, v4
	v_exp_f32_e32 v13, v13
	v_add_f32_e32 v4, 1.0, v4
	v_add_f32_e32 v13, 1.0, v13
	v_rcp_f32_e32 v12, v4
	v_rcp_f32_e32 v13, v13
	v_mul_f32_e32 v4, 0xbfb8aa3b, v14
	v_exp_f32_e32 v4, v4
	v_pk_mul_f32 v[10:11], v[12:13], v[10:11]
	v_cvt_f32_f16_e32 v12, v5
	v_cvt_f32_f16_sdwa v13, v5 dst_sel:DWORD dst_unused:UNUSED_PAD src0_sel:WORD_1
	v_mul_f32_e32 v5, 0xbfb8aa3b, v15
	v_exp_f32_e32 v5, v5
	v_add_f32_e32 v4, 1.0, v4
	v_rcp_f32_e32 v4, v4
	v_pk_add_f32 v[12:13], v[178:179], v[12:13] op_sel_hi:[0,1]
	v_add_f32_e32 v5, 1.0, v5
	v_rcp_f32_e32 v5, v5
	v_pk_mul_f32 v[10:11], v[10:11], v[12:13]
	v_pk_mul_f32 v[4:5], v[4:5], v[14:15]
	s_nop 0
	v_pk_mul_f32 v[10:11], v[4:5], v[10:11]
	v_cvt_pk_f16_f32 v4, v6, v7
	v_cvt_pk_f16_f32 v7, v10, v11
	s_waitcnt vmcnt(16)
	v_cvt_f32_f16_e32 v10, v94
	v_cvt_pk_f16_f32 v5, v2, v3
	v_cvt_pk_f16_f32 v6, v8, v9
	v_lshlrev_b64 v[2:3], 11, v[164:165]
	v_mul_f32_e32 v9, 0xbfb8aa3b, v10
	v_lshl_add_u64 v[2:3], v[148:149], 0, v[2:3]
	v_exp_f32_e32 v9, v9
	global_store_dwordx4 v[2:3], v[4:7], off
	ds_read_b128 v[2:5], v0 offset:2304
	v_cvt_f32_f16_sdwa v11, v94 dst_sel:DWORD dst_unused:UNUSED_PAD src0_sel:WORD_1
	v_cvt_f32_f16_e32 v6, v90
	v_cvt_f32_f16_sdwa v7, v90 dst_sel:DWORD dst_unused:UNUSED_PAD src0_sel:WORD_1
	v_add_f32_e32 v9, 1.0, v9
	v_rcp_f32_e32 v12, v9
	v_mul_f32_e32 v8, 0x3dd2d3e8, v6
	v_mul_f32_e32 v9, 0x3dd2d3e8, v7
	v_fma_mix_f32 v8, -v8, v90, s9 op_sel_hi:[0,1,0]
	v_fma_mix_f32 v9, -v9, v90, s9 op_sel:[0,1,0] op_sel_hi:[0,1,0]
	v_mul_f32_e32 v8, v8, v6
	v_mul_f32_e32 v9, v9, v7
	v_exp_f32_e32 v8, v8
	v_exp_f32_e32 v9, v9
	v_or_b32_e32 v164, s4, v98
	v_or_b32_e32 v90, 24, v167
	v_add_f32_e32 v8, 1.0, v8
	v_add_f32_e32 v9, 1.0, v9
	v_rcp_f32_e32 v8, v8
	v_rcp_f32_e32 v9, v9
	s_nop 0
	v_pk_mul_f32 v[6:7], v[8:9], v[6:7]
	s_waitcnt lgkmcnt(0)
; #define LAS __attribute__((address_space(3)))
; #define GAS __attribute__((address_space(1)))
; __device__ __forceinline__ float siluf(float x) { return x * __builtin_amdgcn_rcpf(1.f + __builtin_amdgcn_exp2f(-1.4426950408889634f * x)); }
; __device__ __forceinline__ float geluf(float x) { return x * __builtin_amdgcn_rcpf(1.f + __builtin_amdgcn_exp2f(x * (-0.10294324f * x * x - 2.3022082f))); }
; __device__ __forceinline__ unsigned cvtpk_h(float lo, float hi) { f32x2 v = {lo, hi}; h16x2 b = __builtin_convertvector(v, h16x2); return __builtin_bit_cast(unsigned, b); }
; __device__ __forceinline__ void gmlp_unit(unsigned char* ws, h16* Y, const h16* Ws16  , const float* bs  , size_t r0, LAS unsigned char* lds, int tid) {
;     ...
;         for (int ps = 0; ps < 4; ++ps) { const int row = 8 * ps + erow;
;             const h16x8 sv = *(const LAS h16x8*)(scr + row * 72 + 8 * ech);
;             float y[8];
; #pragma unroll
;             for (int k = 0; k < 8; ++k) y[k] = geluf((float)gu[q][ps][k]) * ((float)sv[k] + bias[q][ps]) * siluf((float)sz[q][ps][k]);
;             u32x4 w0; w0.x = cvtpk_h(y[0], y[1]); w0.y = cvtpk_h(y[2], y[3]); w0.z = cvtpk_h(y[4], y[5]); w0.w = cvtpk_h(y[6], y[7]);
;             *(GAS u32x4*)(Y + (r0 + 32 * (2 * ph + q) + row) * D + g * 64 + 8 * ech) = w0; }
	v_cvt_f32_f16_e32 v8, v2
	v_cvt_f32_f16_sdwa v9, v2 dst_sel:DWORD dst_unused:UNUSED_PAD src0_sel:WORD_1
	v_mul_f32_e32 v2, 0xbfb8aa3b, v11
	v_exp_f32_e32 v2, v2
	v_pk_add_f32 v[8:9], v[176:177], v[8:9] op_sel_hi:[0,1]
	v_pk_mul_f32 v[6:7], v[6:7], v[8:9]
	v_add_f32_e32 v2, 1.0, v2
	v_rcp_f32_e32 v13, v2
	s_nop 0
	v_pk_mul_f32 v[8:9], v[12:13], v[10:11]
	s_nop 0
	v_pk_mul_f32 v[6:7], v[8:9], v[6:7]
	v_cvt_f32_f16_e32 v8, v91
	v_cvt_f32_f16_sdwa v9, v91 dst_sel:DWORD dst_unused:UNUSED_PAD src0_sel:WORD_1
	v_cvt_f32_f16_e32 v12, v95
	v_cvt_f32_f16_sdwa v13, v95 dst_sel:DWORD dst_unused:UNUSED_PAD src0_sel:WORD_1
	v_mul_f32_e32 v2, 0x3dd2d3e8, v8
	v_mul_f32_e32 v11, 0x3dd2d3e8, v9
	v_fma_mix_f32 v2, -v2, v91, s9 op_sel_hi:[0,1,0]
	v_fma_mix_f32 v11, -v11, v91, s9 op_sel:[0,1,0] op_sel_hi:[0,1,0]
	v_mul_f32_e32 v2, v2, v8
	v_mul_f32_e32 v11, v11, v9
	v_exp_f32_e32 v2, v2
	v_exp_f32_e32 v11, v11
	v_add_f32_e32 v2, 1.0, v2
	v_add_f32_e32 v11, 1.0, v11
	v_rcp_f32_e32 v10, v2
	v_rcp_f32_e32 v11, v11
	v_mul_f32_e32 v2, 0xbfb8aa3b, v12
	v_exp_f32_e32 v2, v2
	v_pk_mul_f32 v[8:9], v[10:11], v[8:9]
	v_cvt_f32_f16_e32 v10, v3
	v_cvt_f32_f16_sdwa v11, v3 dst_sel:DWORD dst_unused:UNUSED_PAD src0_sel:WORD_1
	v_mul_f32_e32 v3, 0xbfb8aa3b, v13
	v_exp_f32_e32 v3, v3
	v_add_f32_e32 v2, 1.0, v2
	v_rcp_f32_e32 v2, v2
	v_pk_add_f32 v[10:11], v[176:177], v[10:11] op_sel_hi:[0,1]
	v_add_f32_e32 v3, 1.0, v3
	v_rcp_f32_e32 v3, v3
	v_pk_mul_f32 v[8:9], v[8:9], v[10:11]
	v_pk_mul_f32 v[2:3], v[2:3], v[12:13]
	v_cvt_f32_f16_e32 v12, v96
	v_pk_mul_f32 v[8:9], v[2:3], v[8:9]
	v_cvt_f32_f16_e32 v2, v92
	v_cvt_f32_f16_sdwa v3, v92 dst_sel:DWORD dst_unused:UNUSED_PAD src0_sel:WORD_1
	v_mul_f32_e32 v11, 0xbfb8aa3b, v12
	v_exp_f32_e32 v11, v11
	v_mul_f32_e32 v10, 0x3dd2d3e8, v2
	v_fma_mix_f32 v10, -v10, v92, s9 op_sel_hi:[0,1,0]
	v_mul_f32_e32 v10, v10, v2
	v_add_f32_e32 v11, 1.0, v11
	v_rcp_f32_e32 v14, v11
	v_mul_f32_e32 v11, 0x3dd2d3e8, v3
	v_fma_mix_f32 v11, -v11, v92, s9 op_sel:[0,1,0] op_sel_hi:[0,1,0]
	v_mul_f32_e32 v11, v11, v3
	v_exp_f32_e32 v10, v10
	v_exp_f32_e32 v11, v11
	v_cvt_f32_f16_sdwa v13, v96 dst_sel:DWORD dst_unused:UNUSED_PAD src0_sel:WORD_1
	v_add_f32_e32 v10, 1.0, v10
	v_add_f32_e32 v11, 1.0, v11
	v_rcp_f32_e32 v10, v10
	v_rcp_f32_e32 v11, v11
	s_nop 0
	v_pk_mul_f32 v[2:3], v[10:11], v[2:3]
	v_cvt_f32_f16_e32 v10, v4
	v_cvt_f32_f16_sdwa v11, v4 dst_sel:DWORD dst_unused:UNUSED_PAD src0_sel:WORD_1
	v_mul_f32_e32 v4, 0xbfb8aa3b, v13
	v_exp_f32_e32 v4, v4
	v_pk_add_f32 v[10:11], v[176:177], v[10:11] op_sel_hi:[0,1]
	v_pk_mul_f32 v[2:3], v[2:3], v[10:11]
	v_add_f32_e32 v4, 1.0, v4
	v_rcp_f32_e32 v15, v4
	s_nop 0
	v_pk_mul_f32 v[10:11], v[14:15], v[12:13]
	s_nop 0
	v_pk_mul_f32 v[10:11], v[10:11], v[2:3]
	v_cvt_f32_f16_e32 v2, v93
	v_cvt_f32_f16_sdwa v3, v93 dst_sel:DWORD dst_unused:UNUSED_PAD src0_sel:WORD_1
	v_cvt_f32_f16_e32 v14, v97
	v_cvt_f32_f16_sdwa v15, v97 dst_sel:DWORD dst_unused:UNUSED_PAD src0_sel:WORD_1
	v_mul_f32_e32 v4, 0x3dd2d3e8, v2
	v_mul_f32_e32 v13, 0x3dd2d3e8, v3
	v_fma_mix_f32 v4, -v4, v93, s9 op_sel_hi:[0,1,0]
	v_fma_mix_f32 v13, -v13, v93, s9 op_sel:[0,1,0] op_sel_hi:[0,1,0]
	v_mul_f32_e32 v4, v4, v2
	v_mul_f32_e32 v13, v13, v3
	v_exp_f32_e32 v4, v4
	v_exp_f32_e32 v13, v13
	v_add_f32_e32 v4, 1.0, v4
	v_add_f32_e32 v13, 1.0, v13
	v_rcp_f32_e32 v12, v4
	v_rcp_f32_e32 v13, v13
	v_mul_f32_e32 v4, 0xbfb8aa3b, v14
	v_exp_f32_e32 v4, v4
	v_pk_mul_f32 v[2:3], v[12:13], v[2:3]
	v_cvt_f32_f16_e32 v12, v5
	v_cvt_f32_f16_sdwa v13, v5 dst_sel:DWORD dst_unused:UNUSED_PAD src0_sel:WORD_1
	v_mul_f32_e32 v5, 0xbfb8aa3b, v15
	v_exp_f32_e32 v5, v5
	v_add_f32_e32 v4, 1.0, v4
	v_rcp_f32_e32 v4, v4
	v_pk_add_f32 v[12:13], v[176:177], v[12:13] op_sel_hi:[0,1]
	v_add_f32_e32 v5, 1.0, v5
	v_rcp_f32_e32 v5, v5
	v_pk_mul_f32 v[2:3], v[2:3], v[12:13]
	v_pk_mul_f32 v[4:5], v[4:5], v[14:15]
	s_nop 0
	v_pk_mul_f32 v[12:13], v[4:5], v[2:3]
	v_cvt_pk_f16_f32 v4, v10, v11
	s_waitcnt vmcnt(14)
	v_cvt_f32_f16_e32 v10, v86
	v_cvt_pk_f16_f32 v2, v6, v7
	v_cvt_pk_f16_f32 v3, v8, v9
	v_lshlrev_b64 v[6:7], 11, v[164:165]
	v_mul_f32_e32 v9, 0xbfb8aa3b, v10
	v_cvt_pk_f16_f32 v5, v12, v13
	v_lshl_add_u64 v[6:7], v[148:149], 0, v[6:7]
	v_exp_f32_e32 v9, v9
	global_store_dwordx4 v[6:7], v[2:5], off
	v_cvt_f32_f16_e32 v6, v82
	v_cvt_f32_f16_sdwa v7, v82 dst_sel:DWORD dst_unused:UNUSED_PAD src0_sel:WORD_1
	v_add_f32_e32 v9, 1.0, v9
	v_rcp_f32_e32 v12, v9
	v_mul_f32_e32 v8, 0x3dd2d3e8, v6
	v_mul_f32_e32 v9, 0x3dd2d3e8, v7
	v_fma_mix_f32 v8, -v8, v82, s9 op_sel_hi:[0,1,0]
	v_fma_mix_f32 v9, -v9, v82, s9 op_sel:[0,1,0] op_sel_hi:[0,1,0]
	v_mul_f32_e32 v8, v8, v6
	v_mul_f32_e32 v9, v9, v7
	v_exp_f32_e32 v8, v8
	v_exp_f32_e32 v9, v9
	ds_read_b128 v[2:5], v0 offset:3456
	v_cvt_f32_f16_sdwa v11, v86 dst_sel:DWORD dst_unused:UNUSED_PAD src0_sel:WORD_1
	v_add_f32_e32 v8, 1.0, v8
	v_add_f32_e32 v9, 1.0, v9
	v_rcp_f32_e32 v8, v8
	v_rcp_f32_e32 v9, v9
	v_or_b32_e32 v164, s4, v90
	v_pk_mul_f32 v[6:7], v[8:9], v[6:7]
	s_waitcnt lgkmcnt(0)
; #define LAS __attribute__((address_space(3)))
; #define GAS __attribute__((address_space(1)))
; __device__ __forceinline__ float siluf(float x) { return x * __builtin_amdgcn_rcpf(1.f + __builtin_amdgcn_exp2f(-1.4426950408889634f * x)); }
; __device__ __forceinline__ float geluf(float x) { return x * __builtin_amdgcn_rcpf(1.f + __builtin_amdgcn_exp2f(x * (-0.10294324f * x * x - 2.3022082f))); }
; __device__ __forceinline__ unsigned cvtpk_h(float lo, float hi) { f32x2 v = {lo, hi}; h16x2 b = __builtin_convertvector(v, h16x2); return __builtin_bit_cast(unsigned, b); }
; __device__ __forceinline__ void gmlp_unit(unsigned char* ws, h16* Y, const h16* Ws16  , const float* bs  , size_t r0, LAS unsigned char* lds, int tid) {
;     ...
;     for (int q = 0; q < 2; ++q) {
; #pragma unroll
;         for (int db = 0; db < 2; ++db) {
;             s16x8 bf[8];
; #pragma unroll
;             for (int ks = 0; ks < 8; ++ks) bf[ks] = tr_frag((LAS const char*)lds + g * 16384, 8192, db, ks, lane);
;             f32x16 acc = f32x16{};
; #pragma unroll
;             for (int ks = 0; ks < 8; ++ks) acc = __builtin_amdgcn_mfma_f32_32x32x16_f16(H8(af[q][ks]), H8(bf[ks]), acc, 0, 0, 0);
;     ...
;         for (int ps = 0; ps < 4; ++ps) { const int row = 8 * ps + erow;
;             const h16x8 sv = *(const LAS h16x8*)(scr + row * 72 + 8 * ech);
;             float y[8];
; #pragma unroll
;             for (int k = 0; k < 8; ++k) y[k] = geluf((float)gu[q][ps][k]) * ((float)sv[k] + bias[q][ps]) * siluf((float)sz[q][ps][k]);
;             u32x4 w0; w0.x = cvtpk_h(y[0], y[1]); w0.y = cvtpk_h(y[2], y[3]); w0.z = cvtpk_h(y[4], y[5]); w0.w = cvtpk_h(y[6], y[7]);
;             *(GAS u32x4*)(Y + (r0 + 32 * (2 * ph + q) + row) * D + g * 64 + 8 * ech) = w0; }
	v_cvt_f32_f16_e32 v8, v2
	v_cvt_f32_f16_sdwa v9, v2 dst_sel:DWORD dst_unused:UNUSED_PAD src0_sel:WORD_1
	v_mul_f32_e32 v2, 0xbfb8aa3b, v11
	v_exp_f32_e32 v2, v2
	v_pk_add_f32 v[8:9], v[174:175], v[8:9] op_sel_hi:[0,1]
	v_pk_mul_f32 v[6:7], v[6:7], v[8:9]
	v_add_f32_e32 v2, 1.0, v2
	v_rcp_f32_e32 v13, v2
	s_nop 0
	v_pk_mul_f32 v[8:9], v[12:13], v[10:11]
	s_nop 0
	v_pk_mul_f32 v[6:7], v[8:9], v[6:7]
	v_cvt_f32_f16_e32 v8, v83
	v_cvt_f32_f16_sdwa v9, v83 dst_sel:DWORD dst_unused:UNUSED_PAD src0_sel:WORD_1
	v_cvt_f32_f16_e32 v12, v87
	v_cvt_f32_f16_sdwa v13, v87 dst_sel:DWORD dst_unused:UNUSED_PAD src0_sel:WORD_1
	v_mul_f32_e32 v2, 0x3dd2d3e8, v8
	v_mul_f32_e32 v11, 0x3dd2d3e8, v9
	v_fma_mix_f32 v2, -v2, v83, s9 op_sel_hi:[0,1,0]
	v_fma_mix_f32 v11, -v11, v83, s9 op_sel:[0,1,0] op_sel_hi:[0,1,0]
	v_mul_f32_e32 v2, v2, v8
	v_mul_f32_e32 v11, v11, v9
	v_exp_f32_e32 v2, v2
	v_exp_f32_e32 v11, v11
	v_add_f32_e32 v2, 1.0, v2
	v_add_f32_e32 v11, 1.0, v11
	v_rcp_f32_e32 v10, v2
	v_rcp_f32_e32 v11, v11
	v_mul_f32_e32 v2, 0xbfb8aa3b, v12
	v_exp_f32_e32 v2, v2
	v_pk_mul_f32 v[8:9], v[10:11], v[8:9]
	v_cvt_f32_f16_e32 v10, v3
	v_cvt_f32_f16_sdwa v11, v3 dst_sel:DWORD dst_unused:UNUSED_PAD src0_sel:WORD_1
	v_mul_f32_e32 v3, 0xbfb8aa3b, v13
	v_exp_f32_e32 v3, v3
	v_add_f32_e32 v2, 1.0, v2
	v_rcp_f32_e32 v2, v2
	v_pk_add_f32 v[10:11], v[174:175], v[10:11] op_sel_hi:[0,1]
	v_add_f32_e32 v3, 1.0, v3
	v_rcp_f32_e32 v3, v3
	v_pk_mul_f32 v[8:9], v[8:9], v[10:11]
	v_pk_mul_f32 v[2:3], v[2:3], v[12:13]
	v_cvt_f32_f16_e32 v12, v88
	v_pk_mul_f32 v[2:3], v[2:3], v[8:9]
	v_cvt_f32_f16_e32 v8, v84
	v_cvt_f32_f16_sdwa v9, v84 dst_sel:DWORD dst_unused:UNUSED_PAD src0_sel:WORD_1
	v_mul_f32_e32 v11, 0xbfb8aa3b, v12
	v_exp_f32_e32 v11, v11
	v_mul_f32_e32 v10, 0x3dd2d3e8, v8
	v_fma_mix_f32 v10, -v10, v84, s9 op_sel_hi:[0,1,0]
	v_mul_f32_e32 v10, v10, v8
	v_add_f32_e32 v11, 1.0, v11
	v_rcp_f32_e32 v14, v11
	v_mul_f32_e32 v11, 0x3dd2d3e8, v9
	v_fma_mix_f32 v11, -v11, v84, s9 op_sel:[0,1,0] op_sel_hi:[0,1,0]
	v_mul_f32_e32 v11, v11, v9
	v_exp_f32_e32 v10, v10
	v_exp_f32_e32 v11, v11
	v_cvt_f32_f16_sdwa v13, v88 dst_sel:DWORD dst_unused:UNUSED_PAD src0_sel:WORD_1
	v_add_f32_e32 v10, 1.0, v10
	v_add_f32_e32 v11, 1.0, v11
	v_rcp_f32_e32 v10, v10
	v_rcp_f32_e32 v11, v11
	s_nop 0
	v_pk_mul_f32 v[8:9], v[10:11], v[8:9]
	v_cvt_f32_f16_e32 v10, v4
	v_cvt_f32_f16_sdwa v11, v4 dst_sel:DWORD dst_unused:UNUSED_PAD src0_sel:WORD_1
	v_mul_f32_e32 v4, 0xbfb8aa3b, v13
	v_exp_f32_e32 v4, v4
	v_pk_add_f32 v[10:11], v[174:175], v[10:11] op_sel_hi:[0,1]
	v_pk_mul_f32 v[8:9], v[8:9], v[10:11]
	v_add_f32_e32 v4, 1.0, v4
	v_rcp_f32_e32 v15, v4
	s_nop 0
	v_pk_mul_f32 v[10:11], v[14:15], v[12:13]
	s_nop 0
	v_pk_mul_f32 v[8:9], v[10:11], v[8:9]
	v_cvt_f32_f16_e32 v10, v85
	v_cvt_f32_f16_sdwa v11, v85 dst_sel:DWORD dst_unused:UNUSED_PAD src0_sel:WORD_1
	v_cvt_f32_f16_e32 v14, v89
	v_cvt_f32_f16_sdwa v15, v89 dst_sel:DWORD dst_unused:UNUSED_PAD src0_sel:WORD_1
	v_mul_f32_e32 v4, 0x3dd2d3e8, v10
	v_mul_f32_e32 v13, 0x3dd2d3e8, v11
	v_fma_mix_f32 v4, -v4, v85, s9 op_sel_hi:[0,1,0]
	v_fma_mix_f32 v13, -v13, v85, s9 op_sel:[0,1,0] op_sel_hi:[0,1,0]
	v_mul_f32_e32 v4, v4, v10
	v_mul_f32_e32 v13, v13, v11
	v_exp_f32_e32 v4, v4
	v_exp_f32_e32 v13, v13
	v_add_f32_e32 v4, 1.0, v4
	v_add_f32_e32 v13, 1.0, v13
	v_rcp_f32_e32 v12, v4
	v_rcp_f32_e32 v13, v13
	v_mul_f32_e32 v4, 0xbfb8aa3b, v14
	v_exp_f32_e32 v4, v4
	v_pk_mul_f32 v[10:11], v[12:13], v[10:11]
	v_cvt_f32_f16_e32 v12, v5
	v_cvt_f32_f16_sdwa v13, v5 dst_sel:DWORD dst_unused:UNUSED_PAD src0_sel:WORD_1
	v_mul_f32_e32 v5, 0xbfb8aa3b, v15
	v_exp_f32_e32 v5, v5
	v_add_f32_e32 v4, 1.0, v4
	v_rcp_f32_e32 v4, v4
	v_pk_add_f32 v[12:13], v[174:175], v[12:13] op_sel_hi:[0,1]
	v_add_f32_e32 v5, 1.0, v5
	v_rcp_f32_e32 v5, v5
	v_pk_mul_f32 v[10:11], v[10:11], v[12:13]
	v_pk_mul_f32 v[4:5], v[4:5], v[14:15]
	s_nop 0
	v_pk_mul_f32 v[10:11], v[4:5], v[10:11]
	v_cvt_pk_f16_f32 v5, v2, v3
	v_lshlrev_b64 v[2:3], 11, v[164:165]
	v_cvt_pk_f16_f32 v4, v6, v7
	v_cvt_pk_f16_f32 v6, v8, v9
	v_cvt_pk_f16_f32 v7, v10, v11
	v_lshl_add_u64 v[2:3], v[148:149], 0, v[2:3]
	global_store_dwordx4 v[2:3], v[4:7], off
	s_waitcnt lgkmcnt(0)
	ds_read_b64_tr_b16 v[2:3], v151
	ds_read_b64_tr_b16 v[4:5], v151 offset:256
	ds_read_b64_tr_b16 v[82:83], v151 offset:1024
	ds_read_b64_tr_b16 v[84:85], v151 offset:1280
	ds_read_b64_tr_b16 v[86:87], v151 offset:2048
	ds_read_b64_tr_b16 v[88:89], v151 offset:2304
	ds_read_b64_tr_b16 v[92:93], v151 offset:3072
	ds_read_b64_tr_b16 v[94:95], v151 offset:3328
	ds_read_b64_tr_b16 v[100:101], v151 offset:4096
	ds_read_b64_tr_b16 v[102:103], v151 offset:4352
	ds_read_b64_tr_b16 v[108:109], v151 offset:5120
	ds_read_b64_tr_b16 v[110:111], v151 offset:5376
	ds_read_b64_tr_b16 v[112:113], v151 offset:6144
	ds_read_b64_tr_b16 v[114:115], v151 offset:6400
	ds_read_b64_tr_b16 v[116:117], v151 offset:7168
	ds_read_b64_tr_b16 v[118:119], v151 offset:7424
	s_waitcnt lgkmcnt(14)
	v_mfma_f32_32x32x16_f16 v[2:17], v[78:81], v[2:5], 0
	v_or_b32_e32 v164, s2, v167
	s_waitcnt lgkmcnt(12)
	v_mfma_f32_32x32x16_f16 v[2:17], v[74:77], v[82:85], v[2:17]
	s_waitcnt lgkmcnt(10)
	v_mfma_f32_32x32x16_f16 v[2:17], v[70:73], v[86:89], v[2:17]
	s_waitcnt lgkmcnt(8)
	v_mfma_f32_32x32x16_f16 v[2:17], v[66:69], v[92:95], v[2:17]
	s_waitcnt lgkmcnt(6)
	v_mfma_f32_32x32x16_f16 v[2:17], v[62:65], v[100:103], v[2:17]
	s_waitcnt lgkmcnt(4)
	v_mfma_f32_32x32x16_f16 v[2:17], v[58:61], v[108:111], v[2:17]
	s_waitcnt lgkmcnt(2)
	v_mfma_f32_32x32x16_f16 v[2:17], v[54:57], v[112:115], v[2:17]
	s_waitcnt lgkmcnt(0)
; #define LAS __attribute__((address_space(3)))
; __device__ __forceinline__ float siluf(float x) { return x * __builtin_amdgcn_rcpf(1.f + __builtin_amdgcn_exp2f(-1.4426950408889634f * x)); }
; __device__ __forceinline__ float geluf(float x) { return x * __builtin_amdgcn_rcpf(1.f + __builtin_amdgcn_exp2f(x * (-0.10294324f * x * x - 2.3022082f))); }
; #define LDS_WAIT() asm volatile("s_waitcnt lgkmcnt(0)" ::: "memory")
; __device__ __forceinline__ int crow(int r, int hi) { return (r & 3) + 8 * (r >> 2) + 4 * hi; }
; __device__ __forceinline__ void gmlp_unit(unsigned char* ws, h16* Y, const h16* Ws16  , const float* bs  , size_t r0, LAS unsigned char* lds, int tid) {
;     ...
;     for (int q = 0; q < 2; ++q) {
; #pragma unroll
;         for (int db = 0; db < 2; ++db) {
;             s16x8 bf[8];
; #pragma unroll
;             for (int ks = 0; ks < 8; ++ks) bf[ks] = tr_frag((LAS const char*)lds + g * 16384, 8192, db, ks, lane);
;             f32x16 acc = f32x16{};
; #pragma unroll
;             for (int ks = 0; ks < 8; ++ks) acc = __builtin_amdgcn_mfma_f32_32x32x16_f16(H8(af[q][ks]), H8(bf[ks]), acc, 0, 0, 0);
; #pragma unroll
;             for (int r = 0; r < 16; ++r) scr[crow(r, hi) * 72 + 32 * db + r32] = (h16)acc[r];
;         }
;         LDS_WAIT();
; #pragma unroll
;         for (int ps = 0; ps < 4; ++ps) { const int row = 8 * ps + erow;
;             const h16x8 sv = *(const LAS h16x8*)(scr + row * 72 + 8 * ech);
;             float y[8];
; #pragma unroll
;             for (int k = 0; k < 8; ++k) y[k] = geluf((float)gu[q][ps][k]) * ((float)sv[k] + bias[q][ps]) * siluf((float)sz[q][ps][k]);
	v_mfma_f32_32x32x16_f16 v[2:17], v[50:53], v[116:119], v[2:17]
	s_nop 11
	v_cvt_f16_f32_e32 v2, v2
	ds_write_b16 v150, v2
	v_cvt_f16_f32_e32 v2, v3
	ds_write_b16 v150, v2 offset:144
	v_cvt_f16_f32_e32 v2, v4
	ds_write_b16 v150, v2 offset:288
	v_cvt_f16_f32_e32 v2, v5
	ds_write_b16 v150, v2 offset:432
	v_cvt_f16_f32_e32 v2, v6
	ds_write_b16 v150, v2 offset:1152
	v_cvt_f16_f32_e32 v2, v7
	ds_write_b16 v150, v2 offset:1296
	v_cvt_f16_f32_e32 v2, v8
	ds_write_b16 v150, v2 offset:1440
	v_cvt_f16_f32_e32 v2, v9
	ds_write_b16 v150, v2 offset:1584
	v_cvt_f16_f32_e32 v2, v10
	ds_write_b16 v150, v2 offset:2304
	v_cvt_f16_f32_e32 v2, v11
	ds_write_b16 v150, v2 offset:2448
	v_cvt_f16_f32_e32 v2, v12
	ds_write_b16 v150, v2 offset:2592
	v_cvt_f16_f32_e32 v2, v13
	ds_write_b16 v150, v2 offset:2736
	v_cvt_f16_f32_e32 v2, v14
	ds_write_b16 v150, v2 offset:3456
	v_cvt_f16_f32_e32 v2, v15
	ds_write_b16 v150, v2 offset:3600
	v_cvt_f16_f32_e32 v2, v16
	ds_write_b16 v150, v2 offset:3744
	v_cvt_f16_f32_e32 v2, v17
	ds_write_b16 v150, v2 offset:3888
	ds_read_b64_tr_b16 v[2:3], v151 offset:8192
	ds_read_b64_tr_b16 v[4:5], v151 offset:8448
	ds_read_b64_tr_b16 v[82:83], v151 offset:9216
	ds_read_b64_tr_b16 v[84:85], v151 offset:9472
	ds_read_b64_tr_b16 v[86:87], v151 offset:10240
	ds_read_b64_tr_b16 v[88:89], v151 offset:10496
	ds_read_b64_tr_b16 v[92:93], v151 offset:11264
	ds_read_b64_tr_b16 v[94:95], v151 offset:11520
	ds_read_b64_tr_b16 v[100:101], v151 offset:12288
	ds_read_b64_tr_b16 v[102:103], v151 offset:12544
	ds_read_b64_tr_b16 v[108:109], v151 offset:13312
	ds_read_b64_tr_b16 v[110:111], v151 offset:13568
	ds_read_b64_tr_b16 v[112:113], v151 offset:14336
	ds_read_b64_tr_b16 v[114:115], v151 offset:14592
	ds_read_b64_tr_b16 v[116:117], v151 offset:15360
	ds_read_b64_tr_b16 v[118:119], v151 offset:15616
	s_waitcnt lgkmcnt(14)
	v_mfma_f32_32x32x16_f16 v[2:17], v[78:81], v[2:5], 0
	s_waitcnt lgkmcnt(12)
	v_mfma_f32_32x32x16_f16 v[2:17], v[74:77], v[82:85], v[2:17]
	s_waitcnt lgkmcnt(10)
	v_mfma_f32_32x32x16_f16 v[2:17], v[70:73], v[86:89], v[2:17]
	s_waitcnt lgkmcnt(8)
	v_mfma_f32_32x32x16_f16 v[2:17], v[66:69], v[92:95], v[2:17]
	s_waitcnt lgkmcnt(6)
	v_mfma_f32_32x32x16_f16 v[2:17], v[62:65], v[100:103], v[2:17]
	s_waitcnt lgkmcnt(4)
	v_mfma_f32_32x32x16_f16 v[2:17], v[58:61], v[108:111], v[2:17]
	s_waitcnt lgkmcnt(2)
	v_mfma_f32_32x32x16_f16 v[2:17], v[54:57], v[112:115], v[2:17]
	s_waitcnt lgkmcnt(0)
	v_mfma_f32_32x32x16_f16 v[2:17], v[50:53], v[116:119], v[2:17]
	s_nop 11
	v_cvt_f16_f32_e32 v2, v2
	ds_write_b16 v150, v2 offset:64
	v_cvt_f16_f32_e32 v2, v3
	ds_write_b16 v150, v2 offset:208
	v_cvt_f16_f32_e32 v2, v4
	ds_write_b16 v150, v2 offset:352
	v_cvt_f16_f32_e32 v2, v5
	ds_write_b16 v150, v2 offset:496
	v_cvt_f16_f32_e32 v2, v6
	s_waitcnt vmcnt(15)
	v_cvt_f32_f16_e32 v6, v42
	ds_write_b16 v150, v2 offset:1216
	v_cvt_f16_f32_e32 v2, v7
	v_cvt_f32_f16_sdwa v7, v42 dst_sel:DWORD dst_unused:UNUSED_PAD src0_sel:WORD_1
	ds_write_b16 v150, v2 offset:1360
	v_cvt_f16_f32_e32 v2, v8
	v_mul_f32_e32 v8, 0x3dd2d3e8, v6
	v_fma_mix_f32 v8, -v8, v42, s9 op_sel_hi:[0,1,0]
	v_mul_f32_e32 v8, v8, v6
	ds_write_b16 v150, v2 offset:1504
	v_cvt_f16_f32_e32 v2, v9
	v_exp_f32_e32 v8, v8
	ds_write_b16 v150, v2 offset:1648
	v_cvt_f16_f32_e32 v2, v10
	s_waitcnt vmcnt(13)
	v_cvt_f32_f16_e32 v10, v46
	v_add_f32_e32 v8, 1.0, v8
	v_rcp_f32_e32 v8, v8
	ds_write_b16 v150, v2 offset:2368
	v_cvt_f16_f32_e32 v2, v11
	v_mul_f32_e32 v9, 0xbfb8aa3b, v10
	v_exp_f32_e32 v9, v9
	v_cvt_f32_f16_sdwa v11, v46 dst_sel:DWORD dst_unused:UNUSED_PAD src0_sel:WORD_1
	ds_write_b16 v150, v2 offset:2512
	v_cvt_f16_f32_e32 v2, v12
	v_add_f32_e32 v9, 1.0, v9
	v_rcp_f32_e32 v12, v9
	v_mul_f32_e32 v9, 0x3dd2d3e8, v7
	ds_write_b16 v150, v2 offset:2656
	v_cvt_f16_f32_e32 v2, v13
	v_fma_mix_f32 v9, -v9, v42, s9 op_sel:[0,1,0] op_sel_hi:[0,1,0]
	v_mul_f32_e32 v9, v9, v7
	v_exp_f32_e32 v9, v9
	ds_write_b16 v150, v2 offset:2800
	v_cvt_f16_f32_e32 v2, v14
	v_add_f32_e32 v9, 1.0, v9
	v_rcp_f32_e32 v9, v9
	ds_write_b16 v150, v2 offset:3520
	v_cvt_f16_f32_e32 v2, v15
	v_pk_mul_f32 v[6:7], v[8:9], v[6:7]
	ds_write_b16 v150, v2 offset:3664
	v_cvt_f16_f32_e32 v2, v16
	ds_write_b16 v150, v2 offset:3808
	v_cvt_f16_f32_e32 v2, v17
	ds_write_b16 v150, v2 offset:3952
	s_waitcnt lgkmcnt(0)
	ds_read_b128 v[2:5], v0
	s_waitcnt lgkmcnt(0)
; #define LAS __attribute__((address_space(3)))
; #define GAS __attribute__((address_space(1)))
; __device__ __forceinline__ float siluf(float x) { return x * __builtin_amdgcn_rcpf(1.f + __builtin_amdgcn_exp2f(-1.4426950408889634f * x)); }
; __device__ __forceinline__ float geluf(float x) { return x * __builtin_amdgcn_rcpf(1.f + __builtin_amdgcn_exp2f(x * (-0.10294324f * x * x - 2.3022082f))); }
; __device__ __forceinline__ unsigned cvtpk_h(float lo, float hi) { f32x2 v = {lo, hi}; h16x2 b = __builtin_convertvector(v, h16x2); return __builtin_bit_cast(unsigned, b); }
; __device__ __forceinline__ void gmlp_unit(unsigned char* ws, h16* Y, const h16* Ws16  , const float* bs  , size_t r0, LAS unsigned char* lds, int tid) {
;     ...
;         for (int ps = 0; ps < 4; ++ps) { const int row = 8 * ps + erow;
;             const h16x8 sv = *(const LAS h16x8*)(scr + row * 72 + 8 * ech);
;             float y[8];
; #pragma unroll
;             for (int k = 0; k < 8; ++k) y[k] = geluf((float)gu[q][ps][k]) * ((float)sv[k] + bias[q][ps]) * siluf((float)sz[q][ps][k]);
;             u32x4 w0; w0.x = cvtpk_h(y[0], y[1]); w0.y = cvtpk_h(y[2], y[3]); w0.z = cvtpk_h(y[4], y[5]); w0.w = cvtpk_h(y[6], y[7]);
;             *(GAS u32x4*)(Y + (r0 + 32 * (2 * ph + q) + row) * D + g * 64 + 8 * ech) = w0; }
	v_cvt_f32_f16_e32 v8, v2
	v_cvt_f32_f16_sdwa v9, v2 dst_sel:DWORD dst_unused:UNUSED_PAD src0_sel:WORD_1
	v_mul_f32_e32 v2, 0xbfb8aa3b, v11
	v_exp_f32_e32 v2, v2
	v_pk_add_f32 v[8:9], v[172:173], v[8:9] op_sel_hi:[0,1]
	v_pk_mul_f32 v[6:7], v[6:7], v[8:9]
	v_add_f32_e32 v2, 1.0, v2
	v_rcp_f32_e32 v13, v2
	s_nop 0
	v_pk_mul_f32 v[8:9], v[12:13], v[10:11]
	s_nop 0
	v_pk_mul_f32 v[6:7], v[8:9], v[6:7]
	v_cvt_f32_f16_e32 v8, v43
	v_cvt_f32_f16_sdwa v9, v43 dst_sel:DWORD dst_unused:UNUSED_PAD src0_sel:WORD_1
	v_cvt_f32_f16_e32 v12, v47
	v_cvt_f32_f16_sdwa v13, v47 dst_sel:DWORD dst_unused:UNUSED_PAD src0_sel:WORD_1
	v_mul_f32_e32 v2, 0x3dd2d3e8, v8
	v_mul_f32_e32 v11, 0x3dd2d3e8, v9
	v_fma_mix_f32 v2, -v2, v43, s9 op_sel_hi:[0,1,0]
	v_fma_mix_f32 v11, -v11, v43, s9 op_sel:[0,1,0] op_sel_hi:[0,1,0]
	v_mul_f32_e32 v2, v2, v8
	v_mul_f32_e32 v11, v11, v9
	v_exp_f32_e32 v2, v2
	v_exp_f32_e32 v11, v11
	v_add_f32_e32 v2, 1.0, v2
	v_add_f32_e32 v11, 1.0, v11
	v_rcp_f32_e32 v10, v2
	v_rcp_f32_e32 v11, v11
	v_mul_f32_e32 v2, 0xbfb8aa3b, v12
	v_exp_f32_e32 v2, v2
	v_pk_mul_f32 v[8:9], v[10:11], v[8:9]
	v_cvt_f32_f16_e32 v10, v3
	v_cvt_f32_f16_sdwa v11, v3 dst_sel:DWORD dst_unused:UNUSED_PAD src0_sel:WORD_1
	v_mul_f32_e32 v3, 0xbfb8aa3b, v13
	v_exp_f32_e32 v3, v3
	v_add_f32_e32 v2, 1.0, v2
	v_rcp_f32_e32 v2, v2
	v_pk_add_f32 v[10:11], v[172:173], v[10:11] op_sel_hi:[0,1]
	v_add_f32_e32 v3, 1.0, v3
	v_rcp_f32_e32 v3, v3
	v_pk_mul_f32 v[8:9], v[8:9], v[10:11]
	v_pk_mul_f32 v[2:3], v[2:3], v[12:13]
	v_cvt_f32_f16_e32 v12, v48
	v_pk_mul_f32 v[8:9], v[2:3], v[8:9]
	v_cvt_f32_f16_e32 v2, v44
	v_cvt_f32_f16_sdwa v3, v44 dst_sel:DWORD dst_unused:UNUSED_PAD src0_sel:WORD_1
	v_mul_f32_e32 v11, 0xbfb8aa3b, v12
	v_exp_f32_e32 v11, v11
	v_mul_f32_e32 v10, 0x3dd2d3e8, v2
	v_fma_mix_f32 v10, -v10, v44, s9 op_sel_hi:[0,1,0]
	v_mul_f32_e32 v10, v10, v2
	v_add_f32_e32 v11, 1.0, v11
	v_rcp_f32_e32 v14, v11
	v_mul_f32_e32 v11, 0x3dd2d3e8, v3
	v_fma_mix_f32 v11, -v11, v44, s9 op_sel:[0,1,0] op_sel_hi:[0,1,0]
	v_mul_f32_e32 v11, v11, v3
	v_exp_f32_e32 v10, v10
	v_exp_f32_e32 v11, v11
	v_cvt_f32_f16_sdwa v13, v48 dst_sel:DWORD dst_unused:UNUSED_PAD src0_sel:WORD_1
	v_add_f32_e32 v10, 1.0, v10
	v_add_f32_e32 v11, 1.0, v11
	v_rcp_f32_e32 v10, v10
	v_rcp_f32_e32 v11, v11
	s_nop 0
	v_pk_mul_f32 v[2:3], v[10:11], v[2:3]
	v_cvt_f32_f16_e32 v10, v4
	v_cvt_f32_f16_sdwa v11, v4 dst_sel:DWORD dst_unused:UNUSED_PAD src0_sel:WORD_1
	v_mul_f32_e32 v4, 0xbfb8aa3b, v13
	v_exp_f32_e32 v4, v4
	v_pk_add_f32 v[10:11], v[172:173], v[10:11] op_sel_hi:[0,1]
	v_pk_mul_f32 v[2:3], v[2:3], v[10:11]
	v_add_f32_e32 v4, 1.0, v4
	v_rcp_f32_e32 v15, v4
	s_nop 0
	v_pk_mul_f32 v[10:11], v[14:15], v[12:13]
	s_nop 0
	v_pk_mul_f32 v[10:11], v[10:11], v[2:3]
	v_cvt_f32_f16_e32 v2, v45
	v_cvt_f32_f16_sdwa v3, v45 dst_sel:DWORD dst_unused:UNUSED_PAD src0_sel:WORD_1
	v_cvt_f32_f16_e32 v14, v49
	v_cvt_f32_f16_sdwa v15, v49 dst_sel:DWORD dst_unused:UNUSED_PAD src0_sel:WORD_1
	v_mul_f32_e32 v4, 0x3dd2d3e8, v2
	v_mul_f32_e32 v13, 0x3dd2d3e8, v3
	v_fma_mix_f32 v4, -v4, v45, s9 op_sel_hi:[0,1,0]
	v_fma_mix_f32 v13, -v13, v45, s9 op_sel:[0,1,0] op_sel_hi:[0,1,0]
	v_mul_f32_e32 v4, v4, v2
	v_mul_f32_e32 v13, v13, v3
	v_exp_f32_e32 v4, v4
	v_exp_f32_e32 v13, v13
	v_add_f32_e32 v4, 1.0, v4
	v_add_f32_e32 v13, 1.0, v13
	v_rcp_f32_e32 v12, v4
	v_rcp_f32_e32 v13, v13
	v_mul_f32_e32 v4, 0xbfb8aa3b, v14
	v_exp_f32_e32 v4, v4
	v_pk_mul_f32 v[2:3], v[12:13], v[2:3]
	v_cvt_f32_f16_e32 v12, v5
	v_cvt_f32_f16_sdwa v13, v5 dst_sel:DWORD dst_unused:UNUSED_PAD src0_sel:WORD_1
	v_mul_f32_e32 v5, 0xbfb8aa3b, v15
	v_exp_f32_e32 v5, v5
	v_add_f32_e32 v4, 1.0, v4
	v_rcp_f32_e32 v4, v4
	v_pk_add_f32 v[12:13], v[172:173], v[12:13] op_sel_hi:[0,1]
	v_add_f32_e32 v5, 1.0, v5
	v_rcp_f32_e32 v5, v5
	v_pk_mul_f32 v[2:3], v[2:3], v[12:13]
	v_pk_mul_f32 v[4:5], v[4:5], v[14:15]
	s_nop 0
	v_pk_mul_f32 v[12:13], v[4:5], v[2:3]
	v_cvt_pk_f16_f32 v4, v10, v11
	s_waitcnt vmcnt(10)
	v_cvt_f32_f16_e32 v10, v38
	v_cvt_pk_f16_f32 v2, v6, v7
	v_cvt_pk_f16_f32 v3, v8, v9
	v_lshlrev_b64 v[6:7], 11, v[164:165]
	v_mul_f32_e32 v9, 0xbfb8aa3b, v10
	v_cvt_pk_f16_f32 v5, v12, v13
	v_lshl_add_u64 v[6:7], v[148:149], 0, v[6:7]
	v_exp_f32_e32 v9, v9
	global_store_dwordx4 v[6:7], v[2:5], off
	v_cvt_f32_f16_e32 v6, v34
	v_cvt_f32_f16_sdwa v7, v34 dst_sel:DWORD dst_unused:UNUSED_PAD src0_sel:WORD_1
	v_add_f32_e32 v9, 1.0, v9
	v_rcp_f32_e32 v12, v9
	v_mul_f32_e32 v8, 0x3dd2d3e8, v6
	v_mul_f32_e32 v9, 0x3dd2d3e8, v7
	v_fma_mix_f32 v8, -v8, v34, s9 op_sel_hi:[0,1,0]
	v_fma_mix_f32 v9, -v9, v34, s9 op_sel:[0,1,0] op_sel_hi:[0,1,0]
	v_mul_f32_e32 v8, v8, v6
	v_mul_f32_e32 v9, v9, v7
	v_exp_f32_e32 v8, v8
	v_exp_f32_e32 v9, v9
	ds_read_b128 v[2:5], v0 offset:1152
	v_cvt_f32_f16_sdwa v11, v38 dst_sel:DWORD dst_unused:UNUSED_PAD src0_sel:WORD_1
	v_add_f32_e32 v8, 1.0, v8
	v_add_f32_e32 v9, 1.0, v9
	v_rcp_f32_e32 v8, v8
	v_rcp_f32_e32 v9, v9
	v_or_b32_e32 v164, s2, v106
	v_pk_mul_f32 v[6:7], v[8:9], v[6:7]
	s_waitcnt lgkmcnt(0)
; #define LAS __attribute__((address_space(3)))
; #define GAS __attribute__((address_space(1)))
; __device__ __forceinline__ float siluf(float x) { return x * __builtin_amdgcn_rcpf(1.f + __builtin_amdgcn_exp2f(-1.4426950408889634f * x)); }
; __device__ __forceinline__ float geluf(float x) { return x * __builtin_amdgcn_rcpf(1.f + __builtin_amdgcn_exp2f(x * (-0.10294324f * x * x - 2.3022082f))); }
; __device__ __forceinline__ unsigned cvtpk_h(float lo, float hi) { f32x2 v = {lo, hi}; h16x2 b = __builtin_convertvector(v, h16x2); return __builtin_bit_cast(unsigned, b); }
; __device__ __forceinline__ void gmlp_unit(unsigned char* ws, h16* Y, const h16* Ws16  , const float* bs  , size_t r0, LAS unsigned char* lds, int tid) {
;     ...
;         for (int ps = 0; ps < 4; ++ps) { const int row = 8 * ps + erow;
;             const h16x8 sv = *(const LAS h16x8*)(scr + row * 72 + 8 * ech);
;             float y[8];
; #pragma unroll
;             for (int k = 0; k < 8; ++k) y[k] = geluf((float)gu[q][ps][k]) * ((float)sv[k] + bias[q][ps]) * siluf((float)sz[q][ps][k]);
;             u32x4 w0; w0.x = cvtpk_h(y[0], y[1]); w0.y = cvtpk_h(y[2], y[3]); w0.z = cvtpk_h(y[4], y[5]); w0.w = cvtpk_h(y[6], y[7]);
;             *(GAS u32x4*)(Y + (r0 + 32 * (2 * ph + q) + row) * D + g * 64 + 8 * ech) = w0; }
	v_cvt_f32_f16_e32 v8, v2
	v_cvt_f32_f16_sdwa v9, v2 dst_sel:DWORD dst_unused:UNUSED_PAD src0_sel:WORD_1
	v_mul_f32_e32 v2, 0xbfb8aa3b, v11
	v_exp_f32_e32 v2, v2
	v_pk_add_f32 v[8:9], v[170:171], v[8:9] op_sel_hi:[0,1]
	v_pk_mul_f32 v[6:7], v[6:7], v[8:9]
	v_add_f32_e32 v2, 1.0, v2
	v_rcp_f32_e32 v13, v2
	s_nop 0
	v_pk_mul_f32 v[8:9], v[12:13], v[10:11]
	s_nop 0
	v_pk_mul_f32 v[6:7], v[8:9], v[6:7]
	v_cvt_f32_f16_e32 v8, v35
	v_cvt_f32_f16_sdwa v9, v35 dst_sel:DWORD dst_unused:UNUSED_PAD src0_sel:WORD_1
	v_cvt_f32_f16_e32 v12, v39
	v_cvt_f32_f16_sdwa v13, v39 dst_sel:DWORD dst_unused:UNUSED_PAD src0_sel:WORD_1
	v_mul_f32_e32 v2, 0x3dd2d3e8, v8
	v_mul_f32_e32 v11, 0x3dd2d3e8, v9
	v_fma_mix_f32 v2, -v2, v35, s9 op_sel_hi:[0,1,0]
	v_fma_mix_f32 v11, -v11, v35, s9 op_sel:[0,1,0] op_sel_hi:[0,1,0]
	v_mul_f32_e32 v2, v2, v8
	v_mul_f32_e32 v11, v11, v9
	v_exp_f32_e32 v2, v2
	v_exp_f32_e32 v11, v11
	v_add_f32_e32 v2, 1.0, v2
	v_add_f32_e32 v11, 1.0, v11
	v_rcp_f32_e32 v10, v2
	v_rcp_f32_e32 v11, v11
	v_mul_f32_e32 v2, 0xbfb8aa3b, v12
	v_exp_f32_e32 v2, v2
	v_pk_mul_f32 v[8:9], v[10:11], v[8:9]
	v_cvt_f32_f16_e32 v10, v3
	v_cvt_f32_f16_sdwa v11, v3 dst_sel:DWORD dst_unused:UNUSED_PAD src0_sel:WORD_1
	v_mul_f32_e32 v3, 0xbfb8aa3b, v13
	v_exp_f32_e32 v3, v3
	v_add_f32_e32 v2, 1.0, v2
	v_rcp_f32_e32 v2, v2
	v_pk_add_f32 v[10:11], v[170:171], v[10:11] op_sel_hi:[0,1]
	v_add_f32_e32 v3, 1.0, v3
	v_rcp_f32_e32 v3, v3
	v_pk_mul_f32 v[8:9], v[8:9], v[10:11]
	v_pk_mul_f32 v[2:3], v[2:3], v[12:13]
	v_cvt_f32_f16_e32 v12, v40
	v_pk_mul_f32 v[2:3], v[2:3], v[8:9]
	v_cvt_f32_f16_e32 v8, v36
	v_cvt_f32_f16_sdwa v9, v36 dst_sel:DWORD dst_unused:UNUSED_PAD src0_sel:WORD_1
	v_mul_f32_e32 v11, 0xbfb8aa3b, v12
	v_exp_f32_e32 v11, v11
	v_mul_f32_e32 v10, 0x3dd2d3e8, v8
	v_fma_mix_f32 v10, -v10, v36, s9 op_sel_hi:[0,1,0]
	v_mul_f32_e32 v10, v10, v8
	v_add_f32_e32 v11, 1.0, v11
	v_rcp_f32_e32 v14, v11
	v_mul_f32_e32 v11, 0x3dd2d3e8, v9
	v_fma_mix_f32 v11, -v11, v36, s9 op_sel:[0,1,0] op_sel_hi:[0,1,0]
	v_mul_f32_e32 v11, v11, v9
	v_exp_f32_e32 v10, v10
	v_exp_f32_e32 v11, v11
	v_cvt_f32_f16_sdwa v13, v40 dst_sel:DWORD dst_unused:UNUSED_PAD src0_sel:WORD_1
	v_add_f32_e32 v10, 1.0, v10
	v_add_f32_e32 v11, 1.0, v11
	v_rcp_f32_e32 v10, v10
	v_rcp_f32_e32 v11, v11
	s_nop 0
	v_pk_mul_f32 v[8:9], v[10:11], v[8:9]
	v_cvt_f32_f16_e32 v10, v4
	v_cvt_f32_f16_sdwa v11, v4 dst_sel:DWORD dst_unused:UNUSED_PAD src0_sel:WORD_1
	v_mul_f32_e32 v4, 0xbfb8aa3b, v13
	v_exp_f32_e32 v4, v4
	v_pk_add_f32 v[10:11], v[170:171], v[10:11] op_sel_hi:[0,1]
	v_pk_mul_f32 v[8:9], v[8:9], v[10:11]
	v_add_f32_e32 v4, 1.0, v4
	v_rcp_f32_e32 v15, v4
	s_nop 0
	v_pk_mul_f32 v[10:11], v[14:15], v[12:13]
	s_nop 0
	v_pk_mul_f32 v[8:9], v[10:11], v[8:9]
	v_cvt_f32_f16_e32 v10, v37
	v_cvt_f32_f16_sdwa v11, v37 dst_sel:DWORD dst_unused:UNUSED_PAD src0_sel:WORD_1
	v_cvt_f32_f16_e32 v14, v41
	v_cvt_f32_f16_sdwa v15, v41 dst_sel:DWORD dst_unused:UNUSED_PAD src0_sel:WORD_1
	v_mul_f32_e32 v4, 0x3dd2d3e8, v10
	v_mul_f32_e32 v13, 0x3dd2d3e8, v11
	v_fma_mix_f32 v4, -v4, v37, s9 op_sel_hi:[0,1,0]
	v_fma_mix_f32 v13, -v13, v37, s9 op_sel:[0,1,0] op_sel_hi:[0,1,0]
	v_mul_f32_e32 v4, v4, v10
	v_mul_f32_e32 v13, v13, v11
	v_exp_f32_e32 v4, v4
	v_exp_f32_e32 v13, v13
	v_add_f32_e32 v4, 1.0, v4
	v_add_f32_e32 v13, 1.0, v13
	v_rcp_f32_e32 v12, v4
	v_rcp_f32_e32 v13, v13
	v_mul_f32_e32 v4, 0xbfb8aa3b, v14
	v_exp_f32_e32 v4, v4
	v_pk_mul_f32 v[10:11], v[12:13], v[10:11]
	v_cvt_f32_f16_e32 v12, v5
	v_cvt_f32_f16_sdwa v13, v5 dst_sel:DWORD dst_unused:UNUSED_PAD src0_sel:WORD_1
	v_mul_f32_e32 v5, 0xbfb8aa3b, v15
	v_exp_f32_e32 v5, v5
	v_add_f32_e32 v4, 1.0, v4
	v_rcp_f32_e32 v4, v4
	v_pk_add_f32 v[12:13], v[170:171], v[12:13] op_sel_hi:[0,1]
	v_add_f32_e32 v5, 1.0, v5
	v_rcp_f32_e32 v5, v5
	v_pk_mul_f32 v[10:11], v[10:11], v[12:13]
	v_pk_mul_f32 v[4:5], v[4:5], v[14:15]
	s_nop 0
	v_pk_mul_f32 v[10:11], v[4:5], v[10:11]
	v_cvt_pk_f16_f32 v4, v6, v7
	v_cvt_pk_f16_f32 v7, v10, v11
	s_waitcnt vmcnt(8)
	v_cvt_f32_f16_e32 v10, v30
	v_cvt_pk_f16_f32 v5, v2, v3
	v_cvt_pk_f16_f32 v6, v8, v9
	v_lshlrev_b64 v[2:3], 11, v[164:165]
	v_mul_f32_e32 v9, 0xbfb8aa3b, v10
	v_lshl_add_u64 v[2:3], v[148:149], 0, v[2:3]
	v_exp_f32_e32 v9, v9
	global_store_dwordx4 v[2:3], v[4:7], off
	ds_read_b128 v[2:5], v0 offset:2304
	v_cvt_f32_f16_sdwa v11, v30 dst_sel:DWORD dst_unused:UNUSED_PAD src0_sel:WORD_1
	v_cvt_f32_f16_e32 v6, v26
	v_cvt_f32_f16_sdwa v7, v26 dst_sel:DWORD dst_unused:UNUSED_PAD src0_sel:WORD_1
	v_add_f32_e32 v9, 1.0, v9
	v_rcp_f32_e32 v12, v9
	v_mul_f32_e32 v8, 0x3dd2d3e8, v6
	v_mul_f32_e32 v9, 0x3dd2d3e8, v7
	v_fma_mix_f32 v8, -v8, v26, s9 op_sel_hi:[0,1,0]
	v_fma_mix_f32 v9, -v9, v26, s9 op_sel:[0,1,0] op_sel_hi:[0,1,0]
	v_mul_f32_e32 v8, v8, v6
	v_mul_f32_e32 v9, v9, v7
	v_exp_f32_e32 v8, v8
	v_exp_f32_e32 v9, v9
	v_or_b32_e32 v164, s2, v98
	v_add_f32_e32 v8, 1.0, v8
	v_add_f32_e32 v9, 1.0, v9
	v_rcp_f32_e32 v8, v8
	v_rcp_f32_e32 v9, v9
	s_nop 0
	v_pk_mul_f32 v[6:7], v[8:9], v[6:7]
	s_waitcnt lgkmcnt(0)
; #define LAS __attribute__((address_space(3)))
; #define GAS __attribute__((address_space(1)))
; __device__ __forceinline__ float siluf(float x) { return x * __builtin_amdgcn_rcpf(1.f + __builtin_amdgcn_exp2f(-1.4426950408889634f * x)); }
; __device__ __forceinline__ float geluf(float x) { return x * __builtin_amdgcn_rcpf(1.f + __builtin_amdgcn_exp2f(x * (-0.10294324f * x * x - 2.3022082f))); }
; __device__ __forceinline__ unsigned cvtpk_h(float lo, float hi) { f32x2 v = {lo, hi}; h16x2 b = __builtin_convertvector(v, h16x2); return __builtin_bit_cast(unsigned, b); }
; __device__ __forceinline__ void gmlp_unit(unsigned char* ws, h16* Y, const h16* Ws16  , const float* bs  , size_t r0, LAS unsigned char* lds, int tid) {
;     ...
;         for (int ps = 0; ps < 4; ++ps) { const int row = 8 * ps + erow;
;             const h16x8 sv = *(const LAS h16x8*)(scr + row * 72 + 8 * ech);
;             float y[8];
; #pragma unroll
;             for (int k = 0; k < 8; ++k) y[k] = geluf((float)gu[q][ps][k]) * ((float)sv[k] + bias[q][ps]) * siluf((float)sz[q][ps][k]);
;             u32x4 w0; w0.x = cvtpk_h(y[0], y[1]); w0.y = cvtpk_h(y[2], y[3]); w0.z = cvtpk_h(y[4], y[5]); w0.w = cvtpk_h(y[6], y[7]);
;             *(GAS u32x4*)(Y + (r0 + 32 * (2 * ph + q) + row) * D + g * 64 + 8 * ech) = w0; }
	v_cvt_f32_f16_e32 v8, v2
	v_cvt_f32_f16_sdwa v9, v2 dst_sel:DWORD dst_unused:UNUSED_PAD src0_sel:WORD_1
	v_mul_f32_e32 v2, 0xbfb8aa3b, v11
	v_exp_f32_e32 v2, v2
	v_pk_add_f32 v[8:9], v[168:169], v[8:9] op_sel_hi:[0,1]
	v_pk_mul_f32 v[6:7], v[6:7], v[8:9]
	v_add_f32_e32 v2, 1.0, v2
	v_rcp_f32_e32 v13, v2
	s_nop 0
	v_pk_mul_f32 v[8:9], v[12:13], v[10:11]
	s_nop 0
	v_pk_mul_f32 v[6:7], v[8:9], v[6:7]
	v_cvt_f32_f16_e32 v8, v27
	v_cvt_f32_f16_sdwa v9, v27 dst_sel:DWORD dst_unused:UNUSED_PAD src0_sel:WORD_1
	v_cvt_f32_f16_e32 v12, v31
	v_cvt_f32_f16_sdwa v13, v31 dst_sel:DWORD dst_unused:UNUSED_PAD src0_sel:WORD_1
	v_mul_f32_e32 v2, 0x3dd2d3e8, v8
	v_mul_f32_e32 v11, 0x3dd2d3e8, v9
	v_fma_mix_f32 v2, -v2, v27, s9 op_sel_hi:[0,1,0]
	v_fma_mix_f32 v11, -v11, v27, s9 op_sel:[0,1,0] op_sel_hi:[0,1,0]
	v_mul_f32_e32 v2, v2, v8
	v_mul_f32_e32 v11, v11, v9
	v_exp_f32_e32 v2, v2
	v_exp_f32_e32 v11, v11
	v_add_f32_e32 v2, 1.0, v2
	v_add_f32_e32 v11, 1.0, v11
	v_rcp_f32_e32 v10, v2
	v_rcp_f32_e32 v11, v11
	v_mul_f32_e32 v2, 0xbfb8aa3b, v12
	v_exp_f32_e32 v2, v2
	v_pk_mul_f32 v[8:9], v[10:11], v[8:9]
	v_cvt_f32_f16_e32 v10, v3
	v_cvt_f32_f16_sdwa v11, v3 dst_sel:DWORD dst_unused:UNUSED_PAD src0_sel:WORD_1
	v_mul_f32_e32 v3, 0xbfb8aa3b, v13
	v_exp_f32_e32 v3, v3
	v_add_f32_e32 v2, 1.0, v2
	v_rcp_f32_e32 v2, v2
	v_pk_add_f32 v[10:11], v[168:169], v[10:11] op_sel_hi:[0,1]
	v_add_f32_e32 v3, 1.0, v3
	v_rcp_f32_e32 v3, v3
	v_pk_mul_f32 v[8:9], v[8:9], v[10:11]
	v_pk_mul_f32 v[2:3], v[2:3], v[12:13]
	v_cvt_f32_f16_e32 v12, v32
	v_pk_mul_f32 v[8:9], v[2:3], v[8:9]
	v_cvt_f32_f16_e32 v2, v28
	v_cvt_f32_f16_sdwa v3, v28 dst_sel:DWORD dst_unused:UNUSED_PAD src0_sel:WORD_1
	v_mul_f32_e32 v11, 0xbfb8aa3b, v12
	v_exp_f32_e32 v11, v11
	v_mul_f32_e32 v10, 0x3dd2d3e8, v2
	v_fma_mix_f32 v10, -v10, v28, s9 op_sel_hi:[0,1,0]
	v_mul_f32_e32 v10, v10, v2
	v_add_f32_e32 v11, 1.0, v11
	v_rcp_f32_e32 v14, v11
	v_mul_f32_e32 v11, 0x3dd2d3e8, v3
	v_fma_mix_f32 v11, -v11, v28, s9 op_sel:[0,1,0] op_sel_hi:[0,1,0]
	v_mul_f32_e32 v11, v11, v3
	v_exp_f32_e32 v10, v10
	v_exp_f32_e32 v11, v11
	v_cvt_f32_f16_sdwa v13, v32 dst_sel:DWORD dst_unused:UNUSED_PAD src0_sel:WORD_1
	v_add_f32_e32 v10, 1.0, v10
	v_add_f32_e32 v11, 1.0, v11
	v_rcp_f32_e32 v10, v10
	v_rcp_f32_e32 v11, v11
	s_nop 0
	v_pk_mul_f32 v[2:3], v[10:11], v[2:3]
	v_cvt_f32_f16_e32 v10, v4
	v_cvt_f32_f16_sdwa v11, v4 dst_sel:DWORD dst_unused:UNUSED_PAD src0_sel:WORD_1
	v_mul_f32_e32 v4, 0xbfb8aa3b, v13
	v_exp_f32_e32 v4, v4
	v_pk_add_f32 v[10:11], v[168:169], v[10:11] op_sel_hi:[0,1]
	v_pk_mul_f32 v[2:3], v[2:3], v[10:11]
	v_add_f32_e32 v4, 1.0, v4
	v_rcp_f32_e32 v15, v4
	s_nop 0
	v_pk_mul_f32 v[10:11], v[14:15], v[12:13]
	s_nop 0
	v_pk_mul_f32 v[10:11], v[10:11], v[2:3]
	v_cvt_f32_f16_e32 v2, v29
	v_cvt_f32_f16_sdwa v3, v29 dst_sel:DWORD dst_unused:UNUSED_PAD src0_sel:WORD_1
	v_cvt_f32_f16_e32 v14, v33
	v_cvt_f32_f16_sdwa v15, v33 dst_sel:DWORD dst_unused:UNUSED_PAD src0_sel:WORD_1
	v_mul_f32_e32 v4, 0x3dd2d3e8, v2
	v_mul_f32_e32 v13, 0x3dd2d3e8, v3
	v_fma_mix_f32 v4, -v4, v29, s9 op_sel_hi:[0,1,0]
	v_fma_mix_f32 v13, -v13, v29, s9 op_sel:[0,1,0] op_sel_hi:[0,1,0]
	v_mul_f32_e32 v4, v4, v2
	v_mul_f32_e32 v13, v13, v3
	v_exp_f32_e32 v4, v4
	v_exp_f32_e32 v13, v13
	v_add_f32_e32 v4, 1.0, v4
	v_add_f32_e32 v13, 1.0, v13
	v_rcp_f32_e32 v12, v4
	v_rcp_f32_e32 v13, v13
	v_mul_f32_e32 v4, 0xbfb8aa3b, v14
	v_exp_f32_e32 v4, v4
	v_pk_mul_f32 v[2:3], v[12:13], v[2:3]
	v_cvt_f32_f16_e32 v12, v5
	v_cvt_f32_f16_sdwa v13, v5 dst_sel:DWORD dst_unused:UNUSED_PAD src0_sel:WORD_1
	v_mul_f32_e32 v5, 0xbfb8aa3b, v15
	v_exp_f32_e32 v5, v5
	v_add_f32_e32 v4, 1.0, v4
	v_rcp_f32_e32 v4, v4
	v_pk_add_f32 v[12:13], v[168:169], v[12:13] op_sel_hi:[0,1]
	v_add_f32_e32 v5, 1.0, v5
	v_rcp_f32_e32 v5, v5
	v_pk_mul_f32 v[2:3], v[2:3], v[12:13]
	v_pk_mul_f32 v[4:5], v[4:5], v[14:15]
	s_nop 0
	v_pk_mul_f32 v[12:13], v[4:5], v[2:3]
	v_cvt_pk_f16_f32 v2, v6, v7
	v_lshlrev_b64 v[6:7], 11, v[164:165]
	v_cvt_pk_f16_f32 v3, v8, v9
	v_cvt_pk_f16_f32 v4, v10, v11
	v_cvt_pk_f16_f32 v5, v12, v13
	v_lshl_add_u64 v[6:7], v[148:149], 0, v[6:7]
	global_store_dwordx4 v[6:7], v[2:5], off
	s_waitcnt vmcnt(8)
	v_cvt_f32_f16_e32 v6, v18
	ds_read_b128 v[2:5], v0 offset:3456
	s_waitcnt vmcnt(7)
; #define LAS __attribute__((address_space(3)))
; #define GAS __attribute__((address_space(1)))
; __device__ __forceinline__ float siluf(float x) { return x * __builtin_amdgcn_rcpf(1.f + __builtin_amdgcn_exp2f(-1.4426950408889634f * x)); }
; __device__ __forceinline__ float geluf(float x) { return x * __builtin_amdgcn_rcpf(1.f + __builtin_amdgcn_exp2f(x * (-0.10294324f * x * x - 2.3022082f))); }
; __device__ __forceinline__ unsigned cvtpk_h(float lo, float hi) { f32x2 v = {lo, hi}; h16x2 b = __builtin_convertvector(v, h16x2); return __builtin_bit_cast(unsigned, b); }
; #define LDS_WAIT() asm volatile("s_waitcnt lgkmcnt(0)" ::: "memory")
; #define BAR_LDS() asm volatile("s_waitcnt lgkmcnt(0)\n\ts_barrier" ::: "memory")
; __device__ __forceinline__ void gmlp_unit(unsigned char* ws, h16* Y, const h16* Ws16  , const float* bs  , size_t r0, LAS unsigned char* lds, int tid) {
;     ...
;         for (int ps = 0; ps < 4; ++ps) { const int row = 8 * ps + erow;
;             const h16x8 sv = *(const LAS h16x8*)(scr + row * 72 + 8 * ech);
;             float y[8];
; #pragma unroll
;             for (int k = 0; k < 8; ++k) y[k] = geluf((float)gu[q][ps][k]) * ((float)sv[k] + bias[q][ps]) * siluf((float)sz[q][ps][k]);
;             u32x4 w0; w0.x = cvtpk_h(y[0], y[1]); w0.y = cvtpk_h(y[2], y[3]); w0.z = cvtpk_h(y[4], y[5]); w0.w = cvtpk_h(y[6], y[7]);
;             *(GAS u32x4*)(Y + (r0 + 32 * (2 * ph + q) + row) * D + g * 64 + 8 * ech) = w0; }
;         LDS_WAIT();
;     }
;     BAR_LDS();
	v_cvt_f32_f16_e32 v10, v22
	v_cvt_f32_f16_sdwa v7, v18 dst_sel:DWORD dst_unused:UNUSED_PAD src0_sel:WORD_1
	v_mul_f32_e32 v0, 0x3dd2d3e8, v6
	v_fma_mix_f32 v0, -v0, v18, s9 op_sel_hi:[0,1,0]
	v_mul_f32_e32 v0, v0, v6
	v_exp_f32_e32 v0, v0
	v_cvt_f32_f16_sdwa v11, v22 dst_sel:DWORD dst_unused:UNUSED_PAD src0_sel:WORD_1
	v_or_b32_e32 v164, s2, v90
	s_mov_b64 s[2:3], 0
	v_add_f32_e32 v0, 1.0, v0
	v_rcp_f32_e32 v8, v0
	v_mul_f32_e32 v0, 0xbfb8aa3b, v10
	v_exp_f32_e32 v0, v0
	s_nop 0
	v_add_f32_e32 v0, 1.0, v0
	v_rcp_f32_e32 v12, v0
	v_mul_f32_e32 v0, 0x3dd2d3e8, v7
	v_fma_mix_f32 v0, -v0, v18, s9 op_sel:[0,1,0] op_sel_hi:[0,1,0]
	v_mul_f32_e32 v0, v0, v7
	v_exp_f32_e32 v0, v0
	s_nop 0
	v_add_f32_e32 v0, 1.0, v0
	v_rcp_f32_e32 v9, v0
	v_mul_f32_e32 v0, 0xbfb8aa3b, v11
	v_exp_f32_e32 v0, v0
	v_pk_mul_f32 v[6:7], v[8:9], v[6:7]
	s_waitcnt lgkmcnt(0)
	v_cvt_f32_f16_e32 v8, v2
	v_cvt_f32_f16_sdwa v9, v2 dst_sel:DWORD dst_unused:UNUSED_PAD src0_sel:WORD_1
	v_add_f32_e32 v0, 1.0, v0
	v_rcp_f32_e32 v13, v0
	v_pk_add_f32 v[8:9], v[166:167], v[8:9] op_sel_hi:[0,1]
	v_pk_mul_f32 v[6:7], v[6:7], v[8:9]
	v_pk_mul_f32 v[8:9], v[12:13], v[10:11]
	v_cvt_f32_f16_e32 v12, v23
	v_pk_mul_f32 v[6:7], v[8:9], v[6:7]
	v_cvt_f32_f16_e32 v8, v19
	v_cvt_f32_f16_sdwa v9, v19 dst_sel:DWORD dst_unused:UNUSED_PAD src0_sel:WORD_1
	v_cvt_f32_f16_sdwa v13, v23 dst_sel:DWORD dst_unused:UNUSED_PAD src0_sel:WORD_1
	v_mul_f32_e32 v0, 0x3dd2d3e8, v8
	v_fma_mix_f32 v0, -v0, v19, s9 op_sel_hi:[0,1,0]
	v_mul_f32_e32 v0, v0, v8
	v_exp_f32_e32 v0, v0
	s_nop 0
	v_add_f32_e32 v0, 1.0, v0
	v_rcp_f32_e32 v10, v0
	v_mul_f32_e32 v0, 0xbfb8aa3b, v12
	v_exp_f32_e32 v0, v0
	s_nop 0
	v_add_f32_e32 v0, 1.0, v0
	v_rcp_f32_e32 v2, v0
	v_mul_f32_e32 v0, 0x3dd2d3e8, v9
	v_fma_mix_f32 v0, -v0, v19, s9 op_sel:[0,1,0] op_sel_hi:[0,1,0]
	v_mul_f32_e32 v0, v0, v9
	v_exp_f32_e32 v0, v0
	s_nop 0
	v_add_f32_e32 v0, 1.0, v0
	v_rcp_f32_e32 v11, v0
	v_mul_f32_e32 v0, 0xbfb8aa3b, v13
	v_exp_f32_e32 v0, v0
	v_pk_mul_f32 v[8:9], v[10:11], v[8:9]
	v_cvt_f32_f16_e32 v10, v3
	v_cvt_f32_f16_sdwa v11, v3 dst_sel:DWORD dst_unused:UNUSED_PAD src0_sel:WORD_1
	v_add_f32_e32 v0, 1.0, v0
	v_rcp_f32_e32 v3, v0
	v_pk_add_f32 v[10:11], v[166:167], v[10:11] op_sel_hi:[0,1]
	v_pk_mul_f32 v[8:9], v[8:9], v[10:11]
	v_pk_mul_f32 v[2:3], v[2:3], v[12:13]
	v_cvt_f32_f16_e32 v12, v24
	v_pk_mul_f32 v[2:3], v[2:3], v[8:9]
	v_cvt_f32_f16_e32 v8, v20
	v_cvt_f32_f16_sdwa v9, v20 dst_sel:DWORD dst_unused:UNUSED_PAD src0_sel:WORD_1
	v_cvt_f32_f16_sdwa v13, v24 dst_sel:DWORD dst_unused:UNUSED_PAD src0_sel:WORD_1
	v_mul_f32_e32 v0, 0x3dd2d3e8, v8
	v_fma_mix_f32 v0, -v0, v20, s9 op_sel_hi:[0,1,0]
	v_mul_f32_e32 v0, v0, v8
	v_exp_f32_e32 v0, v0
	s_nop 0
	v_add_f32_e32 v0, 1.0, v0
	v_rcp_f32_e32 v10, v0
	v_mul_f32_e32 v0, 0xbfb8aa3b, v12
	v_exp_f32_e32 v0, v0
	s_nop 0
	v_add_f32_e32 v0, 1.0, v0
	v_rcp_f32_e32 v14, v0
	v_mul_f32_e32 v0, 0x3dd2d3e8, v9
	v_fma_mix_f32 v0, -v0, v20, s9 op_sel:[0,1,0] op_sel_hi:[0,1,0]
	v_mul_f32_e32 v0, v0, v9
	v_exp_f32_e32 v0, v0
	s_nop 0
	v_add_f32_e32 v0, 1.0, v0
	v_rcp_f32_e32 v11, v0
	v_mul_f32_e32 v0, 0xbfb8aa3b, v13
	v_exp_f32_e32 v0, v0
	v_pk_mul_f32 v[8:9], v[10:11], v[8:9]
	v_cvt_f32_f16_e32 v10, v4
	v_cvt_f32_f16_sdwa v11, v4 dst_sel:DWORD dst_unused:UNUSED_PAD src0_sel:WORD_1
	v_add_f32_e32 v0, 1.0, v0
	v_rcp_f32_e32 v15, v0
	v_pk_add_f32 v[10:11], v[166:167], v[10:11] op_sel_hi:[0,1]
	v_pk_mul_f32 v[8:9], v[8:9], v[10:11]
	v_pk_mul_f32 v[10:11], v[14:15], v[12:13]
	v_cvt_f32_f16_e32 v14, v25
	v_pk_mul_f32 v[8:9], v[10:11], v[8:9]
	v_cvt_f32_f16_e32 v10, v21
	v_cvt_f32_f16_sdwa v11, v21 dst_sel:DWORD dst_unused:UNUSED_PAD src0_sel:WORD_1
	v_cvt_f32_f16_sdwa v15, v25 dst_sel:DWORD dst_unused:UNUSED_PAD src0_sel:WORD_1
	v_mul_f32_e32 v0, 0x3dd2d3e8, v10
	v_fma_mix_f32 v0, -v0, v21, s9 op_sel_hi:[0,1,0]
	v_mul_f32_e32 v0, v0, v10
	v_exp_f32_e32 v0, v0
	s_nop 0
	v_add_f32_e32 v0, 1.0, v0
	v_rcp_f32_e32 v12, v0
	v_mul_f32_e32 v0, 0xbfb8aa3b, v14
	v_exp_f32_e32 v0, v0
	s_nop 0
	v_add_f32_e32 v0, 1.0, v0
	v_rcp_f32_e32 v4, v0
	v_mul_f32_e32 v0, 0x3dd2d3e8, v11
	v_fma_mix_f32 v0, -v0, v21, s9 op_sel:[0,1,0] op_sel_hi:[0,1,0]
	v_mul_f32_e32 v0, v0, v11
	v_exp_f32_e32 v0, v0
	s_nop 0
	v_add_f32_e32 v0, 1.0, v0
	v_rcp_f32_e32 v13, v0
	v_mul_f32_e32 v0, 0xbfb8aa3b, v15
	v_exp_f32_e32 v0, v0
	v_pk_mul_f32 v[10:11], v[12:13], v[10:11]
	v_cvt_f32_f16_e32 v12, v5
	v_cvt_f32_f16_sdwa v13, v5 dst_sel:DWORD dst_unused:UNUSED_PAD src0_sel:WORD_1
	v_add_f32_e32 v0, 1.0, v0
	v_rcp_f32_e32 v5, v0
	v_pk_add_f32 v[12:13], v[166:167], v[12:13] op_sel_hi:[0,1]
	v_pk_mul_f32 v[10:11], v[10:11], v[12:13]
	v_pk_mul_f32 v[4:5], v[4:5], v[14:15]
	s_nop 0
	v_pk_mul_f32 v[10:11], v[4:5], v[10:11]
	v_cvt_pk_f16_f32 v5, v2, v3
	v_lshlrev_b64 v[2:3], 11, v[164:165]
	v_cvt_pk_f16_f32 v4, v6, v7
	v_cvt_pk_f16_f32 v6, v8, v9
	v_cvt_pk_f16_f32 v7, v10, v11
	v_lshl_add_u64 v[2:3], v[148:149], 0, v[2:3]
	global_store_dwordx4 v[2:3], v[4:7], off
	s_waitcnt lgkmcnt(0)
	s_waitcnt lgkmcnt(0)
	s_barrier
